# v13: v8 + packed f32 VALU (v_pk_mul/fma/add_f32) in the GEMM epilogues replaced by scalar f32 pairs (bit-identical)
# speedup vs baseline: 1.0078x; 1.0078x over previous
;     __device__ __forceinline__ void operator()(const f32x4 (&acc)[2][2][4][2], const Unit& u, int wr, int wc, int fr, int fq) const {
;         const int sg = u.pn >> 3, cw = wc * 32 + 8 * fq, hd0 = (u.pn & 7) * 2; const bool rope = sg < 6;
;         const int dsh = 2 * (sg % 3);
;         const int row0 = u.pm * BM + wr * 64 + fr, f0 = 16 * wc + 4 * fq;
;         const int bb = u.pm >> 5;
;         const unsigned sbase = (unsigned)(((sg * 2 + bb) * 16 + hd0) * 8192) * 128u;
; #pragma unroll
;         for (int ai = 0; ai < 2; ++ai)
; #pragma unroll
;             for (int m = 0; m < 4; ++m) { const int row = row0 + ai * HALF + m * 16; const int si = row & 8191;
;                 const int rl = (si & ((1 << dsh) - 1)) * (8192 >> dsh) + (si >> dsh);
;                 f32x4 c = {1.f, 1.f, 1.f, 1.f}, s = {0.f, 0.f, 0.f, 0.f};
;                 if (rope) { c = __builtin_bit_cast(f32x4, __builtin_amdgcn_raw_buffer_load_b128(cs, (row * 64 + f0) * 4, 0, 0)); s = __builtin_bit_cast(f32x4, __builtin_amdgcn_raw_buffer_load_b128(sn, (row * 64 + f0) * 4, 0, 0)); }
; #pragma unroll
;                 for (int bj = 0; bj < 2; ++bj) { f32x4 v0 = acc[ai][bj][m][0] * scl, v1 = acc[ai][bj][m][1] * scl;
;                     rope_pair(v0, v1, c, s);
;                     int w0 = __builtin_amdgcn_cvt_pk_fp8_f32(v0[0], v0[1], 0, false); w0 = __builtin_amdgcn_cvt_pk_fp8_f32(v0[2], v0[3], w0, true);
;                     int w1 = __builtin_amdgcn_cvt_pk_fp8_f32(v1[0], v1[1], 0, false); w1 = __builtin_amdgcn_cvt_pk_fp8_f32(v1[2], v1[3], w1, true);
;                     typedef unsigned u32x2_t __attribute__((ext_vector_type(2)));
;                     __builtin_amdgcn_raw_buffer_store_b64((u32x2_t){(unsigned)w0, (unsigned)w1}, o, rl * 128 + cw, (int)(sbase + (unsigned)bj * (8192u * 128u)), 0); } }
.LBB0_322:
	s_mul_hi_i32 s15, s7, 0x55555556
	s_lshr_b32 s21, s15, 31
	s_add_i32 s15, s15, s21
	s_mul_i32 s15, s15, 3
	v_ashrrev_i32_e32 v129, 1, v129
	s_sub_i32 s15, s7, s15
	v_and_b32_e32 v129, -8, v129
	s_lshl_b32 s23, s15, 1
	v_add_u32_e32 v163, s48, v129
	s_lshl_b32 s35, -1, s23
	v_and_b32_e32 v129, 0x1fcf, v165
	s_lshr_b32 s21, 0x2000, s23
	v_bitop3_b32 v130, v165, s35, v159 bitop3:0x20
	v_lshrrev_b32_e32 v129, s23, v129
	v_mul_f32_e32 v120, s18, v120
	v_mul_f32_e32 v121, s18, v121
	v_mad_u32_u24 v129, v130, s21, v129
	v_mul_f32_e32 v124, s18, v124
	v_mul_f32_e32 v125, s18, v125
	s_waitcnt vmcnt(14)
	v_mul_f32_e32 v130, v120, v172
	v_mul_f32_e32 v131, v121, v173
	v_mul_f32_e32 v120, v120, v168
	v_mul_f32_e32 v121, v121, v169
	v_fma_f32 v130, v124, v168, -v130
	v_fma_f32 v131, v125, v169, -v131
	v_fma_f32 v120, v124, v172, v120
	v_fma_f32 v121, v125, v173, v121
	v_mov_b32_e32 v125, 0
	v_cvt_pk_fp8_f32 v125, v120, v121
	v_mul_f32_e32 v122, s18, v122
	v_mul_f32_e32 v123, s18, v123
	v_mul_f32_e32 v126, s18, v126
	v_mul_f32_e32 v127, s18, v127
	v_mul_f32_e32 v120, v122, v170
	v_mul_f32_e32 v121, v123, v171
	v_mul_f32_e32 v112, s18, v112
	v_mul_f32_e32 v113, s18, v113
	v_fma_f32 v120, v126, v174, v120
	v_fma_f32 v121, v127, v175, v121
	v_mul_f32_e32 v116, s18, v116
	v_mul_f32_e32 v117, s18, v117
	v_cvt_pk_fp8_f32 v125, v120, v121 op_sel:[0,0,1]
	v_mul_f32_e32 v120, v112, v172
	v_mul_f32_e32 v121, v113, v173
	v_mul_f32_e32 v112, v112, v168
	v_mul_f32_e32 v113, v113, v169
	v_mov_b32_e32 v124, 0
	v_fma_f32 v120, v116, v168, -v120
	v_fma_f32 v121, v117, v169, -v121
	v_fma_f32 v112, v116, v172, v112
	v_fma_f32 v113, v117, v173, v113
	v_mov_b32_e32 v116, 0
	v_mov_b32_e32 v117, 0
	v_cvt_pk_fp8_f32 v124, v130, v131
	v_cvt_pk_fp8_f32 v116, v120, v121
	v_cvt_pk_fp8_f32 v117, v112, v113
	v_mul_f32_e32 v114, s18, v114
	v_mul_f32_e32 v115, s18, v115
	s_lshr_b32 s6, s6, 1
	v_mul_f32_e32 v142, v122, v174
	v_mul_f32_e32 v143, v123, v175
	v_mul_f32_e32 v118, s18, v118
	v_mul_f32_e32 v119, s18, v119
	v_mul_f32_e32 v122, v114, v174
	v_mul_f32_e32 v123, v115, v175
	v_mul_f32_e32 v112, v114, v170
	v_mul_f32_e32 v113, v115, v171
	s_lshl_b32 s14, s28, 1
	s_lshl_b32 s7, s7, 5
	s_and_b32 s6, s6, 0xff0
	v_fma_f32 v142, v126, v170, -v142
	v_fma_f32 v143, v127, v171, -v143
	v_fma_f32 v122, v118, v170, -v122
	v_fma_f32 v123, v119, v171, -v123
	v_fma_f32 v112, v118, v174, v112
	v_fma_f32 v113, v119, v175, v113
	s_and_b32 s14, s14, 14
	s_add_i32 s6, s6, s7
	v_cvt_pk_fp8_f32 v124, v142, v143 op_sel:[0,0,1]
	v_cvt_pk_fp8_f32 v116, v122, v123 op_sel:[0,0,1]
	v_cvt_pk_fp8_f32 v117, v112, v113 op_sel:[0,0,1]
	s_or_b32 s6, s6, s14
	s_lshl_b32 s28, s6, 20
	v_lshl_add_u32 v129, v129, 7, v163
	s_or_b32 s34, s28, 0x100000
	v_cndmask_b32_e64 v113, 0, 1, s[30:31]
	buffer_store_dwordx2 v[124:125], v129, s[84:87], s28 offen
	buffer_store_dwordx2 v[116:117], v129, s[84:87], s34 offen
	v_or_b32_e32 v112, 16, v165
	v_cmp_ne_u32_e64 s[6:7], 1, v113
	s_andn2_b64 vcc, exec, s[30:31]
	v_mov_b32_e32 v133, 0
	v_mov_b32_e32 v134, 0
	v_mov_b32_e32 v135, 0
	v_mov_b32_e32 v129, 1.0
	v_mov_b32_e32 v130, 1.0
	v_mov_b32_e32 v131, 1.0
.LBB0_324:
	s_not_b32 s30, s35
	v_and_b32_e32 v113, 0x1fdf, v112
	v_mov_b32_e32 v118, 0x1fdf
	v_mul_f32_e32 v104, s18, v104
	v_mul_f32_e32 v105, s18, v105
	v_bitop3_b32 v116, v112, s30, v118 bitop3:0x80
	v_lshrrev_b32_e32 v117, s23, v113
	v_mul_f32_e32 v108, s18, v108
	v_mul_f32_e32 v109, s18, v109
	s_waitcnt vmcnt(14)
	v_mul_f32_e32 v112, v104, v180
	v_mul_f32_e32 v113, v105, v181
	v_mul_f32_e32 v104, v104, v176
	v_mul_f32_e32 v105, v105, v177
	v_fma_f32 v112, v108, v176, -v112
	v_fma_f32 v113, v109, v177, -v113
	v_fma_f32 v104, v108, v180, v104
	v_fma_f32 v105, v109, v181, v105
	v_mov_b32_e32 v109, 0
	v_cvt_pk_fp8_f32 v109, v104, v105
	v_mul_f32_e32 v106, s18, v106
	v_mul_f32_e32 v107, s18, v107
	v_mul_f32_e32 v110, s18, v110
	v_mul_f32_e32 v111, s18, v111
	v_mul_f32_e32 v104, v106, v178
	v_mul_f32_e32 v105, v107, v179
	v_mul_f32_e32 v96, s18, v96
	v_mul_f32_e32 v97, s18, v97
	v_fma_f32 v104, v110, v182, v104
	v_fma_f32 v105, v111, v183, v105
	v_mov_b32_e32 v108, 0
	v_cvt_pk_fp8_f32 v109, v104, v105 op_sel:[0,0,1]
	v_mul_f32_e32 v100, s18, v100
	v_mul_f32_e32 v101, s18, v101
	v_mul_f32_e32 v104, v96, v180
	v_mul_f32_e32 v105, v97, v181
	v_mul_f32_e32 v96, v96, v176
	v_mul_f32_e32 v97, v97, v177
	v_cvt_pk_fp8_f32 v108, v112, v113
	v_fma_f32 v104, v100, v176, -v104
	v_fma_f32 v105, v101, v177, -v105
	v_fma_f32 v96, v100, v180, v96
	v_fma_f32 v97, v101, v181, v97
	v_mov_b32_e32 v100, 0
	v_mov_b32_e32 v101, 0
	v_cvt_pk_fp8_f32 v100, v104, v105
	v_cvt_pk_fp8_f32 v101, v96, v97
	v_mul_f32_e32 v114, v106, v182
	v_mul_f32_e32 v115, v107, v183
	v_mul_f32_e32 v98, s18, v98
	v_mul_f32_e32 v99, s18, v99
	v_fma_f32 v114, v110, v178, -v114
	v_fma_f32 v115, v111, v179, -v115
	v_mul_f32_e32 v102, s18, v102
	v_mul_f32_e32 v103, s18, v103
	v_mul_f32_e32 v106, v98, v182
	v_mul_f32_e32 v107, v99, v183
	v_mul_f32_e32 v96, v98, v178
	v_mul_f32_e32 v97, v99, v179
	v_cvt_pk_fp8_f32 v108, v114, v115 op_sel:[0,0,1]
	v_fma_f32 v106, v102, v178, -v106
	v_fma_f32 v107, v103, v179, -v107
	v_fma_f32 v96, v102, v182, v96
	v_fma_f32 v97, v103, v183, v97
	v_cvt_pk_fp8_f32 v100, v106, v107 op_sel:[0,0,1]
	v_cvt_pk_fp8_f32 v101, v96, v97 op_sel:[0,0,1]
	v_mad_u32_u24 v96, v116, s21, v117
	v_lshl_add_u32 v96, v96, 7, v163
	buffer_store_dwordx2 v[108:109], v96, s[84:87], s28 offen
	buffer_store_dwordx2 v[100:101], v96, s[84:87], s34 offen
	v_or_b32_e32 v97, 32, v165
	v_mov_b32_e32 v96, 1.0
	v_mov_b32_e32 v100, 0
	s_and_b64 vcc, exec, s[6:7]
	v_mov_b32_e32 v102, 0
	v_mov_b32_e32 v103, 0
	v_mov_b32_e32 v104, 0
	v_mov_b32_e32 v105, 0
	v_mov_b32_e32 v106, 1.0
	v_mov_b32_e32 v107, 1.0
	v_mov_b32_e32 v108, 1.0
	v_mov_b32_e32 v109, 1.0
;     __device__ __forceinline__ void operator()(const f32x4 (&acc)[2][2][4][2], const Unit& u, int wr, int wc, int fr, int fq) const {
;     ...
;             for (int m = 0; m < 4; ++m) { const int row = row0 + ai * HALF + m * 16; const int si = row & 8191;
;                 const int rl = (si & ((1 << dsh) - 1)) * (8192 >> dsh) + (si >> dsh);
;                 f32x4 c = {1.f, 1.f, 1.f, 1.f}, s = {0.f, 0.f, 0.f, 0.f};
;                 if (rope) { c = __builtin_bit_cast(f32x4, __builtin_amdgcn_raw_buffer_load_b128(cs, (row * 64 + f0) * 4, 0, 0)); s = __builtin_bit_cast(f32x4, __builtin_amdgcn_raw_buffer_load_b128(sn, (row * 64 + f0) * 4, 0, 0)); }
; #pragma unroll
;                 for (int bj = 0; bj < 2; ++bj) { f32x4 v0 = acc[ai][bj][m][0] * scl, v1 = acc[ai][bj][m][1] * scl;
;                     rope_pair(v0, v1, c, s);
;                     int w0 = __builtin_amdgcn_cvt_pk_fp8_f32(v0[0], v0[1], 0, false); w0 = __builtin_amdgcn_cvt_pk_fp8_f32(v0[2], v0[3], w0, true);
;                     int w1 = __builtin_amdgcn_cvt_pk_fp8_f32(v1[0], v1[1], 0, false); w1 = __builtin_amdgcn_cvt_pk_fp8_f32(v1[2], v1[3], w1, true);
;                     typedef unsigned u32x2_t __attribute__((ext_vector_type(2)));
;                     __builtin_amdgcn_raw_buffer_store_b64((u32x2_t){(unsigned)w0, (unsigned)w1}, o, rl * 128 + cw, (int)(sbase + (unsigned)bj * (8192u * 128u)), 0); } }
.LBB0_326:
	v_and_b32_e32 v98, 0x1fef, v97
	v_mul_f32_e32 v88, s18, v88
	v_mul_f32_e32 v89, s18, v89
	v_lshrrev_b32_e32 v101, s23, v98
	v_mul_f32_e32 v92, s18, v92
	v_mul_f32_e32 v93, s18, v93
	s_waitcnt vmcnt(14)
	v_mul_f32_e32 v98, v88, v188
	v_mul_f32_e32 v99, v89, v189
	v_mul_f32_e32 v88, v88, v184
	v_mul_f32_e32 v89, v89, v185
	v_fma_f32 v98, v92, v184, -v98
	v_fma_f32 v99, v93, v185, -v99
	v_fma_f32 v88, v92, v188, v88
	v_fma_f32 v89, v93, v189, v89
	v_mov_b32_e32 v93, 0
	v_cvt_pk_fp8_f32 v93, v88, v89
	v_mul_f32_e32 v90, s18, v90
	v_mul_f32_e32 v91, s18, v91
	v_mul_f32_e32 v94, s18, v94
	v_mul_f32_e32 v95, s18, v95
	v_mul_f32_e32 v88, v90, v186
	v_mul_f32_e32 v89, v91, v187
	v_mul_f32_e32 v80, s18, v80
	v_mul_f32_e32 v81, s18, v81
	v_fma_f32 v88, v94, v190, v88
	v_fma_f32 v89, v95, v191, v89
	v_mov_b32_e32 v92, 0
	v_cvt_pk_fp8_f32 v93, v88, v89 op_sel:[0,0,1]
	v_mul_f32_e32 v84, s18, v84
	v_mul_f32_e32 v85, s18, v85
	v_mul_f32_e32 v88, v80, v188
	v_mul_f32_e32 v89, v81, v189
	v_mul_f32_e32 v80, v80, v184
	v_mul_f32_e32 v81, v81, v185
	v_cvt_pk_fp8_f32 v92, v98, v99
	v_fma_f32 v88, v84, v184, -v88
	v_fma_f32 v89, v85, v185, -v89
	v_fma_f32 v80, v84, v188, v80
	v_fma_f32 v81, v85, v189, v81
	v_mov_b32_e32 v84, 0
	v_mov_b32_e32 v85, 0
	v_cvt_pk_fp8_f32 v84, v88, v89
	v_cvt_pk_fp8_f32 v85, v80, v81
	v_mul_f32_e32 v110, v90, v190
	v_mul_f32_e32 v111, v91, v191
	v_mul_f32_e32 v82, s18, v82
	v_mul_f32_e32 v83, s18, v83
	v_fma_f32 v110, v94, v186, -v110
	v_fma_f32 v111, v95, v187, -v111
	v_mul_f32_e32 v86, s18, v86
	v_mul_f32_e32 v87, s18, v87
	v_mul_f32_e32 v90, v82, v190
	v_mul_f32_e32 v91, v83, v191
	v_mul_f32_e32 v80, v82, v186
	v_mul_f32_e32 v81, v83, v187
	v_mov_b32_e32 v112, 0x1fef
	v_cvt_pk_fp8_f32 v92, v110, v111 op_sel:[0,0,1]
	v_fma_f32 v90, v86, v186, -v90
	v_fma_f32 v91, v87, v187, -v91
	v_fma_f32 v80, v86, v190, v80
	v_fma_f32 v81, v87, v191, v81
	v_bitop3_b32 v97, v97, s30, v112 bitop3:0x80
	v_cvt_pk_fp8_f32 v84, v90, v91 op_sel:[0,0,1]
	v_cvt_pk_fp8_f32 v85, v80, v81 op_sel:[0,0,1]
	v_mad_u32_u24 v80, v97, s21, v101
	v_lshl_add_u32 v80, v80, 7, v163
	buffer_store_dwordx2 v[92:93], v80, s[84:87], s28 offen
	buffer_store_dwordx2 v[84:85], v80, s[84:87], s34 offen
	v_or_b32_e32 v80, 48, v165
	s_and_b64 vcc, exec, s[6:7]
	v_mov_b32_e32 v101, 0
	v_mov_b32_e32 v102, 0
	v_mov_b32_e32 v103, 0
	v_mov_b32_e32 v97, 1.0
	v_mov_b32_e32 v98, 1.0
	v_mov_b32_e32 v99, 1.0
.LBB0_328:
	v_and_b32_e32 v81, 0x1fff, v80
	v_mov_b32_e32 v86, 0x1fff
	v_mul_f32_e32 v72, s18, v72
	v_mul_f32_e32 v73, s18, v73
	v_bitop3_b32 v84, v80, s30, v86 bitop3:0x80
	v_lshrrev_b32_e32 v85, s23, v81
	v_mul_f32_e32 v76, s18, v76
	v_mul_f32_e32 v77, s18, v77
	s_waitcnt vmcnt(14)
	v_mul_f32_e32 v80, v72, v196
	v_mul_f32_e32 v81, v73, v197
	v_mul_f32_e32 v72, v72, v192
	v_mul_f32_e32 v73, v73, v193
	v_fma_f32 v80, v76, v192, -v80
	v_fma_f32 v81, v77, v193, -v81
	v_fma_f32 v72, v76, v196, v72
	v_fma_f32 v73, v77, v197, v73
	v_mov_b32_e32 v77, 0
	v_cvt_pk_fp8_f32 v77, v72, v73
	v_mul_f32_e32 v74, s18, v74
	v_mul_f32_e32 v75, s18, v75
	v_mul_f32_e32 v78, s18, v78
	v_mul_f32_e32 v79, s18, v79
	v_mul_f32_e32 v72, v74, v194
	v_mul_f32_e32 v73, v75, v195
	v_mul_f32_e32 v64, s18, v64
	v_mul_f32_e32 v65, s18, v65
	v_fma_f32 v72, v78, v198, v72
	v_fma_f32 v73, v79, v199, v73
	v_mov_b32_e32 v76, 0
	v_cvt_pk_fp8_f32 v77, v72, v73 op_sel:[0,0,1]
	v_mul_f32_e32 v68, s18, v68
	v_mul_f32_e32 v69, s18, v69
	v_mul_f32_e32 v72, v64, v196
	v_mul_f32_e32 v73, v65, v197
	v_mul_f32_e32 v64, v64, v192
	v_mul_f32_e32 v65, v65, v193
	v_cvt_pk_fp8_f32 v76, v80, v81
	v_fma_f32 v72, v68, v192, -v72
	v_fma_f32 v73, v69, v193, -v73
	v_fma_f32 v64, v68, v196, v64
	v_fma_f32 v65, v69, v197, v65
	v_mov_b32_e32 v68, 0
	v_mov_b32_e32 v69, 0
	v_cvt_pk_fp8_f32 v68, v72, v73
	v_cvt_pk_fp8_f32 v69, v64, v65
	v_mul_f32_e32 v82, v74, v198
	v_mul_f32_e32 v83, v75, v199
	v_mul_f32_e32 v66, s18, v66
	v_mul_f32_e32 v67, s18, v67
	v_fma_f32 v82, v78, v194, -v82
	v_fma_f32 v83, v79, v195, -v83
	v_mul_f32_e32 v70, s18, v70
	v_mul_f32_e32 v71, s18, v71
	v_mul_f32_e32 v74, v66, v198
	v_mul_f32_e32 v75, v67, v199
	v_mul_f32_e32 v64, v66, v194
	v_mul_f32_e32 v65, v67, v195
	v_cvt_pk_fp8_f32 v76, v82, v83 op_sel:[0,0,1]
	v_fma_f32 v74, v70, v194, -v74
	v_fma_f32 v75, v71, v195, -v75
	v_fma_f32 v64, v70, v198, v64
	v_fma_f32 v65, v71, v199, v65
	v_cvt_pk_fp8_f32 v68, v74, v75 op_sel:[0,0,1]
	v_cvt_pk_fp8_f32 v69, v64, v65 op_sel:[0,0,1]
	v_mad_u32_u24 v64, v84, s21, v85
	v_lshl_add_u32 v64, v64, 7, v163
	buffer_store_dwordx2 v[76:77], v64, s[84:87], s28 offen
	buffer_store_dwordx2 v[68:69], v64, s[84:87], s34 offen
	v_add_u32_e32 v65, 0x80, v165
	v_mov_b32_e32 v64, 1.0
	v_mov_b32_e32 v68, 0
	s_and_b64 vcc, exec, s[6:7]
	v_mov_b32_e32 v70, 0
	v_mov_b32_e32 v71, 0
	v_mov_b32_e32 v72, 0
	v_mov_b32_e32 v73, 0
	v_mov_b32_e32 v74, 1.0
	v_mov_b32_e32 v75, 1.0
	v_mov_b32_e32 v76, 1.0
	v_mov_b32_e32 v77, 1.0
;     __device__ __forceinline__ void operator()(const f32x4 (&acc)[2][2][4][2], const Unit& u, int wr, int wc, int fr, int fq) const {
;     ...
;             for (int m = 0; m < 4; ++m) { const int row = row0 + ai * HALF + m * 16; const int si = row & 8191;
;                 const int rl = (si & ((1 << dsh) - 1)) * (8192 >> dsh) + (si >> dsh);
;                 f32x4 c = {1.f, 1.f, 1.f, 1.f}, s = {0.f, 0.f, 0.f, 0.f};
;                 if (rope) { c = __builtin_bit_cast(f32x4, __builtin_amdgcn_raw_buffer_load_b128(cs, (row * 64 + f0) * 4, 0, 0)); s = __builtin_bit_cast(f32x4, __builtin_amdgcn_raw_buffer_load_b128(sn, (row * 64 + f0) * 4, 0, 0)); }
; #pragma unroll
;                 for (int bj = 0; bj < 2; ++bj) { f32x4 v0 = acc[ai][bj][m][0] * scl, v1 = acc[ai][bj][m][1] * scl;
;                     rope_pair(v0, v1, c, s);
;                     int w0 = __builtin_amdgcn_cvt_pk_fp8_f32(v0[0], v0[1], 0, false); w0 = __builtin_amdgcn_cvt_pk_fp8_f32(v0[2], v0[3], w0, true);
;                     int w1 = __builtin_amdgcn_cvt_pk_fp8_f32(v1[0], v1[1], 0, false); w1 = __builtin_amdgcn_cvt_pk_fp8_f32(v1[2], v1[3], w1, true);
;                     typedef unsigned u32x2_t __attribute__((ext_vector_type(2)));
;                     __builtin_amdgcn_raw_buffer_store_b64((u32x2_t){(unsigned)w0, (unsigned)w1}, o, rl * 128 + cw, (int)(sbase + (unsigned)bj * (8192u * 128u)), 0); } }
.LBB0_330:
	v_and_b32_e32 v66, 0x1fcf, v65
	v_mul_f32_e32 v56, s18, v56
	v_mul_f32_e32 v57, s18, v57
	v_lshrrev_b32_e32 v69, s23, v66
	v_mul_f32_e32 v60, s18, v60
	v_mul_f32_e32 v61, s18, v61
	s_waitcnt vmcnt(14)
	v_mul_f32_e32 v66, v56, v204
	v_mul_f32_e32 v67, v57, v205
	v_mul_f32_e32 v56, v56, v200
	v_mul_f32_e32 v57, v57, v201
	v_fma_f32 v66, v60, v200, -v66
	v_fma_f32 v67, v61, v201, -v67
	v_fma_f32 v56, v60, v204, v56
	v_fma_f32 v57, v61, v205, v57
	v_mov_b32_e32 v61, 0
	v_cvt_pk_fp8_f32 v61, v56, v57
	v_mul_f32_e32 v58, s18, v58
	v_mul_f32_e32 v59, s18, v59
	v_mul_f32_e32 v62, s18, v62
	v_mul_f32_e32 v63, s18, v63
	v_mul_f32_e32 v56, v58, v202
	v_mul_f32_e32 v57, v59, v203
	v_mul_f32_e32 v48, s18, v48
	v_mul_f32_e32 v49, s18, v49
	v_fma_f32 v56, v62, v206, v56
	v_fma_f32 v57, v63, v207, v57
	v_mov_b32_e32 v60, 0
	v_cvt_pk_fp8_f32 v61, v56, v57 op_sel:[0,0,1]
	v_mul_f32_e32 v52, s18, v52
	v_mul_f32_e32 v53, s18, v53
	v_mul_f32_e32 v56, v48, v204
	v_mul_f32_e32 v57, v49, v205
	v_mul_f32_e32 v48, v48, v200
	v_mul_f32_e32 v49, v49, v201
	v_cvt_pk_fp8_f32 v60, v66, v67
	v_fma_f32 v56, v52, v200, -v56
	v_fma_f32 v57, v53, v201, -v57
	v_fma_f32 v48, v52, v204, v48
	v_fma_f32 v49, v53, v205, v49
	v_mov_b32_e32 v52, 0
	v_mov_b32_e32 v53, 0
	v_cvt_pk_fp8_f32 v52, v56, v57
	v_cvt_pk_fp8_f32 v53, v48, v49
	v_mul_f32_e32 v78, v58, v206
	v_mul_f32_e32 v79, v59, v207
	v_mul_f32_e32 v50, s18, v50
	v_mul_f32_e32 v51, s18, v51
	v_fma_f32 v78, v62, v202, -v78
	v_fma_f32 v79, v63, v203, -v79
	v_mul_f32_e32 v54, s18, v54
	v_mul_f32_e32 v55, s18, v55
	v_mul_f32_e32 v58, v50, v206
	v_mul_f32_e32 v59, v51, v207
	v_mul_f32_e32 v48, v50, v202
	v_mul_f32_e32 v49, v51, v203
	v_cvt_pk_fp8_f32 v60, v78, v79 op_sel:[0,0,1]
	v_fma_f32 v58, v54, v202, -v58
	v_fma_f32 v59, v55, v203, -v59
	v_fma_f32 v48, v54, v206, v48
	v_fma_f32 v49, v55, v207, v49
	v_bitop3_b32 v65, v65, s30, v159 bitop3:0x80
	v_cvt_pk_fp8_f32 v52, v58, v59 op_sel:[0,0,1]
	v_cvt_pk_fp8_f32 v53, v48, v49 op_sel:[0,0,1]
	v_mad_u32_u24 v48, v65, s21, v69
	v_lshl_add_u32 v48, v48, 7, v163
	buffer_store_dwordx2 v[60:61], v48, s[84:87], s28 offen
	buffer_store_dwordx2 v[52:53], v48, s[84:87], s34 offen
	v_add_u32_e32 v48, 0x90, v165
	s_and_b64 vcc, exec, s[6:7]
	v_mov_b32_e32 v69, 0
	v_mov_b32_e32 v70, 0
	v_mov_b32_e32 v71, 0
	v_mov_b32_e32 v65, 1.0
	v_mov_b32_e32 v66, 1.0
	v_mov_b32_e32 v67, 1.0
.LBB0_332:
	v_and_b32_e32 v49, 0x1fdf, v48
	v_mul_f32_e32 v40, s18, v40
	v_mul_f32_e32 v41, s18, v41
	v_bitop3_b32 v52, v48, s30, v118 bitop3:0x80
	v_lshrrev_b32_e32 v53, s23, v49
	v_mul_f32_e32 v44, s18, v44
	v_mul_f32_e32 v45, s18, v45
	s_waitcnt vmcnt(14)
	v_mul_f32_e32 v48, v40, v212
	v_mul_f32_e32 v49, v41, v213
	v_mul_f32_e32 v40, v40, v208
	v_mul_f32_e32 v41, v41, v209
	v_fma_f32 v48, v44, v208, -v48
	v_fma_f32 v49, v45, v209, -v49
	v_fma_f32 v40, v44, v212, v40
	v_fma_f32 v41, v45, v213, v41
	v_mov_b32_e32 v45, 0
	v_cvt_pk_fp8_f32 v45, v40, v41
	v_mul_f32_e32 v42, s18, v42
	v_mul_f32_e32 v43, s18, v43
	v_mul_f32_e32 v46, s18, v46
	v_mul_f32_e32 v47, s18, v47
	v_mul_f32_e32 v40, v42, v210
	v_mul_f32_e32 v41, v43, v211
	v_mul_f32_e32 v32, s18, v32
	v_mul_f32_e32 v33, s18, v33
	v_fma_f32 v40, v46, v214, v40
	v_fma_f32 v41, v47, v215, v41
	v_mov_b32_e32 v44, 0
	v_cvt_pk_fp8_f32 v45, v40, v41 op_sel:[0,0,1]
	v_mul_f32_e32 v36, s18, v36
	v_mul_f32_e32 v37, s18, v37
	v_mul_f32_e32 v40, v32, v212
	v_mul_f32_e32 v41, v33, v213
	v_mul_f32_e32 v32, v32, v208
	v_mul_f32_e32 v33, v33, v209
	v_cvt_pk_fp8_f32 v44, v48, v49
	v_fma_f32 v40, v36, v208, -v40
	v_fma_f32 v41, v37, v209, -v41
	v_fma_f32 v32, v36, v212, v32
	v_fma_f32 v33, v37, v213, v33
	v_mov_b32_e32 v36, 0
	v_mov_b32_e32 v37, 0
	v_cvt_pk_fp8_f32 v36, v40, v41
	v_cvt_pk_fp8_f32 v37, v32, v33
	v_mul_f32_e32 v50, v42, v214
	v_mul_f32_e32 v51, v43, v215
	v_mul_f32_e32 v34, s18, v34
	v_mul_f32_e32 v35, s18, v35
	v_fma_f32 v50, v46, v210, -v50
	v_fma_f32 v51, v47, v211, -v51
	v_mul_f32_e32 v38, s18, v38
	v_mul_f32_e32 v39, s18, v39
	v_mul_f32_e32 v42, v34, v214
	v_mul_f32_e32 v43, v35, v215
	v_mul_f32_e32 v32, v34, v210
	v_mul_f32_e32 v33, v35, v211
	v_cvt_pk_fp8_f32 v44, v50, v51 op_sel:[0,0,1]
	v_fma_f32 v42, v38, v210, -v42
	v_fma_f32 v43, v39, v211, -v43
	v_fma_f32 v32, v38, v214, v32
	v_fma_f32 v33, v39, v215, v33
	v_cvt_pk_fp8_f32 v36, v42, v43 op_sel:[0,0,1]
	v_cvt_pk_fp8_f32 v37, v32, v33 op_sel:[0,0,1]
	v_mad_u32_u24 v32, v52, s21, v53
	v_lshl_add_u32 v32, v32, 7, v163
	buffer_store_dwordx2 v[44:45], v32, s[84:87], s28 offen
	buffer_store_dwordx2 v[36:37], v32, s[84:87], s34 offen
	v_add_u32_e32 v33, 0xa0, v165
	v_mov_b32_e32 v32, 1.0
	v_mov_b32_e32 v36, 0
	s_and_b64 vcc, exec, s[6:7]
	v_mov_b32_e32 v38, 0
	v_mov_b32_e32 v39, 0
	v_mov_b32_e32 v40, 0
	v_mov_b32_e32 v41, 0
	v_mov_b32_e32 v42, 1.0
	v_mov_b32_e32 v43, 1.0
	v_mov_b32_e32 v44, 1.0
	v_mov_b32_e32 v45, 1.0
; #define PG8_BAR __builtin_amdgcn_s_barrier()
;     __device__ __forceinline__ void operator()(const f32x4 (&acc)[2][2][4][2], const Unit& u, int wr, int wc, int fr, int fq) const {
;     ...
;             for (int m = 0; m < 4; ++m) { const int row = row0 + ai * HALF + m * 16; const int si = row & 8191;
;                 const int rl = (si & ((1 << dsh) - 1)) * (8192 >> dsh) + (si >> dsh);
;                 f32x4 c = {1.f, 1.f, 1.f, 1.f}, s = {0.f, 0.f, 0.f, 0.f};
;                 if (rope) { c = __builtin_bit_cast(f32x4, __builtin_amdgcn_raw_buffer_load_b128(cs, (row * 64 + f0) * 4, 0, 0)); s = __builtin_bit_cast(f32x4, __builtin_amdgcn_raw_buffer_load_b128(sn, (row * 64 + f0) * 4, 0, 0)); }
; #pragma unroll
;                 for (int bj = 0; bj < 2; ++bj) { f32x4 v0 = acc[ai][bj][m][0] * scl, v1 = acc[ai][bj][m][1] * scl;
;                     rope_pair(v0, v1, c, s);
;                     int w0 = __builtin_amdgcn_cvt_pk_fp8_f32(v0[0], v0[1], 0, false); w0 = __builtin_amdgcn_cvt_pk_fp8_f32(v0[2], v0[3], w0, true);
;                     int w1 = __builtin_amdgcn_cvt_pk_fp8_f32(v1[0], v1[1], 0, false); w1 = __builtin_amdgcn_cvt_pk_fp8_f32(v1[2], v1[3], w1, true);
;                     typedef unsigned u32x2_t __attribute__((ext_vector_type(2)));
;                     __builtin_amdgcn_raw_buffer_store_b64((u32x2_t){(unsigned)w0, (unsigned)w1}, o, rl * 128 + cw, (int)(sbase + (unsigned)bj * (8192u * 128u)), 0); } }
;     ...
;         if constexpr (!Epi::AFTER_DRAIN) { { unsigned z_ = 0u; asm volatile("" : "+v"(z_)); const int l2_ = (int)__builtin_amdgcn_mbcnt_hi(~0u, __builtin_amdgcn_mbcnt_lo(~0u, z_)); E(acc, cur, wr, wc, l2_ & 15, l2_ >> 4); } S.done(cur);     }
;         if (!has_next) break;
; #pragma unroll
;         for (int a = 0; a < 2; ++a)
; #pragma unroll
;             for (int b = 0; b < 2; ++b)
; #pragma unroll
;                 for (int m = 0; m < 4; ++m)
; #pragma unroll
;                     for (int n = 0; n < 2; ++n) acc[a][b][m][n] = (f32x4){0.f, 0.f, 0.f, 0.f};
;         cur = nxt; cA = nA; cB = nB; ++ui;
;         if constexpr (ALIGN_EPI) { if (wr == 1) PG8_BAR; }
;     }
.LBB0_334:
	v_and_b32_e32 v34, 0x1fef, v33
	v_mul_f32_e32 v24, s18, v24
	v_mul_f32_e32 v25, s18, v25
	v_lshrrev_b32_e32 v37, s23, v34
	v_mul_f32_e32 v28, s18, v28
	v_mul_f32_e32 v29, s18, v29
	s_waitcnt vmcnt(14)
	v_mul_f32_e32 v34, v24, v220
	v_mul_f32_e32 v35, v25, v221
	v_mul_f32_e32 v24, v24, v216
	v_mul_f32_e32 v25, v25, v217
	v_fma_f32 v34, v28, v216, -v34
	v_fma_f32 v35, v29, v217, -v35
	v_fma_f32 v24, v28, v220, v24
	v_fma_f32 v25, v29, v221, v25
	v_mov_b32_e32 v29, 0
	v_cvt_pk_fp8_f32 v29, v24, v25
	v_mul_f32_e32 v26, s18, v26
	v_mul_f32_e32 v27, s18, v27
	v_mul_f32_e32 v30, s18, v30
	v_mul_f32_e32 v31, s18, v31
	v_mul_f32_e32 v24, v26, v218
	v_mul_f32_e32 v25, v27, v219
	v_mul_f32_e32 v16, s18, v16
	v_mul_f32_e32 v17, s18, v17
	v_fma_f32 v24, v30, v222, v24
	v_fma_f32 v25, v31, v223, v25
	v_mov_b32_e32 v28, 0
	v_cvt_pk_fp8_f32 v29, v24, v25 op_sel:[0,0,1]
	v_mul_f32_e32 v20, s18, v20
	v_mul_f32_e32 v21, s18, v21
	v_mul_f32_e32 v24, v16, v220
	v_mul_f32_e32 v25, v17, v221
	v_mul_f32_e32 v16, v16, v216
	v_mul_f32_e32 v17, v17, v217
	v_cvt_pk_fp8_f32 v28, v34, v35
	v_fma_f32 v24, v20, v216, -v24
	v_fma_f32 v25, v21, v217, -v25
	v_fma_f32 v16, v20, v220, v16
	v_fma_f32 v17, v21, v221, v17
	v_mov_b32_e32 v20, 0
	v_mov_b32_e32 v21, 0
	v_cvt_pk_fp8_f32 v20, v24, v25
	v_cvt_pk_fp8_f32 v21, v16, v17
	v_mul_f32_e32 v46, v26, v222
	v_mul_f32_e32 v47, v27, v223
	v_mul_f32_e32 v18, s18, v18
	v_mul_f32_e32 v19, s18, v19
	v_fma_f32 v46, v30, v218, -v46
	v_fma_f32 v47, v31, v219, -v47
	v_mul_f32_e32 v22, s18, v22
	v_mul_f32_e32 v23, s18, v23
	v_mul_f32_e32 v26, v18, v222
	v_mul_f32_e32 v27, v19, v223
	v_mul_f32_e32 v16, v18, v218
	v_mul_f32_e32 v17, v19, v219
	v_cvt_pk_fp8_f32 v28, v46, v47 op_sel:[0,0,1]
	v_fma_f32 v26, v22, v218, -v26
	v_fma_f32 v27, v23, v219, -v27
	v_fma_f32 v16, v22, v222, v16
	v_fma_f32 v17, v23, v223, v17
	v_bitop3_b32 v33, v33, s30, v112 bitop3:0x80
	v_cvt_pk_fp8_f32 v20, v26, v27 op_sel:[0,0,1]
	v_cvt_pk_fp8_f32 v21, v16, v17 op_sel:[0,0,1]
	v_mad_u32_u24 v16, v33, s21, v37
	v_lshl_add_u32 v16, v16, 7, v163
	buffer_store_dwordx2 v[28:29], v16, s[84:87], s28 offen
	buffer_store_dwordx2 v[20:21], v16, s[84:87], s34 offen
	v_add_u32_e32 v16, 0xb0, v165
	s_and_b64 vcc, exec, s[6:7]
	v_mov_b32_e32 v37, 0
	v_mov_b32_e32 v38, 0
	v_mov_b32_e32 v39, 0
	v_mov_b32_e32 v33, 1.0
	v_mov_b32_e32 v34, 1.0
	v_mov_b32_e32 v35, 1.0
.LBB0_336:
	v_and_b32_e32 v17, 0x1fff, v16
	v_mul_f32_e32 v8, s18, v8
	v_mul_f32_e32 v9, s18, v9
	v_bitop3_b32 v20, v16, s30, v86 bitop3:0x80
	v_lshrrev_b32_e32 v21, s23, v17
	v_mul_f32_e32 v12, s18, v12
	v_mul_f32_e32 v13, s18, v13
	s_waitcnt vmcnt(14)
	v_mul_f32_e32 v16, v8, v228
	v_mul_f32_e32 v17, v9, v229
	v_mul_f32_e32 v8, v8, v224
	v_mul_f32_e32 v9, v9, v225
	v_fma_f32 v16, v12, v224, -v16
	v_fma_f32 v17, v13, v225, -v17
	v_fma_f32 v8, v12, v228, v8
	v_fma_f32 v9, v13, v229, v9
	v_mov_b32_e32 v13, 0
	v_cvt_pk_fp8_f32 v13, v8, v9
	v_mul_f32_e32 v10, s18, v10
	v_mul_f32_e32 v11, s18, v11
	v_mul_f32_e32 v14, s18, v14
	v_mul_f32_e32 v15, s18, v15
	v_mul_f32_e32 v8, v10, v226
	v_mul_f32_e32 v9, v11, v227
	v_mul_f32_e32 v0, s18, v0
	v_mul_f32_e32 v1, s18, v1
	v_fma_f32 v8, v14, v230, v8
	v_fma_f32 v9, v15, v231, v9
	v_mov_b32_e32 v12, 0
	v_cvt_pk_fp8_f32 v13, v8, v9 op_sel:[0,0,1]
	v_mul_f32_e32 v4, s18, v4
	v_mul_f32_e32 v5, s18, v5
	v_mul_f32_e32 v8, v0, v228
	v_mul_f32_e32 v9, v1, v229
	v_mul_f32_e32 v0, v0, v224
	v_mul_f32_e32 v1, v1, v225
	v_cvt_pk_fp8_f32 v12, v16, v17
	v_fma_f32 v8, v4, v224, -v8
	v_fma_f32 v9, v5, v225, -v9
	v_fma_f32 v0, v4, v228, v0
	v_fma_f32 v1, v5, v229, v1
	v_mov_b32_e32 v4, 0
	v_mov_b32_e32 v5, 0
	v_cvt_pk_fp8_f32 v4, v8, v9
	v_cvt_pk_fp8_f32 v5, v0, v1
	v_mul_f32_e32 v18, v10, v230
	v_mul_f32_e32 v19, v11, v231
	v_mul_f32_e32 v2, s18, v2
	v_mul_f32_e32 v3, s18, v3
	v_fma_f32 v18, v14, v226, -v18
	v_fma_f32 v19, v15, v227, -v19
	v_mul_f32_e32 v6, s18, v6
	v_mul_f32_e32 v7, s18, v7
	v_mul_f32_e32 v10, v2, v230
	v_mul_f32_e32 v11, v3, v231
	v_mul_f32_e32 v0, v2, v226
	v_mul_f32_e32 v1, v3, v227
	v_cvt_pk_fp8_f32 v12, v18, v19 op_sel:[0,0,1]
	v_fma_f32 v10, v6, v226, -v10
	v_fma_f32 v11, v7, v227, -v11
	v_fma_f32 v0, v6, v230, v0
	v_fma_f32 v1, v7, v231, v1
	v_cvt_pk_fp8_f32 v4, v10, v11 op_sel:[0,0,1]
	v_cvt_pk_fp8_f32 v5, v0, v1 op_sel:[0,0,1]
	v_mad_u32_u24 v0, v20, s21, v21
	v_lshl_add_u32 v0, v0, 7, v163
	s_andn2_b64 vcc, exec, s[4:5]
	s_mov_b64 s[4:5], -1
	buffer_store_dwordx2 v[12:13], v0, s[84:87], s28 offen
	buffer_store_dwordx2 v[4:5], v0, s[84:87], s34 offen
	s_cbranch_vccnz .LBB0_313
	s_andn2_b64 vcc, exec, s[2:3]
	s_cbranch_vccnz .LBB0_312
	s_barrier
	s_branch .LBB0_312

; __device__ __forceinline__ f32x4 f16x4_to_f32(u32x2e_t w) { return __builtin_convertvector(__builtin_bit_cast(f16x4_t, w), f32x4); }
;     __device__ __forceinline__ void operator()(const f32x4 (&acc)[2][2][4][2], const Unit& u, int wr, int wc, int fr, int fq) const {
;         const int row0 = u.pm * BM + wr * 64 + fr, col0 = u.pn * BM + wc * 32 + 4 * fq;
; #pragma unroll
;         for (int ai = 0; ai < 2; ++ai) {
;             f32x4 xv[4][2][2];
; #pragma unroll
;             for (int m = 0; m < 4; ++m) { const int off = ((row0 + ai * HALF + m * 16) * 4096 + col0) * 2;
; #pragma unroll
;                 for (int bj = 0; bj < 2; ++bj)
; #pragma unroll
;                     for (int n = 0; n < 2; ++n) {
;                         if constexpr (XH) xv[m][bj][n] = f16x4_to_f32(__builtin_bit_cast(u32x2e_t, __builtin_amdgcn_raw_buffer_load_b64(X, off + (bj * HALF + n * 16) * 2, 0, 0)));
;                         else xv[m][bj][n] = __builtin_bit_cast(f32x4, __builtin_amdgcn_raw_buffer_load_b128(X, 2 * off + (bj * HALF + n * 16) * 4, 0, 0)); } }
; #pragma unroll
;             for (int m = 0; m < 4; ++m) { const int off = ((row0 + ai * HALF + m * 16) * 4096 + col0) * 2;
; #pragma unroll
;                 for (int bj = 0; bj < 2; ++bj)
; #pragma unroll
;                     for (int n = 0; n < 2; ++n) { const f32x4 r = xv[m][bj][n] * alpha + acc[ai][bj][m][n] * scl;
;                         u32x2e_t w; w.x = cvt_pk_f16(r[0], r[1]); w.y = cvt_pk_f16(r[2], r[3]);
;                         __builtin_amdgcn_raw_buffer_store_b64(w, Y, off + (bj * HALF + n * 16) * 2, 0, 0); } }
.LBB0_545:
	v_mov_b32_e32 v141, 0
	s_lshl_b32 s14, s14, 8
	v_mbcnt_lo_u32_b32 v141, -1, v141
	v_mbcnt_hi_u32_b32 v141, -1, v141
	s_add_i32 s14, s14, s51
	v_and_or_b32 v182, v141, 15, s14
	s_lshl_b32 s14, s15, 8
	v_ashrrev_i32_e32 v141, 2, v141
	s_or_b32 s14, s14, s52
	v_and_b32_e32 v141, -4, v141
	v_add_u32_e32 v141, s14, v141
	v_lshlrev_b32_e32 v142, 14, v182
	v_lshl_add_u32 v206, v141, 2, v142
	buffer_load_dwordx4 v[142:145], v206, s[8:11], 0 offen
	buffer_load_dwordx4 v[146:149], v206, s[8:11], 0 offen offset:64
	buffer_load_dwordx4 v[150:153], v206, s[8:11], 0 offen offset:512
	buffer_load_dwordx4 v[154:157], v206, s[8:11], 0 offen offset:576
	v_add_u32_e32 v170, 0x40000, v206
	buffer_load_dwordx4 v[158:161], v170, s[8:11], 0 offen
	buffer_load_dwordx4 v[162:165], v170, s[8:11], 0 offen offset:64
	buffer_load_dwordx4 v[166:169], v170, s[8:11], 0 offen offset:512
	s_nop 0
	buffer_load_dwordx4 v[170:173], v170, s[8:11], 0 offen offset:576
	v_add_u32_e32 v186, 0x80000, v206
	buffer_load_dwordx4 v[174:177], v186, s[8:11], 0 offen
	buffer_load_dwordx4 v[178:181], v186, s[8:11], 0 offen offset:64
	v_lshlrev_b32_e32 v187, 13, v182
	buffer_load_dwordx4 v[182:185], v186, s[8:11], 0 offen offset:512
	v_add_u32_e32 v202, 0xc0000, v206
	v_lshl_add_u32 v141, v141, 1, v187
	buffer_load_dwordx4 v[186:189], v186, s[8:11], 0 offen offset:576
	s_nop 0
	buffer_load_dwordx4 v[190:193], v202, s[8:11], 0 offen
	buffer_load_dwordx4 v[194:197], v202, s[8:11], 0 offen offset:64
	buffer_load_dwordx4 v[198:201], v202, s[8:11], 0 offen offset:512
	s_nop 0
	buffer_load_dwordx4 v[202:205], v202, s[8:11], 0 offen offset:576
	s_mov_b32 s14, s10
	s_mov_b32 s15, s11
	v_add_u32_e32 v207, 0x20000, v141
	s_andn2_b64 vcc, exec, s[4:5]
	s_mov_b64 s[4:5], -1
	s_waitcnt vmcnt(0)
	v_mul_f32_e32 v144, s16, v144
	v_mul_f32_e32 v145, s16, v145
	v_mul_f32_e32 v142, s16, v142
	v_mul_f32_e32 v143, s16, v143
	v_mul_f32_e32 v148, s16, v148
	v_mul_f32_e32 v149, s16, v149
	v_mul_f32_e32 v156, s16, v156
	v_mul_f32_e32 v157, s16, v157
	v_mul_f32_e32 v154, s16, v154
	v_mul_f32_e32 v155, s16, v155
	v_mul_f32_e32 v146, s16, v146
	v_mul_f32_e32 v147, s16, v147
	v_mul_f32_e32 v152, s16, v152
	v_mul_f32_e32 v153, s16, v153
	v_mul_f32_e32 v150, s16, v150
	v_mul_f32_e32 v151, s16, v151
	v_fma_f32 v126, v126, s18, v144
	v_fma_f32 v127, v127, s18, v145
	v_fma_f32 v124, v124, s18, v142
	v_fma_f32 v125, v125, s18, v143
	v_fma_f32 v114, v114, s18, v156
	v_fma_f32 v115, v115, s18, v157
	v_fma_f32 v112, v112, s18, v154
	v_fma_f32 v113, v113, s18, v155
	v_mul_f32_e32 v142, s16, v160
	v_mul_f32_e32 v143, s16, v161
	v_mul_f32_e32 v144, s16, v158
	v_mul_f32_e32 v145, s16, v159
	v_mul_f32_e32 v154, s16, v172
	v_mul_f32_e32 v155, s16, v173
	v_mul_f32_e32 v156, s16, v170
	v_mul_f32_e32 v157, s16, v171
	v_fma_f32 v122, v122, s18, v148
	v_fma_f32 v123, v123, s18, v149
	v_fma_f32 v120, v120, s18, v146
	v_fma_f32 v121, v121, s18, v147
	v_fma_f32 v118, v118, s18, v152
	v_fma_f32 v119, v119, s18, v153
	v_fma_f32 v116, v116, s18, v150
	v_fma_f32 v117, v117, s18, v151
	v_mul_f32_e32 v146, s16, v164
	v_mul_f32_e32 v147, s16, v165
	v_mul_f32_e32 v148, s16, v162
	v_mul_f32_e32 v149, s16, v163
	v_mul_f32_e32 v150, s16, v168
	v_mul_f32_e32 v151, s16, v169
	v_mul_f32_e32 v152, s16, v166
	v_mul_f32_e32 v153, s16, v167
	v_fma_f32 v110, v110, s18, v142
	v_fma_f32 v111, v111, s18, v143
	v_fma_f32 v108, v108, s18, v144
	v_fma_f32 v109, v109, s18, v145
	v_fma_f32 v94, v94, s18, v154
	v_fma_f32 v95, v95, s18, v155
	v_fma_f32 v92, v92, s18, v156
	v_fma_f32 v93, v93, s18, v157
	v_cvt_pk_f16_f32 v124, v124, v125
	v_cvt_pk_f16_f32 v125, v126, v127
	v_fma_f32 v106, v106, s18, v146
	v_fma_f32 v107, v107, s18, v147
	v_fma_f32 v104, v104, s18, v148
	v_fma_f32 v105, v105, s18, v149
	v_fma_f32 v102, v102, s18, v150
	v_fma_f32 v103, v103, s18, v151
	v_fma_f32 v100, v100, s18, v152
	v_fma_f32 v101, v101, s18, v153
	v_cvt_pk_f16_f32 v108, v108, v109
	v_cvt_pk_f16_f32 v109, v110, v111
	v_cvt_pk_f16_f32 v92, v92, v93
	v_cvt_pk_f16_f32 v93, v94, v95
	v_cvt_pk_f16_f32 v120, v120, v121
	v_cvt_pk_f16_f32 v121, v122, v123
	v_cvt_pk_f16_f32 v116, v116, v117
	v_cvt_pk_f16_f32 v117, v118, v119
	v_cvt_pk_f16_f32 v112, v112, v113
	v_cvt_pk_f16_f32 v113, v114, v115
	buffer_store_dwordx2 v[124:125], v141, s[12:15], 0 offen
	buffer_store_dwordx2 v[120:121], v141, s[12:15], 0 offen offset:32
	buffer_store_dwordx2 v[116:117], v141, s[12:15], 0 offen offset:256
	buffer_store_dwordx2 v[112:113], v141, s[12:15], 0 offen offset:288
	v_cvt_pk_f16_f32 v104, v104, v105
	v_cvt_pk_f16_f32 v105, v106, v107
	v_cvt_pk_f16_f32 v100, v100, v101
	v_cvt_pk_f16_f32 v101, v102, v103
	buffer_store_dwordx2 v[108:109], v207, s[12:15], 0 offen
	buffer_store_dwordx2 v[104:105], v207, s[12:15], 0 offen offset:32
	buffer_store_dwordx2 v[100:101], v207, s[12:15], 0 offen offset:256
	buffer_store_dwordx2 v[92:93], v207, s[12:15], 0 offen offset:288
	v_mul_f32_e32 v92, s16, v176
	v_mul_f32_e32 v93, s16, v177
	v_mul_f32_e32 v94, s16, v174
	v_mul_f32_e32 v95, s16, v175
	v_fma_f32 v92, v98, s18, v92
	v_fma_f32 v93, v99, s18, v93
	v_fma_f32 v94, v96, s18, v94
	v_fma_f32 v95, v97, s18, v95
	v_add_u32_e32 v100, 0x40000, v141
	v_cvt_pk_f16_f32 v94, v94, v95
	v_cvt_pk_f16_f32 v95, v92, v93
	buffer_store_dwordx2 v[94:95], v100, s[12:15], 0 offen
	v_mul_f32_e32 v92, s16, v180
	v_mul_f32_e32 v93, s16, v181
	v_mul_f32_e32 v94, s16, v178
	v_mul_f32_e32 v95, s16, v179
	v_fma_f32 v90, v90, s18, v92
	v_fma_f32 v91, v91, s18, v93
	v_fma_f32 v88, v88, s18, v94
	v_fma_f32 v89, v89, s18, v95
	v_add_u32_e32 v92, 0x240000, v206
	v_cvt_pk_f16_f32 v88, v88, v89
	v_cvt_pk_f16_f32 v89, v90, v91
; __device__ __forceinline__ f32x4 f16x4_to_f32(u32x2e_t w) { return __builtin_convertvector(__builtin_bit_cast(f16x4_t, w), f32x4); }
;     __device__ __forceinline__ void operator()(const f32x4 (&acc)[2][2][4][2], const Unit& u, int wr, int wc, int fr, int fq) const {
;     ...
;             for (int m = 0; m < 4; ++m) { const int off = ((row0 + ai * HALF + m * 16) * 4096 + col0) * 2;
; #pragma unroll
;                 for (int bj = 0; bj < 2; ++bj)
; #pragma unroll
;                     for (int n = 0; n < 2; ++n) {
;                         if constexpr (XH) xv[m][bj][n] = f16x4_to_f32(__builtin_bit_cast(u32x2e_t, __builtin_amdgcn_raw_buffer_load_b64(X, off + (bj * HALF + n * 16) * 2, 0, 0)));
;                         else xv[m][bj][n] = __builtin_bit_cast(f32x4, __builtin_amdgcn_raw_buffer_load_b128(X, 2 * off + (bj * HALF + n * 16) * 4, 0, 0)); } }
; #pragma unroll
;             for (int m = 0; m < 4; ++m) { const int off = ((row0 + ai * HALF + m * 16) * 4096 + col0) * 2;
; #pragma unroll
;                 for (int bj = 0; bj < 2; ++bj)
; #pragma unroll
;                     for (int n = 0; n < 2; ++n) { const f32x4 r = xv[m][bj][n] * alpha + acc[ai][bj][m][n] * scl;
;                         u32x2e_t w; w.x = cvt_pk_f16(r[0], r[1]); w.y = cvt_pk_f16(r[2], r[3]);
;                         __builtin_amdgcn_raw_buffer_store_b64(w, Y, off + (bj * HALF + n * 16) * 2, 0, 0); } }
	buffer_store_dwordx2 v[88:89], v100, s[12:15], 0 offen offset:32
	v_mul_f32_e32 v88, s16, v184
	v_mul_f32_e32 v89, s16, v185
	v_mul_f32_e32 v90, s16, v182
	v_mul_f32_e32 v91, s16, v183
	v_fma_f32 v86, v86, s18, v88
	v_fma_f32 v87, v87, s18, v89
	v_fma_f32 v84, v84, s18, v90
	v_fma_f32 v85, v85, s18, v91
	v_add_u32_e32 v108, 0x280000, v206
	v_cvt_pk_f16_f32 v84, v84, v85
	v_cvt_pk_f16_f32 v85, v86, v87
	buffer_store_dwordx2 v[84:85], v100, s[12:15], 0 offen offset:256
	v_mul_f32_e32 v84, s16, v188
	v_mul_f32_e32 v85, s16, v189
	v_mul_f32_e32 v86, s16, v186
	v_mul_f32_e32 v87, s16, v187
	v_fma_f32 v78, v78, s18, v84
	v_fma_f32 v79, v79, s18, v85
	v_fma_f32 v76, v76, s18, v86
	v_fma_f32 v77, v77, s18, v87
	v_add_u32_e32 v84, 0x60000, v141
	v_cvt_pk_f16_f32 v76, v76, v77
	v_cvt_pk_f16_f32 v77, v78, v79
	buffer_store_dwordx2 v[76:77], v100, s[12:15], 0 offen offset:288
	v_mul_f32_e32 v76, s16, v192
	v_mul_f32_e32 v77, s16, v193
	v_mul_f32_e32 v78, s16, v190
	v_mul_f32_e32 v79, s16, v191
	v_fma_f32 v76, v82, s18, v76
	v_fma_f32 v77, v83, s18, v77
	v_fma_f32 v78, v80, s18, v78
	v_fma_f32 v79, v81, s18, v79
	v_add_u32_e32 v124, 0x2c0000, v206
	v_cvt_pk_f16_f32 v78, v78, v79
	v_cvt_pk_f16_f32 v79, v76, v77
	buffer_store_dwordx2 v[78:79], v84, s[12:15], 0 offen
	v_mul_f32_e32 v76, s16, v196
	v_mul_f32_e32 v77, s16, v197
	v_mul_f32_e32 v78, s16, v194
	v_mul_f32_e32 v79, s16, v195
	v_fma_f32 v74, v74, s18, v76
	v_fma_f32 v75, v75, s18, v77
	v_fma_f32 v72, v72, s18, v78
	v_fma_f32 v73, v73, s18, v79
	v_add_u32_e32 v76, 0x200000, v206
	v_cvt_pk_f16_f32 v72, v72, v73
	v_cvt_pk_f16_f32 v73, v74, v75
	buffer_store_dwordx2 v[72:73], v84, s[12:15], 0 offen offset:32
	v_mul_f32_e32 v72, s16, v200
	v_mul_f32_e32 v73, s16, v201
	v_mul_f32_e32 v74, s16, v198
	v_mul_f32_e32 v75, s16, v199
	v_fma_f32 v70, v70, s18, v72
	v_fma_f32 v71, v71, s18, v73
	v_fma_f32 v68, v68, s18, v74
	v_fma_f32 v69, v69, s18, v75
	v_add_u32_e32 v142, 0x100000, v141
	v_cvt_pk_f16_f32 v68, v68, v69
	v_cvt_pk_f16_f32 v69, v70, v71
	buffer_store_dwordx2 v[68:69], v84, s[12:15], 0 offen offset:256
	v_mul_f32_e32 v68, s16, v204
	v_mul_f32_e32 v69, s16, v205
	v_mul_f32_e32 v70, s16, v202
	v_mul_f32_e32 v71, s16, v203
	v_fma_f32 v66, v66, s18, v68
	v_fma_f32 v67, v67, s18, v69
	v_fma_f32 v64, v64, s18, v70
	v_fma_f32 v65, v65, s18, v71
	s_nop 0
	v_cvt_pk_f16_f32 v64, v64, v65
	v_cvt_pk_f16_f32 v65, v66, v67
	buffer_store_dwordx2 v[64:65], v84, s[12:15], 0 offen offset:288
	buffer_load_dwordx4 v[64:67], v76, s[8:11], 0 offen
	buffer_load_dwordx4 v[68:71], v76, s[8:11], 0 offen offset:64
	buffer_load_dwordx4 v[72:75], v76, s[8:11], 0 offen offset:512
	s_nop 0
	buffer_load_dwordx4 v[76:79], v76, s[8:11], 0 offen offset:576
	s_nop 0
	buffer_load_dwordx4 v[80:83], v92, s[8:11], 0 offen
	buffer_load_dwordx4 v[84:87], v92, s[8:11], 0 offen offset:64
	buffer_load_dwordx4 v[88:91], v92, s[8:11], 0 offen offset:512
	s_nop 0
	buffer_load_dwordx4 v[92:95], v92, s[8:11], 0 offen offset:576
	s_nop 0
	buffer_load_dwordx4 v[96:99], v108, s[8:11], 0 offen
	buffer_load_dwordx4 v[100:103], v108, s[8:11], 0 offen offset:64
	buffer_load_dwordx4 v[104:107], v108, s[8:11], 0 offen offset:512
	s_nop 0
	buffer_load_dwordx4 v[108:111], v108, s[8:11], 0 offen offset:576
	s_nop 0
	buffer_load_dwordx4 v[112:115], v124, s[8:11], 0 offen
	buffer_load_dwordx4 v[116:119], v124, s[8:11], 0 offen offset:64
	buffer_load_dwordx4 v[120:123], v124, s[8:11], 0 offen offset:512
	s_nop 0
	buffer_load_dwordx4 v[124:127], v124, s[8:11], 0 offen offset:576
	s_waitcnt vmcnt(15)
	v_mul_f32_e32 v66, s16, v66
	v_mul_f32_e32 v67, s16, v67
	v_mul_f32_e32 v64, s16, v64
	v_mul_f32_e32 v65, s16, v65
	v_fma_f32 v62, v62, s18, v66
	v_fma_f32 v63, v63, s18, v67
	v_fma_f32 v60, v60, s18, v64
	v_fma_f32 v61, v61, s18, v65
	s_nop 0
	v_cvt_pk_f16_f32 v60, v60, v61
	v_cvt_pk_f16_f32 v61, v62, v63
	buffer_store_dwordx2 v[60:61], v142, s[12:15], 0 offen
	s_waitcnt vmcnt(15)
	v_mul_f32_e32 v60, s16, v70
	v_mul_f32_e32 v61, s16, v71
	v_mul_f32_e32 v62, s16, v68
	v_mul_f32_e32 v63, s16, v69
	v_fma_f32 v58, v58, s18, v60
	v_fma_f32 v59, v59, s18, v61
	v_fma_f32 v56, v56, s18, v62
	v_fma_f32 v57, v57, s18, v63
	s_nop 0
	v_cvt_pk_f16_f32 v56, v56, v57
	v_cvt_pk_f16_f32 v57, v58, v59
	buffer_store_dwordx2 v[56:57], v142, s[12:15], 0 offen offset:32
	s_waitcnt vmcnt(15)
	v_mul_f32_e32 v56, s16, v74
	v_mul_f32_e32 v57, s16, v75
	v_mul_f32_e32 v58, s16, v72
	v_mul_f32_e32 v59, s16, v73
	v_fma_f32 v54, v54, s18, v56
	v_fma_f32 v55, v55, s18, v57
	v_fma_f32 v52, v52, s18, v58
	v_fma_f32 v53, v53, s18, v59
	s_nop 0
	v_cvt_pk_f16_f32 v52, v52, v53
	v_cvt_pk_f16_f32 v53, v54, v55
	buffer_store_dwordx2 v[52:53], v142, s[12:15], 0 offen offset:256
	s_waitcnt vmcnt(15)
	v_mul_f32_e32 v52, s16, v78
	v_mul_f32_e32 v53, s16, v79
	v_mul_f32_e32 v54, s16, v76
	v_mul_f32_e32 v55, s16, v77
	v_fma_f32 v46, v46, s18, v52
	v_fma_f32 v47, v47, s18, v53
	v_fma_f32 v44, v44, s18, v54
	v_fma_f32 v45, v45, s18, v55
	v_add_u32_e32 v52, 0x120000, v141
	v_cvt_pk_f16_f32 v44, v44, v45
	v_cvt_pk_f16_f32 v45, v46, v47
	buffer_store_dwordx2 v[44:45], v142, s[12:15], 0 offen offset:288
	s_waitcnt vmcnt(15)
; __device__ __forceinline__ f32x4 f16x4_to_f32(u32x2e_t w) { return __builtin_convertvector(__builtin_bit_cast(f16x4_t, w), f32x4); }
;     __device__ __forceinline__ void operator()(const f32x4 (&acc)[2][2][4][2], const Unit& u, int wr, int wc, int fr, int fq) const {
;     ...
;             for (int m = 0; m < 4; ++m) { const int off = ((row0 + ai * HALF + m * 16) * 4096 + col0) * 2;
; #pragma unroll
;                 for (int bj = 0; bj < 2; ++bj)
; #pragma unroll
;                     for (int n = 0; n < 2; ++n) {
;                         if constexpr (XH) xv[m][bj][n] = f16x4_to_f32(__builtin_bit_cast(u32x2e_t, __builtin_amdgcn_raw_buffer_load_b64(X, off + (bj * HALF + n * 16) * 2, 0, 0)));
;                         else xv[m][bj][n] = __builtin_bit_cast(f32x4, __builtin_amdgcn_raw_buffer_load_b128(X, 2 * off + (bj * HALF + n * 16) * 4, 0, 0)); } }
; #pragma unroll
;             for (int m = 0; m < 4; ++m) { const int off = ((row0 + ai * HALF + m * 16) * 4096 + col0) * 2;
; #pragma unroll
;                 for (int bj = 0; bj < 2; ++bj)
; #pragma unroll
;                     for (int n = 0; n < 2; ++n) { const f32x4 r = xv[m][bj][n] * alpha + acc[ai][bj][m][n] * scl;
;                         u32x2e_t w; w.x = cvt_pk_f16(r[0], r[1]); w.y = cvt_pk_f16(r[2], r[3]);
;                         __builtin_amdgcn_raw_buffer_store_b64(w, Y, off + (bj * HALF + n * 16) * 2, 0, 0); } }
;             asm volatile("" ::: "memory"); }
	v_mul_f32_e32 v44, s16, v82
	v_mul_f32_e32 v45, s16, v83
	v_mul_f32_e32 v46, s16, v80
	v_mul_f32_e32 v47, s16, v81
	v_fma_f32 v44, v50, s18, v44
	v_fma_f32 v45, v51, s18, v45
	v_fma_f32 v46, v48, s18, v46
	v_fma_f32 v47, v49, s18, v47
	s_nop 0
	v_cvt_pk_f16_f32 v46, v46, v47
	v_cvt_pk_f16_f32 v47, v44, v45
	buffer_store_dwordx2 v[46:47], v52, s[12:15], 0 offen
	s_waitcnt vmcnt(15)
	v_mul_f32_e32 v44, s16, v86
	v_mul_f32_e32 v45, s16, v87
	v_mul_f32_e32 v46, s16, v84
	v_mul_f32_e32 v47, s16, v85
	v_fma_f32 v42, v42, s18, v44
	v_fma_f32 v43, v43, s18, v45
	v_fma_f32 v40, v40, s18, v46
	v_fma_f32 v41, v41, s18, v47
	s_nop 0
	v_cvt_pk_f16_f32 v40, v40, v41
	v_cvt_pk_f16_f32 v41, v42, v43
	buffer_store_dwordx2 v[40:41], v52, s[12:15], 0 offen offset:32
	s_waitcnt vmcnt(15)
	v_mul_f32_e32 v40, s16, v90
	v_mul_f32_e32 v41, s16, v91
	v_mul_f32_e32 v42, s16, v88
	v_mul_f32_e32 v43, s16, v89
	v_fma_f32 v38, v38, s18, v40
	v_fma_f32 v39, v39, s18, v41
	v_fma_f32 v36, v36, s18, v42
	v_fma_f32 v37, v37, s18, v43
	s_nop 0
	v_cvt_pk_f16_f32 v36, v36, v37
	v_cvt_pk_f16_f32 v37, v38, v39
	buffer_store_dwordx2 v[36:37], v52, s[12:15], 0 offen offset:256
	s_waitcnt vmcnt(15)
	v_mul_f32_e32 v36, s16, v94
	v_mul_f32_e32 v37, s16, v95
	v_mul_f32_e32 v38, s16, v92
	v_mul_f32_e32 v39, s16, v93
	v_fma_f32 v30, v30, s18, v36
	v_fma_f32 v31, v31, s18, v37
	v_fma_f32 v28, v28, s18, v38
	v_fma_f32 v29, v29, s18, v39
	v_add_u32_e32 v36, 0x140000, v141
	v_cvt_pk_f16_f32 v28, v28, v29
	v_cvt_pk_f16_f32 v29, v30, v31
	buffer_store_dwordx2 v[28:29], v52, s[12:15], 0 offen offset:288
	s_waitcnt vmcnt(15)
	v_mul_f32_e32 v28, s16, v98
	v_mul_f32_e32 v29, s16, v99
	v_mul_f32_e32 v30, s16, v96
	v_mul_f32_e32 v31, s16, v97
	v_fma_f32 v28, v34, s18, v28
	v_fma_f32 v29, v35, s18, v29
	v_fma_f32 v30, v32, s18, v30
	v_fma_f32 v31, v33, s18, v31
	s_nop 0
	v_cvt_pk_f16_f32 v30, v30, v31
	v_cvt_pk_f16_f32 v31, v28, v29
	buffer_store_dwordx2 v[30:31], v36, s[12:15], 0 offen
	s_waitcnt vmcnt(15)
	v_mul_f32_e32 v28, s16, v102
	v_mul_f32_e32 v29, s16, v103
	v_mul_f32_e32 v30, s16, v100
	v_mul_f32_e32 v31, s16, v101
	v_fma_f32 v26, v26, s18, v28
	v_fma_f32 v27, v27, s18, v29
	v_fma_f32 v24, v24, s18, v30
	v_fma_f32 v25, v25, s18, v31
	s_nop 0
	v_cvt_pk_f16_f32 v24, v24, v25
	v_cvt_pk_f16_f32 v25, v26, v27
	buffer_store_dwordx2 v[24:25], v36, s[12:15], 0 offen offset:32
	s_waitcnt vmcnt(15)
	v_mul_f32_e32 v24, s16, v106
	v_mul_f32_e32 v25, s16, v107
	v_mul_f32_e32 v26, s16, v104
	v_mul_f32_e32 v27, s16, v105
	v_fma_f32 v22, v22, s18, v24
	v_fma_f32 v23, v23, s18, v25
	v_fma_f32 v20, v20, s18, v26
	v_fma_f32 v21, v21, s18, v27
	s_nop 0
	v_cvt_pk_f16_f32 v20, v20, v21
	v_cvt_pk_f16_f32 v21, v22, v23
	buffer_store_dwordx2 v[20:21], v36, s[12:15], 0 offen offset:256
	s_waitcnt vmcnt(15)
	v_mul_f32_e32 v20, s16, v110
	v_mul_f32_e32 v21, s16, v111
	v_mul_f32_e32 v22, s16, v108
	v_mul_f32_e32 v23, s16, v109
	v_fma_f32 v14, v14, s18, v20
	v_fma_f32 v15, v15, s18, v21
	v_fma_f32 v12, v12, s18, v22
	v_fma_f32 v13, v13, s18, v23
	v_add_u32_e32 v20, 0x160000, v141
	v_cvt_pk_f16_f32 v12, v12, v13
	v_cvt_pk_f16_f32 v13, v14, v15
	buffer_store_dwordx2 v[12:13], v36, s[12:15], 0 offen offset:288
	s_waitcnt vmcnt(15)
	v_mul_f32_e32 v12, s16, v114
	v_mul_f32_e32 v13, s16, v115
	v_mul_f32_e32 v14, s16, v112
	v_mul_f32_e32 v15, s16, v113
	v_fma_f32 v12, v18, s18, v12
	v_fma_f32 v13, v19, s18, v13
	v_fma_f32 v14, v16, s18, v14
	v_fma_f32 v15, v17, s18, v15
	s_nop 0
	v_cvt_pk_f16_f32 v14, v14, v15
	v_cvt_pk_f16_f32 v15, v12, v13
	buffer_store_dwordx2 v[14:15], v20, s[12:15], 0 offen
	s_waitcnt vmcnt(15)
	v_mul_f32_e32 v12, s16, v118
	v_mul_f32_e32 v13, s16, v119
	v_mul_f32_e32 v14, s16, v116
	v_mul_f32_e32 v15, s16, v117
	v_fma_f32 v10, v10, s18, v12
	v_fma_f32 v11, v11, s18, v13
	v_fma_f32 v8, v8, s18, v14
	v_fma_f32 v9, v9, s18, v15
	s_nop 0
	v_cvt_pk_f16_f32 v8, v8, v9
	v_cvt_pk_f16_f32 v9, v10, v11
	buffer_store_dwordx2 v[8:9], v20, s[12:15], 0 offen offset:32
	s_waitcnt vmcnt(15)
	v_mul_f32_e32 v8, s16, v122
	v_mul_f32_e32 v9, s16, v123
	v_mul_f32_e32 v10, s16, v120
	v_mul_f32_e32 v11, s16, v121
	v_fma_f32 v6, v6, s18, v8
	v_fma_f32 v7, v7, s18, v9
	v_fma_f32 v4, v4, s18, v10
	v_fma_f32 v5, v5, s18, v11
	s_nop 0
	v_cvt_pk_f16_f32 v4, v4, v5
	v_cvt_pk_f16_f32 v5, v6, v7
	buffer_store_dwordx2 v[4:5], v20, s[12:15], 0 offen offset:256
	s_waitcnt vmcnt(15)
	v_mul_f32_e32 v4, s16, v126
	v_mul_f32_e32 v5, s16, v127
	v_mul_f32_e32 v6, s16, v124
	v_mul_f32_e32 v7, s16, v125
	v_fma_f32 v2, v2, s18, v4
	v_fma_f32 v3, v3, s18, v5
	v_fma_f32 v0, v0, s18, v6
	v_fma_f32 v1, v1, s18, v7
	s_nop 0
	v_cvt_pk_f16_f32 v0, v0, v1
	v_cvt_pk_f16_f32 v1, v2, v3
	buffer_store_dwordx2 v[0:1], v20, s[12:15], 0 offen offset:288
	s_cbranch_vccnz .LBB0_534
	s_andn2_b64 vcc, exec, s[2:3]
	s_cbranch_vccnz .LBB0_533
	s_barrier
	s_branch .LBB0_533

; __device__ __forceinline__ f32x4 f16x4_to_f32(u32x2e_t w) { return __builtin_convertvector(__builtin_bit_cast(f16x4_t, w), f32x4); }
;     __device__ __forceinline__ void operator()(const f32x4 (&acc)[2][2][4][2], const Unit& u, int wr, int wc, int fr, int fq) const {
;     ...
;             for (int m = 0; m < 4; ++m) { const int off = ((row0 + ai * HALF + m * 16) * 4096 + col0) * 2;
; #pragma unroll
;                 for (int bj = 0; bj < 2; ++bj)
; #pragma unroll
;                     for (int n = 0; n < 2; ++n) {
;                         if constexpr (XH) xv[m][bj][n] = f16x4_to_f32(__builtin_bit_cast(u32x2e_t, __builtin_amdgcn_raw_buffer_load_b64(X, off + (bj * HALF + n * 16) * 2, 0, 0)));
;                         else xv[m][bj][n] = __builtin_bit_cast(f32x4, __builtin_amdgcn_raw_buffer_load_b128(X, 2 * off + (bj * HALF + n * 16) * 4, 0, 0)); } }
; #pragma unroll
;             for (int m = 0; m < 4; ++m) { const int off = ((row0 + ai * HALF + m * 16) * 4096 + col0) * 2;
; #pragma unroll
;                 for (int bj = 0; bj < 2; ++bj)
; #pragma unroll
;                     for (int n = 0; n < 2; ++n) { const f32x4 r = xv[m][bj][n] * alpha + acc[ai][bj][m][n] * scl;
;                         u32x2e_t w; w.x = cvt_pk_f16(r[0], r[1]); w.y = cvt_pk_f16(r[2], r[3]);
;                         __builtin_amdgcn_raw_buffer_store_b64(w, Y, off + (bj * HALF + n * 16) * 2, 0, 0); } }
.LBB0_796:
	v_mov_b32_e32 v140, 0
	s_lshl_b32 s10, s50, 8
	v_mbcnt_lo_u32_b32 v140, -1, v140
	v_mbcnt_hi_u32_b32 v140, -1, v140
	s_add_i32 s10, s10, s42
	v_and_or_b32 v141, v140, 15, s10
	s_lshl_b32 s10, s51, 9
	v_ashrrev_i32_e32 v140, 1, v140
	s_or_b32 s10, s10, s45
	v_lshlrev_b32_e32 v141, 13, v141
	v_and_b32_e32 v140, -8, v140
	v_add3_u32 v204, s10, v140, v141
	buffer_load_dwordx2 v[140:141], v204, s[16:19], 0 offen
	buffer_load_dwordx2 v[142:143], v204, s[16:19], 0 offen offset:32
	buffer_load_dwordx2 v[144:145], v204, s[16:19], 0 offen offset:256
	buffer_load_dwordx2 v[146:147], v204, s[16:19], 0 offen offset:288
	v_add_u32_e32 v205, 0x20000, v204
	v_add_u32_e32 v206, 0x40000, v204
	buffer_load_dwordx2 v[148:149], v205, s[16:19], 0 offen
	buffer_load_dwordx2 v[150:151], v205, s[16:19], 0 offen offset:32
	buffer_load_dwordx2 v[152:153], v205, s[16:19], 0 offen offset:256
	buffer_load_dwordx2 v[154:155], v205, s[16:19], 0 offen offset:288
	buffer_load_dwordx2 v[156:157], v206, s[16:19], 0 offen
	buffer_load_dwordx2 v[158:159], v206, s[16:19], 0 offen offset:32
	buffer_load_dwordx2 v[160:161], v206, s[16:19], 0 offen offset:256
	buffer_load_dwordx2 v[162:163], v206, s[16:19], 0 offen offset:288
	v_add_u32_e32 v207, 0x60000, v204
	buffer_load_dwordx2 v[164:165], v207, s[16:19], 0 offen
	buffer_load_dwordx2 v[166:167], v207, s[16:19], 0 offen offset:32
	buffer_load_dwordx2 v[168:169], v207, s[16:19], 0 offen offset:256
	buffer_load_dwordx2 v[170:171], v207, s[16:19], 0 offen offset:288
	s_mov_b32 s10, s18
	s_mov_b32 s11, s19
	s_and_b64 vcc, exec, s[4:5]
	s_mov_b64 s[4:5], -1
	s_waitcnt vmcnt(0)
	v_cvt_f32_f16_e32 v172, v140
	v_cvt_f32_f16_sdwa v173, v140 dst_sel:DWORD dst_unused:UNUSED_PAD src0_sel:WORD_1
	v_cvt_f32_f16_e32 v140, v141
	v_cvt_f32_f16_e32 v178, v146
	v_cvt_f32_f16_sdwa v179, v146 dst_sel:DWORD dst_unused:UNUSED_PAD src0_sel:WORD_1
	v_cvt_f32_f16_e32 v146, v147
	v_cvt_f32_f16_sdwa v147, v147 dst_sel:DWORD dst_unused:UNUSED_PAD src0_sel:WORD_1
	v_cvt_f32_f16_sdwa v141, v141 dst_sel:DWORD dst_unused:UNUSED_PAD src0_sel:WORD_1
	v_cvt_f32_f16_e32 v174, v142
	v_cvt_f32_f16_sdwa v175, v142 dst_sel:DWORD dst_unused:UNUSED_PAD src0_sel:WORD_1
	v_cvt_f32_f16_e32 v142, v143
	v_cvt_f32_f16_sdwa v143, v143 dst_sel:DWORD dst_unused:UNUSED_PAD src0_sel:WORD_1
	v_cvt_f32_f16_e32 v176, v144
	v_cvt_f32_f16_sdwa v177, v144 dst_sel:DWORD dst_unused:UNUSED_PAD src0_sel:WORD_1
	v_cvt_f32_f16_e32 v144, v145
	v_cvt_f32_f16_sdwa v145, v145 dst_sel:DWORD dst_unused:UNUSED_PAD src0_sel:WORD_1
	v_cvt_f32_f16_e32 v180, v148
	v_cvt_f32_f16_sdwa v181, v148 dst_sel:DWORD dst_unused:UNUSED_PAD src0_sel:WORD_1
	v_cvt_f32_f16_e32 v148, v149
	v_cvt_f32_f16_sdwa v149, v149 dst_sel:DWORD dst_unused:UNUSED_PAD src0_sel:WORD_1
	v_cvt_f32_f16_e32 v182, v150
	v_cvt_f32_f16_sdwa v183, v150 dst_sel:DWORD dst_unused:UNUSED_PAD src0_sel:WORD_1
	v_cvt_f32_f16_e32 v150, v151
	v_cvt_f32_f16_sdwa v151, v151 dst_sel:DWORD dst_unused:UNUSED_PAD src0_sel:WORD_1
	v_cvt_f32_f16_e32 v184, v152
	v_cvt_f32_f16_sdwa v185, v152 dst_sel:DWORD dst_unused:UNUSED_PAD src0_sel:WORD_1
	v_cvt_f32_f16_e32 v152, v153
	v_cvt_f32_f16_sdwa v153, v153 dst_sel:DWORD dst_unused:UNUSED_PAD src0_sel:WORD_1
	v_cvt_f32_f16_e32 v186, v154
	v_cvt_f32_f16_sdwa v187, v154 dst_sel:DWORD dst_unused:UNUSED_PAD src0_sel:WORD_1
	v_cvt_f32_f16_e32 v154, v155
	v_cvt_f32_f16_sdwa v155, v155 dst_sel:DWORD dst_unused:UNUSED_PAD src0_sel:WORD_1
	v_cvt_f32_f16_e32 v194, v162
	v_cvt_f32_f16_sdwa v195, v162 dst_sel:DWORD dst_unused:UNUSED_PAD src0_sel:WORD_1
	v_cvt_f32_f16_e32 v162, v163
	v_cvt_f32_f16_sdwa v163, v163 dst_sel:DWORD dst_unused:UNUSED_PAD src0_sel:WORD_1
	v_cvt_f32_f16_e32 v188, v156
	v_cvt_f32_f16_sdwa v189, v156 dst_sel:DWORD dst_unused:UNUSED_PAD src0_sel:WORD_1
	v_cvt_f32_f16_e32 v156, v157
	v_cvt_f32_f16_sdwa v157, v157 dst_sel:DWORD dst_unused:UNUSED_PAD src0_sel:WORD_1
	v_cvt_f32_f16_e32 v190, v158
	v_cvt_f32_f16_sdwa v191, v158 dst_sel:DWORD dst_unused:UNUSED_PAD src0_sel:WORD_1
	v_cvt_f32_f16_e32 v158, v159
	v_cvt_f32_f16_sdwa v159, v159 dst_sel:DWORD dst_unused:UNUSED_PAD src0_sel:WORD_1
	v_cvt_f32_f16_e32 v192, v160
	v_cvt_f32_f16_sdwa v193, v160 dst_sel:DWORD dst_unused:UNUSED_PAD src0_sel:WORD_1
	v_cvt_f32_f16_e32 v160, v161
	v_cvt_f32_f16_sdwa v161, v161 dst_sel:DWORD dst_unused:UNUSED_PAD src0_sel:WORD_1
	v_cvt_f32_f16_e32 v196, v164
	v_cvt_f32_f16_sdwa v197, v164 dst_sel:DWORD dst_unused:UNUSED_PAD src0_sel:WORD_1
	v_cvt_f32_f16_e32 v164, v165
	v_cvt_f32_f16_sdwa v165, v165 dst_sel:DWORD dst_unused:UNUSED_PAD src0_sel:WORD_1
	v_cvt_f32_f16_e32 v198, v166
	v_cvt_f32_f16_sdwa v199, v166 dst_sel:DWORD dst_unused:UNUSED_PAD src0_sel:WORD_1
	v_cvt_f32_f16_e32 v166, v167
	v_cvt_f32_f16_sdwa v167, v167 dst_sel:DWORD dst_unused:UNUSED_PAD src0_sel:WORD_1
	v_cvt_f32_f16_e32 v200, v168
	v_cvt_f32_f16_sdwa v201, v168 dst_sel:DWORD dst_unused:UNUSED_PAD src0_sel:WORD_1
	v_cvt_f32_f16_e32 v168, v169
	v_cvt_f32_f16_sdwa v169, v169 dst_sel:DWORD dst_unused:UNUSED_PAD src0_sel:WORD_1
	v_cvt_f32_f16_e32 v202, v170
	v_cvt_f32_f16_sdwa v203, v170 dst_sel:DWORD dst_unused:UNUSED_PAD src0_sel:WORD_1
	v_cvt_f32_f16_e32 v170, v171
	v_cvt_f32_f16_sdwa v171, v171 dst_sel:DWORD dst_unused:UNUSED_PAD src0_sel:WORD_1
	v_fma_f32 v110, v146, s14, v110
	v_fma_f32 v111, v147, s14, v111
	v_fma_f32 v108, v178, s14, v108
	v_fma_f32 v109, v179, s14, v109
	v_fma_f32 v126, v140, s14, v126
	v_fma_f32 v127, v141, s14, v127
	v_cvt_pk_f16_f32 v108, v108, v109
	v_cvt_pk_f16_f32 v109, v110, v111
	v_fma_f32 v124, v172, s14, v124
	v_fma_f32 v125, v173, s14, v125
	v_fma_f32 v122, v142, s14, v122
	v_fma_f32 v123, v143, s14, v123
; __device__ __forceinline__ f32x4 f16x4_to_f32(u32x2e_t w) { return __builtin_convertvector(__builtin_bit_cast(f16x4_t, w), f32x4); }
;     __device__ __forceinline__ void operator()(const f32x4 (&acc)[2][2][4][2], const Unit& u, int wr, int wc, int fr, int fq) const {
;     ...
;             for (int m = 0; m < 4; ++m) { const int off = ((row0 + ai * HALF + m * 16) * 4096 + col0) * 2;
; #pragma unroll
;                 for (int bj = 0; bj < 2; ++bj)
; #pragma unroll
;                     for (int n = 0; n < 2; ++n) {
;                         if constexpr (XH) xv[m][bj][n] = f16x4_to_f32(__builtin_bit_cast(u32x2e_t, __builtin_amdgcn_raw_buffer_load_b64(X, off + (bj * HALF + n * 16) * 2, 0, 0)));
;                         else xv[m][bj][n] = __builtin_bit_cast(f32x4, __builtin_amdgcn_raw_buffer_load_b128(X, 2 * off + (bj * HALF + n * 16) * 4, 0, 0)); } }
; #pragma unroll
;             for (int m = 0; m < 4; ++m) { const int off = ((row0 + ai * HALF + m * 16) * 4096 + col0) * 2;
; #pragma unroll
;                 for (int bj = 0; bj < 2; ++bj)
; #pragma unroll
;                     for (int n = 0; n < 2; ++n) { const f32x4 r = xv[m][bj][n] * alpha + acc[ai][bj][m][n] * scl;
;                         u32x2e_t w; w.x = cvt_pk_f16(r[0], r[1]); w.y = cvt_pk_f16(r[2], r[3]);
;                         __builtin_amdgcn_raw_buffer_store_b64(w, Y, off + (bj * HALF + n * 16) * 2, 0, 0); } }
	v_fma_f32 v120, v174, s14, v120
	v_fma_f32 v121, v175, s14, v121
	v_fma_f32 v118, v144, s14, v118
	v_fma_f32 v119, v145, s14, v119
	v_fma_f32 v116, v176, s14, v116
	v_fma_f32 v117, v177, s14, v117
	buffer_store_dwordx2 v[108:109], v204, s[8:11], 0 offen offset:288
	v_fma_f32 v108, v148, s14, v114
	v_fma_f32 v109, v149, s14, v115
	v_fma_f32 v110, v180, s14, v112
	v_fma_f32 v111, v181, s14, v113
	v_fma_f32 v106, v150, s14, v106
	v_fma_f32 v107, v151, s14, v107
	v_fma_f32 v104, v182, s14, v104
	v_fma_f32 v105, v183, s14, v105
	v_fma_f32 v102, v152, s14, v102
	v_fma_f32 v103, v153, s14, v103
	v_fma_f32 v100, v184, s14, v100
	v_fma_f32 v101, v185, s14, v101
	v_fma_f32 v94, v154, s14, v94
	v_fma_f32 v95, v155, s14, v95
	v_fma_f32 v92, v186, s14, v92
	v_fma_f32 v93, v187, s14, v93
	v_fma_f32 v78, v162, s14, v78
	v_fma_f32 v79, v163, s14, v79
	v_fma_f32 v76, v194, s14, v76
	v_fma_f32 v77, v195, s14, v77
	v_cvt_pk_f16_f32 v124, v124, v125
	v_cvt_pk_f16_f32 v125, v126, v127
	v_cvt_pk_f16_f32 v120, v120, v121
	v_cvt_pk_f16_f32 v121, v122, v123
	v_cvt_pk_f16_f32 v116, v116, v117
	v_cvt_pk_f16_f32 v117, v118, v119
	v_cvt_pk_f16_f32 v110, v110, v111
	v_cvt_pk_f16_f32 v111, v108, v109
	v_cvt_pk_f16_f32 v104, v104, v105
	v_cvt_pk_f16_f32 v105, v106, v107
	v_cvt_pk_f16_f32 v100, v100, v101
	v_cvt_pk_f16_f32 v101, v102, v103
	v_cvt_pk_f16_f32 v92, v92, v93
	v_cvt_pk_f16_f32 v93, v94, v95
	v_cvt_pk_f16_f32 v76, v76, v77
	v_cvt_pk_f16_f32 v77, v78, v79
	buffer_store_dwordx2 v[124:125], v204, s[8:11], 0 offen
	buffer_store_dwordx2 v[120:121], v204, s[8:11], 0 offen offset:32
	buffer_store_dwordx2 v[116:117], v204, s[8:11], 0 offen offset:256
	buffer_store_dwordx2 v[110:111], v205, s[8:11], 0 offen
	buffer_store_dwordx2 v[104:105], v205, s[8:11], 0 offen offset:32
	buffer_store_dwordx2 v[100:101], v205, s[8:11], 0 offen offset:256
	buffer_store_dwordx2 v[92:93], v205, s[8:11], 0 offen offset:288
	v_fma_f32 v92, v156, s14, v98
	v_fma_f32 v93, v157, s14, v99
	v_fma_f32 v94, v188, s14, v96
	v_fma_f32 v95, v189, s14, v97
	v_fma_f32 v90, v158, s14, v90
	v_fma_f32 v91, v159, s14, v91
	v_fma_f32 v88, v190, s14, v88
	v_fma_f32 v89, v191, s14, v89
	v_fma_f32 v86, v160, s14, v86
	v_fma_f32 v87, v161, s14, v87
	v_fma_f32 v84, v192, s14, v84
	v_fma_f32 v85, v193, s14, v85
	buffer_store_dwordx2 v[76:77], v206, s[8:11], 0 offen offset:288
	v_fma_f32 v76, v164, s14, v82
	v_fma_f32 v77, v165, s14, v83
	v_fma_f32 v78, v196, s14, v80
	v_fma_f32 v79, v197, s14, v81
	v_fma_f32 v74, v166, s14, v74
	v_fma_f32 v75, v167, s14, v75
	v_fma_f32 v72, v198, s14, v72
	v_fma_f32 v73, v199, s14, v73
	v_fma_f32 v70, v168, s14, v70
	v_fma_f32 v71, v169, s14, v71
	v_fma_f32 v68, v200, s14, v68
	v_fma_f32 v69, v201, s14, v69
	v_fma_f32 v66, v170, s14, v66
	v_fma_f32 v67, v171, s14, v67
	v_fma_f32 v64, v202, s14, v64
	v_fma_f32 v65, v203, s14, v65
	v_cvt_pk_f16_f32 v94, v94, v95
	v_cvt_pk_f16_f32 v95, v92, v93
	v_cvt_pk_f16_f32 v88, v88, v89
	v_cvt_pk_f16_f32 v89, v90, v91
	v_cvt_pk_f16_f32 v84, v84, v85
	v_cvt_pk_f16_f32 v85, v86, v87
	v_cvt_pk_f16_f32 v78, v78, v79
	v_cvt_pk_f16_f32 v79, v76, v77
	v_cvt_pk_f16_f32 v72, v72, v73
	v_cvt_pk_f16_f32 v73, v74, v75
	v_cvt_pk_f16_f32 v68, v68, v69
	v_cvt_pk_f16_f32 v69, v70, v71
	v_cvt_pk_f16_f32 v64, v64, v65
	v_cvt_pk_f16_f32 v65, v66, v67
	buffer_store_dwordx2 v[94:95], v206, s[8:11], 0 offen
	buffer_store_dwordx2 v[88:89], v206, s[8:11], 0 offen offset:32
	buffer_store_dwordx2 v[84:85], v206, s[8:11], 0 offen offset:256
	buffer_store_dwordx2 v[78:79], v207, s[8:11], 0 offen
	buffer_store_dwordx2 v[72:73], v207, s[8:11], 0 offen offset:32
	buffer_store_dwordx2 v[68:69], v207, s[8:11], 0 offen offset:256
	buffer_store_dwordx2 v[64:65], v207, s[8:11], 0 offen offset:288
	v_add_u32_e32 v140, 0x100000, v204
	buffer_load_dwordx2 v[64:65], v140, s[16:19], 0 offen
	buffer_load_dwordx2 v[66:67], v140, s[16:19], 0 offen offset:32
	buffer_load_dwordx2 v[68:69], v140, s[16:19], 0 offen offset:256
	buffer_load_dwordx2 v[70:71], v140, s[16:19], 0 offen offset:288
	v_add_u32_e32 v141, 0x120000, v204
	v_add_u32_e32 v142, 0x140000, v204
	buffer_load_dwordx2 v[72:73], v141, s[16:19], 0 offen
	buffer_load_dwordx2 v[74:75], v141, s[16:19], 0 offen offset:32
	buffer_load_dwordx2 v[76:77], v141, s[16:19], 0 offen offset:256
	buffer_load_dwordx2 v[78:79], v141, s[16:19], 0 offen offset:288
	buffer_load_dwordx2 v[80:81], v142, s[16:19], 0 offen
	buffer_load_dwordx2 v[82:83], v142, s[16:19], 0 offen offset:32
	buffer_load_dwordx2 v[84:85], v142, s[16:19], 0 offen offset:256
	buffer_load_dwordx2 v[86:87], v142, s[16:19], 0 offen offset:288
	v_add_u32_e32 v143, 0x160000, v204
	buffer_load_dwordx2 v[88:89], v143, s[16:19], 0 offen
	buffer_load_dwordx2 v[90:91], v143, s[16:19], 0 offen offset:32
	buffer_load_dwordx2 v[92:93], v143, s[16:19], 0 offen offset:256
	buffer_load_dwordx2 v[94:95], v143, s[16:19], 0 offen offset:288
	s_waitcnt vmcnt(15)
	v_cvt_f32_f16_e32 v96, v64
	v_cvt_f32_f16_sdwa v97, v64 dst_sel:DWORD dst_unused:UNUSED_PAD src0_sel:WORD_1
	v_cvt_f32_f16_e32 v64, v65
	s_waitcnt vmcnt(12)
	v_cvt_f32_f16_e32 v102, v70
	v_cvt_f32_f16_sdwa v103, v70 dst_sel:DWORD dst_unused:UNUSED_PAD src0_sel:WORD_1
	v_cvt_f32_f16_e32 v70, v71
	v_cvt_f32_f16_sdwa v71, v71 dst_sel:DWORD dst_unused:UNUSED_PAD src0_sel:WORD_1
	v_cvt_f32_f16_sdwa v65, v65 dst_sel:DWORD dst_unused:UNUSED_PAD src0_sel:WORD_1
	v_cvt_f32_f16_e32 v98, v66
	v_cvt_f32_f16_sdwa v99, v66 dst_sel:DWORD dst_unused:UNUSED_PAD src0_sel:WORD_1
	v_cvt_f32_f16_e32 v66, v67
	v_cvt_f32_f16_sdwa v67, v67 dst_sel:DWORD dst_unused:UNUSED_PAD src0_sel:WORD_1
	v_cvt_f32_f16_e32 v100, v68
	v_cvt_f32_f16_sdwa v101, v68 dst_sel:DWORD dst_unused:UNUSED_PAD src0_sel:WORD_1
	v_cvt_f32_f16_e32 v68, v69
	v_cvt_f32_f16_sdwa v69, v69 dst_sel:DWORD dst_unused:UNUSED_PAD src0_sel:WORD_1
	s_waitcnt vmcnt(11)
; __device__ __forceinline__ f32x4 f16x4_to_f32(u32x2e_t w) { return __builtin_convertvector(__builtin_bit_cast(f16x4_t, w), f32x4); }
;     __device__ __forceinline__ void operator()(const f32x4 (&acc)[2][2][4][2], const Unit& u, int wr, int wc, int fr, int fq) const {
;     ...
;             for (int m = 0; m < 4; ++m) { const int off = ((row0 + ai * HALF + m * 16) * 4096 + col0) * 2;
; #pragma unroll
;                 for (int bj = 0; bj < 2; ++bj)
; #pragma unroll
;                     for (int n = 0; n < 2; ++n) {
;                         if constexpr (XH) xv[m][bj][n] = f16x4_to_f32(__builtin_bit_cast(u32x2e_t, __builtin_amdgcn_raw_buffer_load_b64(X, off + (bj * HALF + n * 16) * 2, 0, 0)));
;                         else xv[m][bj][n] = __builtin_bit_cast(f32x4, __builtin_amdgcn_raw_buffer_load_b128(X, 2 * off + (bj * HALF + n * 16) * 4, 0, 0)); } }
; #pragma unroll
;             for (int m = 0; m < 4; ++m) { const int off = ((row0 + ai * HALF + m * 16) * 4096 + col0) * 2;
; #pragma unroll
;                 for (int bj = 0; bj < 2; ++bj)
; #pragma unroll
;                     for (int n = 0; n < 2; ++n) { const f32x4 r = xv[m][bj][n] * alpha + acc[ai][bj][m][n] * scl;
;                         u32x2e_t w; w.x = cvt_pk_f16(r[0], r[1]); w.y = cvt_pk_f16(r[2], r[3]);
;                         __builtin_amdgcn_raw_buffer_store_b64(w, Y, off + (bj * HALF + n * 16) * 2, 0, 0); } }
;             asm volatile("" ::: "memory"); }
	v_cvt_f32_f16_e32 v104, v72
	v_cvt_f32_f16_sdwa v105, v72 dst_sel:DWORD dst_unused:UNUSED_PAD src0_sel:WORD_1
	v_cvt_f32_f16_e32 v72, v73
	v_cvt_f32_f16_sdwa v73, v73 dst_sel:DWORD dst_unused:UNUSED_PAD src0_sel:WORD_1
	s_waitcnt vmcnt(10)
	v_cvt_f32_f16_e32 v106, v74
	v_cvt_f32_f16_sdwa v107, v74 dst_sel:DWORD dst_unused:UNUSED_PAD src0_sel:WORD_1
	v_cvt_f32_f16_e32 v74, v75
	v_cvt_f32_f16_sdwa v75, v75 dst_sel:DWORD dst_unused:UNUSED_PAD src0_sel:WORD_1
	s_waitcnt vmcnt(9)
	v_cvt_f32_f16_e32 v108, v76
	v_cvt_f32_f16_sdwa v109, v76 dst_sel:DWORD dst_unused:UNUSED_PAD src0_sel:WORD_1
	v_cvt_f32_f16_e32 v76, v77
	v_cvt_f32_f16_sdwa v77, v77 dst_sel:DWORD dst_unused:UNUSED_PAD src0_sel:WORD_1
	s_waitcnt vmcnt(8)
	v_cvt_f32_f16_e32 v110, v78
	v_cvt_f32_f16_sdwa v111, v78 dst_sel:DWORD dst_unused:UNUSED_PAD src0_sel:WORD_1
	v_cvt_f32_f16_e32 v78, v79
	v_cvt_f32_f16_sdwa v79, v79 dst_sel:DWORD dst_unused:UNUSED_PAD src0_sel:WORD_1
	s_waitcnt vmcnt(4)
	v_cvt_f32_f16_e32 v118, v86
	v_cvt_f32_f16_sdwa v119, v86 dst_sel:DWORD dst_unused:UNUSED_PAD src0_sel:WORD_1
	v_cvt_f32_f16_e32 v86, v87
	v_cvt_f32_f16_sdwa v87, v87 dst_sel:DWORD dst_unused:UNUSED_PAD src0_sel:WORD_1
	v_cvt_f32_f16_e32 v112, v80
	v_cvt_f32_f16_sdwa v113, v80 dst_sel:DWORD dst_unused:UNUSED_PAD src0_sel:WORD_1
	v_cvt_f32_f16_e32 v80, v81
	v_cvt_f32_f16_sdwa v81, v81 dst_sel:DWORD dst_unused:UNUSED_PAD src0_sel:WORD_1
	v_cvt_f32_f16_e32 v114, v82
	v_cvt_f32_f16_sdwa v115, v82 dst_sel:DWORD dst_unused:UNUSED_PAD src0_sel:WORD_1
	v_cvt_f32_f16_e32 v82, v83
	v_cvt_f32_f16_sdwa v83, v83 dst_sel:DWORD dst_unused:UNUSED_PAD src0_sel:WORD_1
	v_cvt_f32_f16_e32 v116, v84
	v_cvt_f32_f16_sdwa v117, v84 dst_sel:DWORD dst_unused:UNUSED_PAD src0_sel:WORD_1
	v_cvt_f32_f16_e32 v84, v85
	v_cvt_f32_f16_sdwa v85, v85 dst_sel:DWORD dst_unused:UNUSED_PAD src0_sel:WORD_1
	s_waitcnt vmcnt(3)
	v_cvt_f32_f16_e32 v120, v88
	v_cvt_f32_f16_sdwa v121, v88 dst_sel:DWORD dst_unused:UNUSED_PAD src0_sel:WORD_1
	v_cvt_f32_f16_e32 v88, v89
	v_cvt_f32_f16_sdwa v89, v89 dst_sel:DWORD dst_unused:UNUSED_PAD src0_sel:WORD_1
	s_waitcnt vmcnt(2)
	v_cvt_f32_f16_e32 v122, v90
	v_cvt_f32_f16_sdwa v123, v90 dst_sel:DWORD dst_unused:UNUSED_PAD src0_sel:WORD_1
	v_cvt_f32_f16_e32 v90, v91
	v_cvt_f32_f16_sdwa v91, v91 dst_sel:DWORD dst_unused:UNUSED_PAD src0_sel:WORD_1
	s_waitcnt vmcnt(1)
	v_cvt_f32_f16_e32 v124, v92
	v_cvt_f32_f16_sdwa v125, v92 dst_sel:DWORD dst_unused:UNUSED_PAD src0_sel:WORD_1
	v_cvt_f32_f16_e32 v92, v93
	v_cvt_f32_f16_sdwa v93, v93 dst_sel:DWORD dst_unused:UNUSED_PAD src0_sel:WORD_1
	s_waitcnt vmcnt(0)
	v_cvt_f32_f16_e32 v126, v94
	v_cvt_f32_f16_sdwa v127, v94 dst_sel:DWORD dst_unused:UNUSED_PAD src0_sel:WORD_1
	v_cvt_f32_f16_e32 v94, v95
	v_cvt_f32_f16_sdwa v95, v95 dst_sel:DWORD dst_unused:UNUSED_PAD src0_sel:WORD_1
	v_fma_f32 v46, v70, s14, v46
	v_fma_f32 v47, v71, s14, v47
	v_fma_f32 v44, v102, s14, v44
	v_fma_f32 v45, v103, s14, v45
	v_fma_f32 v62, v64, s14, v62
	v_fma_f32 v63, v65, s14, v63
	v_cvt_pk_f16_f32 v44, v44, v45
	v_cvt_pk_f16_f32 v45, v46, v47
	v_fma_f32 v60, v96, s14, v60
	v_fma_f32 v61, v97, s14, v61
	v_fma_f32 v58, v66, s14, v58
	v_fma_f32 v59, v67, s14, v59
	v_fma_f32 v56, v98, s14, v56
	v_fma_f32 v57, v99, s14, v57
	v_fma_f32 v54, v68, s14, v54
	v_fma_f32 v55, v69, s14, v55
	v_fma_f32 v52, v100, s14, v52
	v_fma_f32 v53, v101, s14, v53
	buffer_store_dwordx2 v[44:45], v140, s[8:11], 0 offen offset:288
	v_fma_f32 v44, v72, s14, v50
	v_fma_f32 v45, v73, s14, v51
	v_fma_f32 v46, v104, s14, v48
	v_fma_f32 v47, v105, s14, v49
	v_fma_f32 v42, v74, s14, v42
	v_fma_f32 v43, v75, s14, v43
	v_fma_f32 v40, v106, s14, v40
	v_fma_f32 v41, v107, s14, v41
	v_fma_f32 v38, v76, s14, v38
	v_fma_f32 v39, v77, s14, v39
	v_fma_f32 v36, v108, s14, v36
	v_fma_f32 v37, v109, s14, v37
	v_fma_f32 v30, v78, s14, v30
	v_fma_f32 v31, v79, s14, v31
	v_fma_f32 v28, v110, s14, v28
	v_fma_f32 v29, v111, s14, v29
	v_fma_f32 v14, v86, s14, v14
	v_fma_f32 v15, v87, s14, v15
	v_fma_f32 v12, v118, s14, v12
	v_fma_f32 v13, v119, s14, v13
	v_cvt_pk_f16_f32 v60, v60, v61
	v_cvt_pk_f16_f32 v61, v62, v63
	v_cvt_pk_f16_f32 v56, v56, v57
	v_cvt_pk_f16_f32 v57, v58, v59
	v_cvt_pk_f16_f32 v52, v52, v53
	v_cvt_pk_f16_f32 v53, v54, v55
	v_cvt_pk_f16_f32 v46, v46, v47
	v_cvt_pk_f16_f32 v47, v44, v45
	v_cvt_pk_f16_f32 v40, v40, v41
	v_cvt_pk_f16_f32 v41, v42, v43
	v_cvt_pk_f16_f32 v36, v36, v37
	v_cvt_pk_f16_f32 v37, v38, v39
	v_cvt_pk_f16_f32 v28, v28, v29
	v_cvt_pk_f16_f32 v29, v30, v31
	v_cvt_pk_f16_f32 v12, v12, v13
	v_cvt_pk_f16_f32 v13, v14, v15
	buffer_store_dwordx2 v[60:61], v140, s[8:11], 0 offen
	buffer_store_dwordx2 v[56:57], v140, s[8:11], 0 offen offset:32
	buffer_store_dwordx2 v[52:53], v140, s[8:11], 0 offen offset:256
	buffer_store_dwordx2 v[46:47], v141, s[8:11], 0 offen
	buffer_store_dwordx2 v[40:41], v141, s[8:11], 0 offen offset:32
	buffer_store_dwordx2 v[36:37], v141, s[8:11], 0 offen offset:256
	buffer_store_dwordx2 v[28:29], v141, s[8:11], 0 offen offset:288
	v_fma_f32 v28, v80, s14, v34
	v_fma_f32 v29, v81, s14, v35
	v_fma_f32 v30, v112, s14, v32
	v_fma_f32 v31, v113, s14, v33
	v_fma_f32 v26, v82, s14, v26
	v_fma_f32 v27, v83, s14, v27
	v_fma_f32 v24, v114, s14, v24
	v_fma_f32 v25, v115, s14, v25
	v_fma_f32 v22, v84, s14, v22
	v_fma_f32 v23, v85, s14, v23
	v_fma_f32 v20, v116, s14, v20
	v_fma_f32 v21, v117, s14, v21
	buffer_store_dwordx2 v[12:13], v142, s[8:11], 0 offen offset:288
	v_fma_f32 v12, v88, s14, v18
	v_fma_f32 v13, v89, s14, v19
	v_fma_f32 v14, v120, s14, v16
	v_fma_f32 v15, v121, s14, v17
	v_fma_f32 v10, v90, s14, v10
	v_fma_f32 v11, v91, s14, v11
	v_fma_f32 v8, v122, s14, v8
	v_fma_f32 v9, v123, s14, v9
	v_fma_f32 v6, v92, s14, v6
	v_fma_f32 v7, v93, s14, v7
	v_fma_f32 v4, v124, s14, v4
	v_fma_f32 v5, v125, s14, v5
	v_fma_f32 v2, v94, s14, v2
	v_fma_f32 v3, v95, s14, v3
	v_fma_f32 v0, v126, s14, v0
	v_fma_f32 v1, v127, s14, v1
	v_cvt_pk_f16_f32 v30, v30, v31
	v_cvt_pk_f16_f32 v31, v28, v29
	v_cvt_pk_f16_f32 v24, v24, v25
	v_cvt_pk_f16_f32 v25, v26, v27
	v_cvt_pk_f16_f32 v20, v20, v21
	v_cvt_pk_f16_f32 v21, v22, v23
	v_cvt_pk_f16_f32 v14, v14, v15
	v_cvt_pk_f16_f32 v15, v12, v13
	v_cvt_pk_f16_f32 v8, v8, v9
	v_cvt_pk_f16_f32 v9, v10, v11
	v_cvt_pk_f16_f32 v4, v4, v5
	v_cvt_pk_f16_f32 v5, v6, v7
	v_cvt_pk_f16_f32 v0, v0, v1
	v_cvt_pk_f16_f32 v1, v2, v3
	buffer_store_dwordx2 v[30:31], v142, s[8:11], 0 offen
	buffer_store_dwordx2 v[24:25], v142, s[8:11], 0 offen offset:32
	buffer_store_dwordx2 v[20:21], v142, s[8:11], 0 offen offset:256
	buffer_store_dwordx2 v[14:15], v143, s[8:11], 0 offen
	buffer_store_dwordx2 v[8:9], v143, s[8:11], 0 offen offset:32
	buffer_store_dwordx2 v[4:5], v143, s[8:11], 0 offen offset:256
	buffer_store_dwordx2 v[0:1], v143, s[8:11], 0 offen offset:288
	s_cbranch_vccnz .LBB0_781
	s_andn2_b64 vcc, exec, s[2:3]
	s_cbranch_vccnz .LBB0_780
	s_barrier
	s_branch .LBB0_780

; __device__ __forceinline__ unsigned cvt_pk_bf16(float lo, float hi) { unsigned r; asm volatile("v_cvt_pk_bf16_f32 %0, %1, %2" : "=v"(r) : "v"(lo), "v"(hi)); return r; }
;     __device__ __forceinline__ void operator()(const f32x4 (&acc)[2][2][4][2], const Unit& u, int wr, int wc, int fr, int fq) const {
;     ...
;             for (int m = 0; m < 4; ++m) { const int row = row0 + ai * HALF + m * 16;
;                 f32x4 c = {1.f, 1.f, 1.f, 1.f}, s = {0.f, 0.f, 0.f, 0.f};
;                 if (rope) { c = __builtin_bit_cast(f32x4, __builtin_amdgcn_raw_buffer_load_b128(cs, (row * 64 + f0) * 4, 0, 0)); s = __builtin_bit_cast(f32x4, __builtin_amdgcn_raw_buffer_load_b128(sn, (row * 64 + f0) * 4, 0, 0)); }
; #pragma unroll
;                 for (int bj = 0; bj < 2; ++bj) { f32x4 v0 = acc[ai][bj][m][0] * scl, v1 = acc[ai][bj][m][1] * scl;
;                     rope_pair(v0, v1, c, s);
;                     u32x4 w; w.x = cvt_pk_bf16(v0[0], v0[1]); w.y = cvt_pk_bf16(v0[2], v0[3]); w.z = cvt_pk_bf16(v1[0], v1[1]); w.w = cvt_pk_bf16(v1[2], v1[3]);
;                     if (pn < 16) __builtin_amdgcn_raw_buffer_store_b128(w, q, (row * 4096 + bj * HALF + cw) * 2, pn * 512, 0);
;                     else { const int kvh = ((pn - 16) & 3) * 2 + bj; const int off = ((((row >> 13) * 8 + kvh) * 8192 + (row & 8191)) * 128 + cw) * 2;
;                         if (pn < 20) __builtin_amdgcn_raw_buffer_store_b128(w, k, off, 0, 0); else __builtin_amdgcn_raw_buffer_store_b128(w, v, off, 0, 0); } } }
.LBB0_1206:
	v_ashrrev_i32_e32 v144, 1, v153
	v_and_b32_e32 v144, -8, v144
	v_add_u32_e32 v153, s67, v144
	s_cmp_gt_i32 s6, 15
	v_lshlrev_b32_e32 v144, 7, v154
	s_cselect_b64 s[30:31], -1, 0
	s_lshl_b32 s8, s6, 1
	s_lshr_b32 s7, s7, 10
	v_and_b32_e32 v144, 0xfe780, v144
	v_mul_f32_e32 v122, s38, v122
	v_mul_f32_e32 v123, s38, v123
	v_mul_f32_e32 v120, s38, v120
	v_mul_f32_e32 v121, s38, v121
	s_and_b32 s43, s8, 6
	s_and_b32 s7, s7, 0x7f8
	v_add_u32_e32 v156, v144, v153
	v_mul_f32_e32 v126, s38, v126
	v_mul_f32_e32 v127, s38, v127
	v_mul_f32_e32 v124, s38, v124
	v_mul_f32_e32 v125, s38, v125
	s_waitcnt vmcnt(0)
	v_mul_f32_e32 v144, v120, v128
	v_mul_f32_e32 v145, v121, v129
	v_mul_f32_e32 v146, v122, v130
	v_mul_f32_e32 v147, v123, v131
	v_mul_f32_e32 v120, v120, v132
	v_mul_f32_e32 v121, v121, v133
	v_mul_f32_e32 v122, v122, v134
	v_mul_f32_e32 v123, v123, v135
	s_or_b32 s50, s7, s43
	v_fma_f32 v146, v126, v134, -v146
	v_fma_f32 v147, v127, v135, -v147
	v_fma_f32 v126, v126, v130, v122
	v_fma_f32 v127, v127, v131, v123
	v_fma_f32 v122, v124, v128, v120
	v_fma_f32 v123, v125, v129, v121
	s_mov_b64 s[8:9], -1
	s_and_b64 vcc, exec, s[30:31]
	v_fma_f32 v144, v124, v132, -v144
	v_fma_f32 v145, v125, v133, -v145
	s_nop 0
	v_cvt_pk_bf16_f32 v120, v144, v145
	v_cvt_pk_bf16_f32 v121, v146, v147
	v_cvt_pk_bf16_f32 v122, v122, v123
	v_cvt_pk_bf16_f32 v123, v126, v127
	s_cbranch_vccz .LBB0_1212
	s_lshl_b32 s7, s50, 21
	v_lshl_add_u32 v124, v156, 1, s7
	s_and_b64 vcc, exec, s[10:11]
	s_cbranch_vccz .LBB0_1209
	s_mov_b32 s26, s22
	s_mov_b32 s27, s23
	buffer_store_dwordx4 v[120:123], v124, s[24:27], 0 offen
	s_mov_b64 s[8:9], 0

; __device__ __forceinline__ unsigned cvt_pk_bf16(float lo, float hi) { unsigned r; asm volatile("v_cvt_pk_bf16_f32 %0, %1, %2" : "=v"(r) : "v"(lo), "v"(hi)); return r; }
;     __device__ __forceinline__ void operator()(const f32x4 (&acc)[2][2][4][2], const Unit& u, int wr, int wc, int fr, int fq) const {
;     ...
;                 for (int bj = 0; bj < 2; ++bj) { f32x4 v0 = acc[ai][bj][m][0] * scl, v1 = acc[ai][bj][m][1] * scl;
;                     rope_pair(v0, v1, c, s);
;                     u32x4 w; w.x = cvt_pk_bf16(v0[0], v0[1]); w.y = cvt_pk_bf16(v0[2], v0[3]); w.z = cvt_pk_bf16(v1[0], v1[1]); w.w = cvt_pk_bf16(v1[2], v1[3]);
;                     if (pn < 16) __builtin_amdgcn_raw_buffer_store_b128(w, q, (row * 4096 + bj * HALF + cw) * 2, pn * 512, 0);
;                     else { const int kvh = ((pn - 16) & 3) * 2 + bj; const int off = ((((row >> 13) * 8 + kvh) * 8192 + (row & 8191)) * 128 + cw) * 2;
;                         if (pn < 20) __builtin_amdgcn_raw_buffer_store_b128(w, k, off, 0, 0); else __builtin_amdgcn_raw_buffer_store_b128(w, v, off, 0, 0); } } }
.LBB0_1214:
	v_mul_f32_e32 v114, s38, v114
	v_mul_f32_e32 v115, s38, v115
	v_mul_f32_e32 v112, s38, v112
	v_mul_f32_e32 v113, s38, v113
	v_mul_f32_e32 v118, s38, v118
	v_mul_f32_e32 v119, s38, v119
	v_mul_f32_e32 v116, s38, v116
	v_mul_f32_e32 v117, s38, v117
	v_mul_f32_e32 v120, v114, v130
	v_mul_f32_e32 v121, v115, v131
	v_mul_f32_e32 v122, v112, v128
	v_mul_f32_e32 v123, v113, v129
	v_mul_f32_e32 v114, v114, v134
	v_mul_f32_e32 v115, v115, v135
	v_mul_f32_e32 v112, v112, v132
	v_mul_f32_e32 v113, v113, v133
	v_fma_f32 v120, v118, v134, -v120
	v_fma_f32 v121, v119, v135, -v121
	v_fma_f32 v122, v116, v132, -v122
	v_fma_f32 v123, v117, v133, -v123
	v_fma_f32 v118, v118, v130, v114
	v_fma_f32 v119, v119, v131, v115
	v_fma_f32 v114, v116, v128, v112
	v_fma_f32 v115, v117, v129, v113
	v_cndmask_b32_e64 v116, 0, 1, s[30:31]
	v_cmp_ne_u32_e64 s[8:9], 1, v116
	v_cndmask_b32_e64 v116, 0, 1, s[10:11]
	s_mov_b64 s[26:27], -1
	s_andn2_b64 vcc, exec, s[30:31]
	v_cmp_ne_u32_e64 s[6:7], 1, v116
	v_cvt_pk_bf16_f32 v112, v122, v123
	v_cvt_pk_bf16_f32 v113, v120, v121
	v_cvt_pk_bf16_f32 v114, v114, v115
	v_cvt_pk_bf16_f32 v115, v118, v119
	s_cbranch_vccnz .LBB0_1220
	s_lshl_b32 s10, s50, 21
	v_lshl_add_u32 v116, v156, 1, s10
	v_add_u32_e32 v116, 0x200000, v116
	s_and_b64 vcc, exec, s[6:7]
	s_mov_b64 s[10:11], -1
	s_cbranch_vccnz .LBB0_1217
	s_mov_b32 s26, s22
	s_mov_b32 s27, s23
	s_mov_b64 s[10:11], 0
	buffer_store_dwordx4 v[112:115], v116, s[24:27], 0 offen

; __device__ __forceinline__ unsigned cvt_pk_bf16(float lo, float hi) { unsigned r; asm volatile("v_cvt_pk_bf16_f32 %0, %1, %2" : "=v"(r) : "v"(lo), "v"(hi)); return r; }
;     __device__ __forceinline__ void operator()(const f32x4 (&acc)[2][2][4][2], const Unit& u, int wr, int wc, int fr, int fq) const {
;     ...
;             for (int m = 0; m < 4; ++m) { const int row = row0 + ai * HALF + m * 16;
;                 f32x4 c = {1.f, 1.f, 1.f, 1.f}, s = {0.f, 0.f, 0.f, 0.f};
;                 if (rope) { c = __builtin_bit_cast(f32x4, __builtin_amdgcn_raw_buffer_load_b128(cs, (row * 64 + f0) * 4, 0, 0)); s = __builtin_bit_cast(f32x4, __builtin_amdgcn_raw_buffer_load_b128(sn, (row * 64 + f0) * 4, 0, 0)); }
; #pragma unroll
;                 for (int bj = 0; bj < 2; ++bj) { f32x4 v0 = acc[ai][bj][m][0] * scl, v1 = acc[ai][bj][m][1] * scl;
;                     rope_pair(v0, v1, c, s);
;                     u32x4 w; w.x = cvt_pk_bf16(v0[0], v0[1]); w.y = cvt_pk_bf16(v0[2], v0[3]); w.z = cvt_pk_bf16(v1[0], v1[1]); w.w = cvt_pk_bf16(v1[2], v1[3]);
;                     if (pn < 16) __builtin_amdgcn_raw_buffer_store_b128(w, q, (row * 4096 + bj * HALF + cw) * 2, pn * 512, 0);
;                     else { const int kvh = ((pn - 16) & 3) * 2 + bj; const int off = ((((row >> 13) * 8 + kvh) * 8192 + (row & 8191)) * 128 + cw) * 2;
;                         if (pn < 20) __builtin_amdgcn_raw_buffer_store_b128(w, k, off, 0, 0); else __builtin_amdgcn_raw_buffer_store_b128(w, v, off, 0, 0); } } }
.LBB0_1225:
	v_lshlrev_b32_e32 v121, 7, v120
	v_mul_f32_e32 v106, s38, v106
	v_mul_f32_e32 v107, s38, v107
	v_mul_f32_e32 v104, s38, v104
	v_mul_f32_e32 v105, s38, v105
	v_and_b32_e32 v121, 0xfef80, v121
	v_mul_f32_e32 v110, s38, v110
	v_mul_f32_e32 v111, s38, v111
	v_mul_f32_e32 v108, s38, v108
	v_mul_f32_e32 v109, s38, v109
	s_waitcnt vmcnt(0)
	v_mul_f32_e32 v122, v104, v112
	v_mul_f32_e32 v123, v105, v113
	v_mul_f32_e32 v124, v106, v114
	v_mul_f32_e32 v125, v107, v115
	v_mul_f32_e32 v104, v104, v116
	v_mul_f32_e32 v105, v105, v117
	v_mul_f32_e32 v106, v106, v118
	v_mul_f32_e32 v107, v107, v119
	v_add_u32_e32 v121, v121, v153
	v_fma_f32 v124, v110, v118, -v124
	v_fma_f32 v125, v111, v119, -v125
	v_fma_f32 v110, v110, v114, v106
	v_fma_f32 v111, v111, v115, v107
	v_fma_f32 v106, v108, v112, v104
	v_fma_f32 v107, v109, v113, v105
	s_and_b64 vcc, exec, s[8:9]
	s_mov_b64 s[26:27], -1
	v_fma_f32 v122, v108, v116, -v122
	v_fma_f32 v123, v109, v117, -v123
	s_nop 0
	v_cvt_pk_bf16_f32 v104, v122, v123
	v_cvt_pk_bf16_f32 v105, v124, v125
	v_cvt_pk_bf16_f32 v106, v106, v107
	v_cvt_pk_bf16_f32 v107, v110, v111
	s_cbranch_vccnz .LBB0_1231
	s_lshl_b32 s26, s50, 21
	v_lshl_add_u32 v108, v121, 1, s26
	s_and_b64 vcc, exec, s[6:7]
	s_mov_b64 s[26:27], -1
	s_cbranch_vccnz .LBB0_1228
	s_mov_b32 s26, s22
	s_mov_b32 s27, s23
	buffer_store_dwordx4 v[104:107], v108, s[24:27], 0 offen
	s_mov_b64 s[26:27], 0

; __device__ __forceinline__ unsigned cvt_pk_bf16(float lo, float hi) { unsigned r; asm volatile("v_cvt_pk_bf16_f32 %0, %1, %2" : "=v"(r) : "v"(lo), "v"(hi)); return r; }
;     __device__ __forceinline__ void operator()(const f32x4 (&acc)[2][2][4][2], const Unit& u, int wr, int wc, int fr, int fq) const {
;     ...
;                 for (int bj = 0; bj < 2; ++bj) { f32x4 v0 = acc[ai][bj][m][0] * scl, v1 = acc[ai][bj][m][1] * scl;
;                     rope_pair(v0, v1, c, s);
;                     u32x4 w; w.x = cvt_pk_bf16(v0[0], v0[1]); w.y = cvt_pk_bf16(v0[2], v0[3]); w.z = cvt_pk_bf16(v1[0], v1[1]); w.w = cvt_pk_bf16(v1[2], v1[3]);
;                     if (pn < 16) __builtin_amdgcn_raw_buffer_store_b128(w, q, (row * 4096 + bj * HALF + cw) * 2, pn * 512, 0);
;                     else { const int kvh = ((pn - 16) & 3) * 2 + bj; const int off = ((((row >> 13) * 8 + kvh) * 8192 + (row & 8191)) * 128 + cw) * 2;
;                         if (pn < 20) __builtin_amdgcn_raw_buffer_store_b128(w, k, off, 0, 0); else __builtin_amdgcn_raw_buffer_store_b128(w, v, off, 0, 0); } } }
.LBB0_1233:
	v_mul_f32_e32 v98, s38, v98
	v_mul_f32_e32 v99, s38, v99
	v_mul_f32_e32 v96, s38, v96
	v_mul_f32_e32 v97, s38, v97
	v_mul_f32_e32 v102, s38, v102
	v_mul_f32_e32 v103, s38, v103
	v_mul_f32_e32 v100, s38, v100
	v_mul_f32_e32 v101, s38, v101
	v_mul_f32_e32 v104, v98, v114
	v_mul_f32_e32 v105, v99, v115
	v_mul_f32_e32 v106, v96, v112
	v_mul_f32_e32 v107, v97, v113
	v_mul_f32_e32 v98, v98, v118
	v_mul_f32_e32 v99, v99, v119
	v_mul_f32_e32 v96, v96, v116
	v_mul_f32_e32 v97, v97, v117
	v_fma_f32 v104, v102, v118, -v104
	v_fma_f32 v105, v103, v119, -v105
	v_fma_f32 v102, v102, v114, v98
	v_fma_f32 v103, v103, v115, v99
	v_fma_f32 v98, v100, v112, v96
	v_fma_f32 v99, v101, v113, v97
	s_and_b64 vcc, exec, s[8:9]
	s_mov_b64 s[26:27], -1
	v_fma_f32 v106, v100, v116, -v106
	v_fma_f32 v107, v101, v117, -v107
	s_nop 0
	v_cvt_pk_bf16_f32 v96, v106, v107
	v_cvt_pk_bf16_f32 v97, v104, v105
	v_cvt_pk_bf16_f32 v98, v98, v99
	v_cvt_pk_bf16_f32 v99, v102, v103
	s_cbranch_vccz .LBB0_1237
	s_andn2_b64 vcc, exec, s[26:27]
	s_cbranch_vccz .LBB0_1242

; __device__ __forceinline__ unsigned cvt_pk_bf16(float lo, float hi) { unsigned r; asm volatile("v_cvt_pk_bf16_f32 %0, %1, %2" : "=v"(r) : "v"(lo), "v"(hi)); return r; }
;     __device__ __forceinline__ void operator()(const f32x4 (&acc)[2][2][4][2], const Unit& u, int wr, int wc, int fr, int fq) const {
;     ...
;             for (int m = 0; m < 4; ++m) { const int row = row0 + ai * HALF + m * 16;
;                 f32x4 c = {1.f, 1.f, 1.f, 1.f}, s = {0.f, 0.f, 0.f, 0.f};
;                 if (rope) { c = __builtin_bit_cast(f32x4, __builtin_amdgcn_raw_buffer_load_b128(cs, (row * 64 + f0) * 4, 0, 0)); s = __builtin_bit_cast(f32x4, __builtin_amdgcn_raw_buffer_load_b128(sn, (row * 64 + f0) * 4, 0, 0)); }
; #pragma unroll
;                 for (int bj = 0; bj < 2; ++bj) { f32x4 v0 = acc[ai][bj][m][0] * scl, v1 = acc[ai][bj][m][1] * scl;
;                     rope_pair(v0, v1, c, s);
;                     u32x4 w; w.x = cvt_pk_bf16(v0[0], v0[1]); w.y = cvt_pk_bf16(v0[2], v0[3]); w.z = cvt_pk_bf16(v1[0], v1[1]); w.w = cvt_pk_bf16(v1[2], v1[3]);
;                     if (pn < 16) __builtin_amdgcn_raw_buffer_store_b128(w, q, (row * 4096 + bj * HALF + cw) * 2, pn * 512, 0);
;                     else { const int kvh = ((pn - 16) & 3) * 2 + bj; const int off = ((((row >> 13) * 8 + kvh) * 8192 + (row & 8191)) * 128 + cw) * 2;
;                         if (pn < 20) __builtin_amdgcn_raw_buffer_store_b128(w, k, off, 0, 0); else __builtin_amdgcn_raw_buffer_store_b128(w, v, off, 0, 0); } } }
.LBB0_1244:
	v_lshlrev_b32_e32 v105, 7, v104
	v_mul_f32_e32 v90, s38, v90
	v_mul_f32_e32 v91, s38, v91
	v_mul_f32_e32 v88, s38, v88
	v_mul_f32_e32 v89, s38, v89
	v_and_b32_e32 v105, 0xff780, v105
	v_mul_f32_e32 v94, s38, v94
	v_mul_f32_e32 v95, s38, v95
	v_mul_f32_e32 v92, s38, v92
	v_mul_f32_e32 v93, s38, v93
	s_waitcnt vmcnt(0)
	v_mul_f32_e32 v106, v88, v96
	v_mul_f32_e32 v107, v89, v97
	v_mul_f32_e32 v110, v90, v98
	v_mul_f32_e32 v111, v91, v99
	v_mul_f32_e32 v88, v88, v100
	v_mul_f32_e32 v89, v89, v101
	v_mul_f32_e32 v90, v90, v102
	v_mul_f32_e32 v91, v91, v103
	v_add_u32_e32 v105, v105, v153
	v_fma_f32 v110, v94, v102, -v110
	v_fma_f32 v111, v95, v103, -v111
	v_fma_f32 v94, v94, v98, v90
	v_fma_f32 v95, v95, v99, v91
	v_fma_f32 v90, v92, v96, v88
	v_fma_f32 v91, v93, v97, v89
	s_and_b64 vcc, exec, s[8:9]
	s_mov_b64 s[26:27], -1
	v_fma_f32 v106, v92, v100, -v106
	v_fma_f32 v107, v93, v101, -v107
	s_nop 0
	v_cvt_pk_bf16_f32 v88, v106, v107
	v_cvt_pk_bf16_f32 v89, v110, v111
	v_cvt_pk_bf16_f32 v90, v90, v91
	v_cvt_pk_bf16_f32 v91, v94, v95
	s_cbranch_vccnz .LBB0_1250
	s_lshl_b32 s26, s50, 21
	v_lshl_add_u32 v92, v105, 1, s26
	s_and_b64 vcc, exec, s[6:7]
	s_mov_b64 s[26:27], -1
	s_cbranch_vccnz .LBB0_1247
	s_mov_b32 s26, s22
	s_mov_b32 s27, s23
	buffer_store_dwordx4 v[88:91], v92, s[24:27], 0 offen
	s_mov_b64 s[26:27], 0

; __device__ __forceinline__ unsigned cvt_pk_bf16(float lo, float hi) { unsigned r; asm volatile("v_cvt_pk_bf16_f32 %0, %1, %2" : "=v"(r) : "v"(lo), "v"(hi)); return r; }
;     __device__ __forceinline__ void operator()(const f32x4 (&acc)[2][2][4][2], const Unit& u, int wr, int wc, int fr, int fq) const {
;     ...
;                 for (int bj = 0; bj < 2; ++bj) { f32x4 v0 = acc[ai][bj][m][0] * scl, v1 = acc[ai][bj][m][1] * scl;
;                     rope_pair(v0, v1, c, s);
;                     u32x4 w; w.x = cvt_pk_bf16(v0[0], v0[1]); w.y = cvt_pk_bf16(v0[2], v0[3]); w.z = cvt_pk_bf16(v1[0], v1[1]); w.w = cvt_pk_bf16(v1[2], v1[3]);
;                     if (pn < 16) __builtin_amdgcn_raw_buffer_store_b128(w, q, (row * 4096 + bj * HALF + cw) * 2, pn * 512, 0);
;                     else { const int kvh = ((pn - 16) & 3) * 2 + bj; const int off = ((((row >> 13) * 8 + kvh) * 8192 + (row & 8191)) * 128 + cw) * 2;
;                         if (pn < 20) __builtin_amdgcn_raw_buffer_store_b128(w, k, off, 0, 0); else __builtin_amdgcn_raw_buffer_store_b128(w, v, off, 0, 0); } } }
.LBB0_1252:
	v_mul_f32_e32 v82, s38, v82
	v_mul_f32_e32 v83, s38, v83
	v_mul_f32_e32 v80, s38, v80
	v_mul_f32_e32 v81, s38, v81
	v_mul_f32_e32 v86, s38, v86
	v_mul_f32_e32 v87, s38, v87
	v_mul_f32_e32 v84, s38, v84
	v_mul_f32_e32 v85, s38, v85
	v_mul_f32_e32 v88, v82, v98
	v_mul_f32_e32 v89, v83, v99
	v_mul_f32_e32 v90, v80, v96
	v_mul_f32_e32 v91, v81, v97
	v_mul_f32_e32 v82, v82, v102
	v_mul_f32_e32 v83, v83, v103
	v_mul_f32_e32 v80, v80, v100
	v_mul_f32_e32 v81, v81, v101
	v_fma_f32 v88, v86, v102, -v88
	v_fma_f32 v89, v87, v103, -v89
	v_fma_f32 v86, v86, v98, v82
	v_fma_f32 v87, v87, v99, v83
	v_fma_f32 v82, v84, v96, v80
	v_fma_f32 v83, v85, v97, v81
	s_and_b64 vcc, exec, s[8:9]
	s_mov_b64 s[26:27], -1
	v_fma_f32 v90, v84, v100, -v90
	v_fma_f32 v91, v85, v101, -v91
	s_nop 0
	v_cvt_pk_bf16_f32 v80, v90, v91
	v_cvt_pk_bf16_f32 v81, v88, v89
	v_cvt_pk_bf16_f32 v82, v82, v83
	v_cvt_pk_bf16_f32 v83, v86, v87
	s_cbranch_vccz .LBB0_1256
	s_andn2_b64 vcc, exec, s[26:27]
	s_cbranch_vccz .LBB0_1261

; __device__ __forceinline__ unsigned cvt_pk_bf16(float lo, float hi) { unsigned r; asm volatile("v_cvt_pk_bf16_f32 %0, %1, %2" : "=v"(r) : "v"(lo), "v"(hi)); return r; }
;     __device__ __forceinline__ void operator()(const f32x4 (&acc)[2][2][4][2], const Unit& u, int wr, int wc, int fr, int fq) const {
;     ...
;             for (int m = 0; m < 4; ++m) { const int row = row0 + ai * HALF + m * 16;
;                 f32x4 c = {1.f, 1.f, 1.f, 1.f}, s = {0.f, 0.f, 0.f, 0.f};
;                 if (rope) { c = __builtin_bit_cast(f32x4, __builtin_amdgcn_raw_buffer_load_b128(cs, (row * 64 + f0) * 4, 0, 0)); s = __builtin_bit_cast(f32x4, __builtin_amdgcn_raw_buffer_load_b128(sn, (row * 64 + f0) * 4, 0, 0)); }
; #pragma unroll
;                 for (int bj = 0; bj < 2; ++bj) { f32x4 v0 = acc[ai][bj][m][0] * scl, v1 = acc[ai][bj][m][1] * scl;
;                     rope_pair(v0, v1, c, s);
;                     u32x4 w; w.x = cvt_pk_bf16(v0[0], v0[1]); w.y = cvt_pk_bf16(v0[2], v0[3]); w.z = cvt_pk_bf16(v1[0], v1[1]); w.w = cvt_pk_bf16(v1[2], v1[3]);
;                     if (pn < 16) __builtin_amdgcn_raw_buffer_store_b128(w, q, (row * 4096 + bj * HALF + cw) * 2, pn * 512, 0);
;                     else { const int kvh = ((pn - 16) & 3) * 2 + bj; const int off = ((((row >> 13) * 8 + kvh) * 8192 + (row & 8191)) * 128 + cw) * 2;
;                         if (pn < 20) __builtin_amdgcn_raw_buffer_store_b128(w, k, off, 0, 0); else __builtin_amdgcn_raw_buffer_store_b128(w, v, off, 0, 0); } } }
.LBB0_1263:
	v_lshlrev_b32_e32 v89, 7, v88
	v_mul_f32_e32 v74, s38, v74
	v_mul_f32_e32 v75, s38, v75
	v_mul_f32_e32 v72, s38, v72
	v_mul_f32_e32 v73, s38, v73
	v_and_b32_e32 v89, 0xfff80, v89
	v_mul_f32_e32 v78, s38, v78
	v_mul_f32_e32 v79, s38, v79
	v_mul_f32_e32 v76, s38, v76
	v_mul_f32_e32 v77, s38, v77
	s_waitcnt vmcnt(0)
	v_mul_f32_e32 v90, v72, v80
	v_mul_f32_e32 v91, v73, v81
	v_mul_f32_e32 v92, v74, v82
	v_mul_f32_e32 v93, v75, v83
	v_mul_f32_e32 v72, v72, v84
	v_mul_f32_e32 v73, v73, v85
	v_mul_f32_e32 v74, v74, v86
	v_mul_f32_e32 v75, v75, v87
	v_add_u32_e32 v89, v89, v153
	v_fma_f32 v92, v78, v86, -v92
	v_fma_f32 v93, v79, v87, -v93
	v_fma_f32 v78, v78, v82, v74
	v_fma_f32 v79, v79, v83, v75
	v_fma_f32 v74, v76, v80, v72
	v_fma_f32 v75, v77, v81, v73
	s_and_b64 vcc, exec, s[8:9]
	s_mov_b64 s[26:27], -1
	v_fma_f32 v90, v76, v84, -v90
	v_fma_f32 v91, v77, v85, -v91
	s_nop 0
	v_cvt_pk_bf16_f32 v72, v90, v91
	v_cvt_pk_bf16_f32 v73, v92, v93
	v_cvt_pk_bf16_f32 v74, v74, v75
	v_cvt_pk_bf16_f32 v75, v78, v79
	s_cbranch_vccnz .LBB0_1269
	s_lshl_b32 s26, s50, 21
	v_lshl_add_u32 v76, v89, 1, s26
	s_and_b64 vcc, exec, s[6:7]
	s_mov_b64 s[26:27], -1
	s_cbranch_vccnz .LBB0_1266
	s_mov_b32 s26, s22
	s_mov_b32 s27, s23
	buffer_store_dwordx4 v[72:75], v76, s[24:27], 0 offen
	s_mov_b64 s[26:27], 0

; __device__ __forceinline__ unsigned cvt_pk_bf16(float lo, float hi) { unsigned r; asm volatile("v_cvt_pk_bf16_f32 %0, %1, %2" : "=v"(r) : "v"(lo), "v"(hi)); return r; }
;     __device__ __forceinline__ void operator()(const f32x4 (&acc)[2][2][4][2], const Unit& u, int wr, int wc, int fr, int fq) const {
;     ...
;                 for (int bj = 0; bj < 2; ++bj) { f32x4 v0 = acc[ai][bj][m][0] * scl, v1 = acc[ai][bj][m][1] * scl;
;                     rope_pair(v0, v1, c, s);
;                     u32x4 w; w.x = cvt_pk_bf16(v0[0], v0[1]); w.y = cvt_pk_bf16(v0[2], v0[3]); w.z = cvt_pk_bf16(v1[0], v1[1]); w.w = cvt_pk_bf16(v1[2], v1[3]);
;                     if (pn < 16) __builtin_amdgcn_raw_buffer_store_b128(w, q, (row * 4096 + bj * HALF + cw) * 2, pn * 512, 0);
;                     else { const int kvh = ((pn - 16) & 3) * 2 + bj; const int off = ((((row >> 13) * 8 + kvh) * 8192 + (row & 8191)) * 128 + cw) * 2;
;                         if (pn < 20) __builtin_amdgcn_raw_buffer_store_b128(w, k, off, 0, 0); else __builtin_amdgcn_raw_buffer_store_b128(w, v, off, 0, 0); } } }
.LBB0_1271:
	v_mul_f32_e32 v66, s38, v66
	v_mul_f32_e32 v67, s38, v67
	v_mul_f32_e32 v64, s38, v64
	v_mul_f32_e32 v65, s38, v65
	v_mul_f32_e32 v70, s38, v70
	v_mul_f32_e32 v71, s38, v71
	v_mul_f32_e32 v68, s38, v68
	v_mul_f32_e32 v69, s38, v69
	v_mul_f32_e32 v72, v66, v82
	v_mul_f32_e32 v73, v67, v83
	v_mul_f32_e32 v74, v64, v80
	v_mul_f32_e32 v75, v65, v81
	v_mul_f32_e32 v66, v66, v86
	v_mul_f32_e32 v67, v67, v87
	v_mul_f32_e32 v64, v64, v84
	v_mul_f32_e32 v65, v65, v85
	v_fma_f32 v72, v70, v86, -v72
	v_fma_f32 v73, v71, v87, -v73
	v_fma_f32 v70, v70, v82, v66
	v_fma_f32 v71, v71, v83, v67
	v_fma_f32 v66, v68, v80, v64
	v_fma_f32 v67, v69, v81, v65
	s_and_b64 vcc, exec, s[8:9]
	s_mov_b64 s[26:27], -1
	v_fma_f32 v74, v68, v84, -v74
	v_fma_f32 v75, v69, v85, -v75
	s_nop 0
	v_cvt_pk_bf16_f32 v64, v74, v75
	v_cvt_pk_bf16_f32 v65, v72, v73
	v_cvt_pk_bf16_f32 v66, v66, v67
	v_cvt_pk_bf16_f32 v67, v70, v71
	s_cbranch_vccz .LBB0_1275
	s_andn2_b64 vcc, exec, s[26:27]
	s_cbranch_vccz .LBB0_1280

; __device__ __forceinline__ unsigned cvt_pk_bf16(float lo, float hi) { unsigned r; asm volatile("v_cvt_pk_bf16_f32 %0, %1, %2" : "=v"(r) : "v"(lo), "v"(hi)); return r; }
;     __device__ __forceinline__ void operator()(const f32x4 (&acc)[2][2][4][2], const Unit& u, int wr, int wc, int fr, int fq) const {
;     ...
;             for (int m = 0; m < 4; ++m) { const int row = row0 + ai * HALF + m * 16;
;                 f32x4 c = {1.f, 1.f, 1.f, 1.f}, s = {0.f, 0.f, 0.f, 0.f};
;                 if (rope) { c = __builtin_bit_cast(f32x4, __builtin_amdgcn_raw_buffer_load_b128(cs, (row * 64 + f0) * 4, 0, 0)); s = __builtin_bit_cast(f32x4, __builtin_amdgcn_raw_buffer_load_b128(sn, (row * 64 + f0) * 4, 0, 0)); }
; #pragma unroll
;                 for (int bj = 0; bj < 2; ++bj) { f32x4 v0 = acc[ai][bj][m][0] * scl, v1 = acc[ai][bj][m][1] * scl;
;                     rope_pair(v0, v1, c, s);
;                     u32x4 w; w.x = cvt_pk_bf16(v0[0], v0[1]); w.y = cvt_pk_bf16(v0[2], v0[3]); w.z = cvt_pk_bf16(v1[0], v1[1]); w.w = cvt_pk_bf16(v1[2], v1[3]);
;                     if (pn < 16) __builtin_amdgcn_raw_buffer_store_b128(w, q, (row * 4096 + bj * HALF + cw) * 2, pn * 512, 0);
;                     else { const int kvh = ((pn - 16) & 3) * 2 + bj; const int off = ((((row >> 13) * 8 + kvh) * 8192 + (row & 8191)) * 128 + cw) * 2;
;                         if (pn < 20) __builtin_amdgcn_raw_buffer_store_b128(w, k, off, 0, 0); else __builtin_amdgcn_raw_buffer_store_b128(w, v, off, 0, 0); } } }
.LBB0_1282:
	v_lshlrev_b32_e32 v74, 7, v73
	v_lshrrev_b32_e32 v72, 10, v73
	v_and_b32_e32 v74, 0xfe780, v74
	v_mul_f32_e32 v58, s38, v58
	v_mul_f32_e32 v59, s38, v59
	v_mul_f32_e32 v56, s38, v56
	v_mul_f32_e32 v57, s38, v57
	v_and_b32_e32 v72, 0x7f8, v72
	v_add_u32_e32 v78, v74, v153
	v_mul_f32_e32 v62, s38, v62
	v_mul_f32_e32 v63, s38, v63
	v_mul_f32_e32 v60, s38, v60
	v_mul_f32_e32 v61, s38, v61
	s_waitcnt vmcnt(0)
	v_mul_f32_e32 v74, v56, v64
	v_mul_f32_e32 v75, v57, v65
	v_mul_f32_e32 v76, v58, v66
	v_mul_f32_e32 v77, v59, v67
	v_mul_f32_e32 v56, v56, v68
	v_mul_f32_e32 v57, v57, v69
	v_mul_f32_e32 v58, v58, v70
	v_mul_f32_e32 v59, v59, v71
	v_or_b32_e32 v72, s43, v72
	v_fma_f32 v76, v62, v70, -v76
	v_fma_f32 v77, v63, v71, -v77
	v_fma_f32 v74, v60, v68, -v74
	v_fma_f32 v75, v61, v69, -v75
	v_fma_f32 v62, v62, v66, v58
	v_fma_f32 v63, v63, v67, v59
	v_fma_f32 v58, v60, v64, v56
	v_fma_f32 v59, v61, v65, v57
	s_mov_b64 s[26:27], -1
	s_and_b64 vcc, exec, s[8:9]
	v_lshlrev_b32_e32 v60, 1, v78
	v_cvt_pk_bf16_f32 v56, v74, v75
	v_cvt_pk_bf16_f32 v57, v76, v77
	v_cvt_pk_bf16_f32 v58, v58, v59
	v_cvt_pk_bf16_f32 v59, v62, v63
	s_cbranch_vccnz .LBB0_1288
	v_lshl_add_u32 v61, v72, 21, v60
	s_and_b64 vcc, exec, s[6:7]
	s_cbranch_vccnz .LBB0_1285
	s_mov_b32 s26, s22
	s_mov_b32 s27, s23
	buffer_store_dwordx4 v[56:59], v61, s[24:27], 0 offen
	s_mov_b64 s[26:27], 0

; __device__ __forceinline__ unsigned cvt_pk_bf16(float lo, float hi) { unsigned r; asm volatile("v_cvt_pk_bf16_f32 %0, %1, %2" : "=v"(r) : "v"(lo), "v"(hi)); return r; }
;     __device__ __forceinline__ void operator()(const f32x4 (&acc)[2][2][4][2], const Unit& u, int wr, int wc, int fr, int fq) const {
;     ...
;                 for (int bj = 0; bj < 2; ++bj) { f32x4 v0 = acc[ai][bj][m][0] * scl, v1 = acc[ai][bj][m][1] * scl;
;                     rope_pair(v0, v1, c, s);
;                     u32x4 w; w.x = cvt_pk_bf16(v0[0], v0[1]); w.y = cvt_pk_bf16(v0[2], v0[3]); w.z = cvt_pk_bf16(v1[0], v1[1]); w.w = cvt_pk_bf16(v1[2], v1[3]);
;                     if (pn < 16) __builtin_amdgcn_raw_buffer_store_b128(w, q, (row * 4096 + bj * HALF + cw) * 2, pn * 512, 0);
;                     else { const int kvh = ((pn - 16) & 3) * 2 + bj; const int off = ((((row >> 13) * 8 + kvh) * 8192 + (row & 8191)) * 128 + cw) * 2;
;                         if (pn < 20) __builtin_amdgcn_raw_buffer_store_b128(w, k, off, 0, 0); else __builtin_amdgcn_raw_buffer_store_b128(w, v, off, 0, 0); } } }
.LBB0_1290:
	v_mul_f32_e32 v50, s38, v50
	v_mul_f32_e32 v51, s38, v51
	v_mul_f32_e32 v54, s38, v54
	v_mul_f32_e32 v55, s38, v55
	v_mul_f32_e32 v48, s38, v48
	v_mul_f32_e32 v49, s38, v49
	v_mul_f32_e32 v56, v50, v66
	v_mul_f32_e32 v57, v51, v67
	v_mul_f32_e32 v52, s38, v52
	v_mul_f32_e32 v53, s38, v53
	v_mul_f32_e32 v58, v48, v64
	v_mul_f32_e32 v59, v49, v65
	v_fma_f32 v56, v54, v70, -v56
	v_fma_f32 v57, v55, v71, -v57
	v_mul_f32_e32 v50, v50, v70
	v_mul_f32_e32 v51, v51, v71
	v_mul_f32_e32 v48, v48, v68
	v_mul_f32_e32 v49, v49, v69
	v_fma_f32 v58, v52, v68, -v58
	v_fma_f32 v59, v53, v69, -v59
	v_fma_f32 v54, v54, v66, v50
	v_fma_f32 v55, v55, v67, v51
	v_fma_f32 v50, v52, v64, v48
	v_fma_f32 v51, v53, v65, v49
	v_cvt_pk_bf16_f32 v48, v58, v59
	v_cvt_pk_bf16_f32 v49, v56, v57
	s_mov_b64 s[26:27], -1
	s_and_b64 vcc, exec, s[8:9]
	v_lshlrev_b32_e32 v56, 21, v72
	v_cvt_pk_bf16_f32 v50, v50, v51
	v_cvt_pk_bf16_f32 v51, v54, v55
	s_cbranch_vccz .LBB0_1294
	s_andn2_b64 vcc, exec, s[26:27]
	s_cbranch_vccz .LBB0_1299

; __device__ __forceinline__ unsigned cvt_pk_bf16(float lo, float hi) { unsigned r; asm volatile("v_cvt_pk_bf16_f32 %0, %1, %2" : "=v"(r) : "v"(lo), "v"(hi)); return r; }
;     __device__ __forceinline__ void operator()(const f32x4 (&acc)[2][2][4][2], const Unit& u, int wr, int wc, int fr, int fq) const {
;     ...
;             for (int m = 0; m < 4; ++m) { const int row = row0 + ai * HALF + m * 16;
;                 f32x4 c = {1.f, 1.f, 1.f, 1.f}, s = {0.f, 0.f, 0.f, 0.f};
;                 if (rope) { c = __builtin_bit_cast(f32x4, __builtin_amdgcn_raw_buffer_load_b128(cs, (row * 64 + f0) * 4, 0, 0)); s = __builtin_bit_cast(f32x4, __builtin_amdgcn_raw_buffer_load_b128(sn, (row * 64 + f0) * 4, 0, 0)); }
; #pragma unroll
;                 for (int bj = 0; bj < 2; ++bj) { f32x4 v0 = acc[ai][bj][m][0] * scl, v1 = acc[ai][bj][m][1] * scl;
;                     rope_pair(v0, v1, c, s);
;                     u32x4 w; w.x = cvt_pk_bf16(v0[0], v0[1]); w.y = cvt_pk_bf16(v0[2], v0[3]); w.z = cvt_pk_bf16(v1[0], v1[1]); w.w = cvt_pk_bf16(v1[2], v1[3]);
;                     if (pn < 16) __builtin_amdgcn_raw_buffer_store_b128(w, q, (row * 4096 + bj * HALF + cw) * 2, pn * 512, 0);
;                     else { const int kvh = ((pn - 16) & 3) * 2 + bj; const int off = ((((row >> 13) * 8 + kvh) * 8192 + (row & 8191)) * 128 + cw) * 2;
;                         if (pn < 20) __builtin_amdgcn_raw_buffer_store_b128(w, k, off, 0, 0); else __builtin_amdgcn_raw_buffer_store_b128(w, v, off, 0, 0); } } }
.LBB0_1301:
	v_lshlrev_b32_e32 v58, 7, v57
	v_and_b32_e32 v58, 0xfef80, v58
	v_mul_f32_e32 v42, s38, v42
	v_mul_f32_e32 v43, s38, v43
	v_mul_f32_e32 v40, s38, v40
	v_mul_f32_e32 v41, s38, v41
	v_add_u32_e32 v62, v58, v153
	v_mul_f32_e32 v46, s38, v46
	v_mul_f32_e32 v47, s38, v47
	v_mul_f32_e32 v44, s38, v44
	v_mul_f32_e32 v45, s38, v45
	s_waitcnt vmcnt(0)
	v_mul_f32_e32 v58, v40, v48
	v_mul_f32_e32 v59, v41, v49
	v_mul_f32_e32 v60, v42, v50
	v_mul_f32_e32 v61, v43, v51
	v_mul_f32_e32 v40, v40, v52
	v_mul_f32_e32 v41, v41, v53
	v_mul_f32_e32 v42, v42, v54
	v_mul_f32_e32 v43, v43, v55
	v_fma_f32 v60, v46, v54, -v60
	v_fma_f32 v61, v47, v55, -v61
	v_fma_f32 v58, v44, v52, -v58
	v_fma_f32 v59, v45, v53, -v59
	v_fma_f32 v46, v46, v50, v42
	v_fma_f32 v47, v47, v51, v43
	v_fma_f32 v42, v44, v48, v40
	v_fma_f32 v43, v45, v49, v41
	s_mov_b64 s[26:27], -1
	s_and_b64 vcc, exec, s[8:9]
	v_lshlrev_b32_e32 v44, 1, v62
	v_cvt_pk_bf16_f32 v40, v58, v59
	v_cvt_pk_bf16_f32 v41, v60, v61
	v_cvt_pk_bf16_f32 v42, v42, v43
	v_cvt_pk_bf16_f32 v43, v46, v47
	s_cbranch_vccnz .LBB0_1307
	v_lshl_add_u32 v45, v72, 21, v44
	s_and_b64 vcc, exec, s[6:7]
	s_cbranch_vccnz .LBB0_1304
	s_mov_b32 s26, s22
	s_mov_b32 s27, s23
	buffer_store_dwordx4 v[40:43], v45, s[24:27], 0 offen
	s_mov_b64 s[26:27], 0

; __device__ __forceinline__ unsigned cvt_pk_bf16(float lo, float hi) { unsigned r; asm volatile("v_cvt_pk_bf16_f32 %0, %1, %2" : "=v"(r) : "v"(lo), "v"(hi)); return r; }
;     __device__ __forceinline__ void operator()(const f32x4 (&acc)[2][2][4][2], const Unit& u, int wr, int wc, int fr, int fq) const {
;     ...
;                 for (int bj = 0; bj < 2; ++bj) { f32x4 v0 = acc[ai][bj][m][0] * scl, v1 = acc[ai][bj][m][1] * scl;
;                     rope_pair(v0, v1, c, s);
;                     u32x4 w; w.x = cvt_pk_bf16(v0[0], v0[1]); w.y = cvt_pk_bf16(v0[2], v0[3]); w.z = cvt_pk_bf16(v1[0], v1[1]); w.w = cvt_pk_bf16(v1[2], v1[3]);
;                     if (pn < 16) __builtin_amdgcn_raw_buffer_store_b128(w, q, (row * 4096 + bj * HALF + cw) * 2, pn * 512, 0);
;                     else { const int kvh = ((pn - 16) & 3) * 2 + bj; const int off = ((((row >> 13) * 8 + kvh) * 8192 + (row & 8191)) * 128 + cw) * 2;
;                         if (pn < 20) __builtin_amdgcn_raw_buffer_store_b128(w, k, off, 0, 0); else __builtin_amdgcn_raw_buffer_store_b128(w, v, off, 0, 0); } } }
.LBB0_1309:
	v_mul_f32_e32 v34, s38, v34
	v_mul_f32_e32 v35, s38, v35
	v_mul_f32_e32 v32, s38, v32
	v_mul_f32_e32 v33, s38, v33
	v_mul_f32_e32 v38, s38, v38
	v_mul_f32_e32 v39, s38, v39
	v_mul_f32_e32 v36, s38, v36
	v_mul_f32_e32 v37, s38, v37
	v_mul_f32_e32 v40, v34, v50
	v_mul_f32_e32 v41, v35, v51
	v_mul_f32_e32 v42, v32, v48
	v_mul_f32_e32 v43, v33, v49
	v_mul_f32_e32 v34, v34, v54
	v_mul_f32_e32 v35, v35, v55
	v_mul_f32_e32 v32, v32, v52
	v_mul_f32_e32 v33, v33, v53
	v_fma_f32 v40, v38, v54, -v40
	v_fma_f32 v41, v39, v55, -v41
	v_fma_f32 v38, v38, v50, v34
	v_fma_f32 v39, v39, v51, v35
	v_fma_f32 v34, v36, v48, v32
	v_fma_f32 v35, v37, v49, v33
	s_and_b64 vcc, exec, s[8:9]
	s_mov_b64 s[26:27], -1
	v_fma_f32 v42, v36, v52, -v42
	v_fma_f32 v43, v37, v53, -v43
	s_nop 0
	v_cvt_pk_bf16_f32 v32, v42, v43
	v_cvt_pk_bf16_f32 v33, v40, v41
	v_cvt_pk_bf16_f32 v34, v34, v35
	v_cvt_pk_bf16_f32 v35, v38, v39
	s_cbranch_vccz .LBB0_1313
	s_andn2_b64 vcc, exec, s[26:27]
	s_cbranch_vccz .LBB0_1318

; __device__ __forceinline__ unsigned cvt_pk_bf16(float lo, float hi) { unsigned r; asm volatile("v_cvt_pk_bf16_f32 %0, %1, %2" : "=v"(r) : "v"(lo), "v"(hi)); return r; }
;     __device__ __forceinline__ void operator()(const f32x4 (&acc)[2][2][4][2], const Unit& u, int wr, int wc, int fr, int fq) const {
;     ...
;             for (int m = 0; m < 4; ++m) { const int row = row0 + ai * HALF + m * 16;
;                 f32x4 c = {1.f, 1.f, 1.f, 1.f}, s = {0.f, 0.f, 0.f, 0.f};
;                 if (rope) { c = __builtin_bit_cast(f32x4, __builtin_amdgcn_raw_buffer_load_b128(cs, (row * 64 + f0) * 4, 0, 0)); s = __builtin_bit_cast(f32x4, __builtin_amdgcn_raw_buffer_load_b128(sn, (row * 64 + f0) * 4, 0, 0)); }
; #pragma unroll
;                 for (int bj = 0; bj < 2; ++bj) { f32x4 v0 = acc[ai][bj][m][0] * scl, v1 = acc[ai][bj][m][1] * scl;
;                     rope_pair(v0, v1, c, s);
;                     u32x4 w; w.x = cvt_pk_bf16(v0[0], v0[1]); w.y = cvt_pk_bf16(v0[2], v0[3]); w.z = cvt_pk_bf16(v1[0], v1[1]); w.w = cvt_pk_bf16(v1[2], v1[3]);
;                     if (pn < 16) __builtin_amdgcn_raw_buffer_store_b128(w, q, (row * 4096 + bj * HALF + cw) * 2, pn * 512, 0);
;                     else { const int kvh = ((pn - 16) & 3) * 2 + bj; const int off = ((((row >> 13) * 8 + kvh) * 8192 + (row & 8191)) * 128 + cw) * 2;
;                         if (pn < 20) __builtin_amdgcn_raw_buffer_store_b128(w, k, off, 0, 0); else __builtin_amdgcn_raw_buffer_store_b128(w, v, off, 0, 0); } } }
.LBB0_1320:
	v_lshlrev_b32_e32 v41, 7, v40
	v_and_b32_e32 v41, 0xff780, v41
	v_mul_f32_e32 v26, s38, v26
	v_mul_f32_e32 v27, s38, v27
	v_mul_f32_e32 v24, s38, v24
	v_mul_f32_e32 v25, s38, v25
	v_add_u32_e32 v41, v41, v153
	v_mul_f32_e32 v30, s38, v30
	v_mul_f32_e32 v31, s38, v31
	v_mul_f32_e32 v28, s38, v28
	v_mul_f32_e32 v29, s38, v29
	s_waitcnt vmcnt(0)
	v_mul_f32_e32 v42, v24, v32
	v_mul_f32_e32 v43, v25, v33
	v_mul_f32_e32 v44, v26, v34
	v_mul_f32_e32 v45, v27, v35
	v_mul_f32_e32 v24, v24, v36
	v_mul_f32_e32 v25, v25, v37
	v_mul_f32_e32 v26, v26, v38
	v_mul_f32_e32 v27, v27, v39
	v_fma_f32 v44, v30, v38, -v44
	v_fma_f32 v45, v31, v39, -v45
	v_fma_f32 v42, v28, v36, -v42
	v_fma_f32 v43, v29, v37, -v43
	v_fma_f32 v30, v30, v34, v26
	v_fma_f32 v31, v31, v35, v27
	v_fma_f32 v26, v28, v32, v24
	v_fma_f32 v27, v29, v33, v25
	s_mov_b64 s[26:27], -1
	s_and_b64 vcc, exec, s[8:9]
	v_lshlrev_b32_e32 v28, 1, v41
	v_cvt_pk_bf16_f32 v24, v42, v43
	v_cvt_pk_bf16_f32 v25, v44, v45
	v_cvt_pk_bf16_f32 v26, v26, v27
	v_cvt_pk_bf16_f32 v27, v30, v31
	s_cbranch_vccnz .LBB0_1326
	v_lshl_add_u32 v29, v72, 21, v28
	s_and_b64 vcc, exec, s[6:7]
	s_cbranch_vccnz .LBB0_1323
	s_mov_b32 s26, s22
	s_mov_b32 s27, s23
	buffer_store_dwordx4 v[24:27], v29, s[24:27], 0 offen
	s_mov_b64 s[26:27], 0

; __device__ __forceinline__ unsigned cvt_pk_bf16(float lo, float hi) { unsigned r; asm volatile("v_cvt_pk_bf16_f32 %0, %1, %2" : "=v"(r) : "v"(lo), "v"(hi)); return r; }
;     __device__ __forceinline__ void operator()(const f32x4 (&acc)[2][2][4][2], const Unit& u, int wr, int wc, int fr, int fq) const {
;     ...
;                 for (int bj = 0; bj < 2; ++bj) { f32x4 v0 = acc[ai][bj][m][0] * scl, v1 = acc[ai][bj][m][1] * scl;
;                     rope_pair(v0, v1, c, s);
;                     u32x4 w; w.x = cvt_pk_bf16(v0[0], v0[1]); w.y = cvt_pk_bf16(v0[2], v0[3]); w.z = cvt_pk_bf16(v1[0], v1[1]); w.w = cvt_pk_bf16(v1[2], v1[3]);
;                     if (pn < 16) __builtin_amdgcn_raw_buffer_store_b128(w, q, (row * 4096 + bj * HALF + cw) * 2, pn * 512, 0);
;                     else { const int kvh = ((pn - 16) & 3) * 2 + bj; const int off = ((((row >> 13) * 8 + kvh) * 8192 + (row & 8191)) * 128 + cw) * 2;
;                         if (pn < 20) __builtin_amdgcn_raw_buffer_store_b128(w, k, off, 0, 0); else __builtin_amdgcn_raw_buffer_store_b128(w, v, off, 0, 0); } } }
.LBB0_1328:
	v_mul_f32_e32 v18, s38, v18
	v_mul_f32_e32 v19, s38, v19
	v_mul_f32_e32 v16, s38, v16
	v_mul_f32_e32 v17, s38, v17
	v_mul_f32_e32 v22, s38, v22
	v_mul_f32_e32 v23, s38, v23
	v_mul_f32_e32 v20, s38, v20
	v_mul_f32_e32 v21, s38, v21
	v_mul_f32_e32 v24, v18, v34
	v_mul_f32_e32 v25, v19, v35
	v_mul_f32_e32 v26, v16, v32
	v_mul_f32_e32 v27, v17, v33
	v_mul_f32_e32 v18, v18, v38
	v_mul_f32_e32 v19, v19, v39
	v_mul_f32_e32 v16, v16, v36
	v_mul_f32_e32 v17, v17, v37
	v_fma_f32 v24, v22, v38, -v24
	v_fma_f32 v25, v23, v39, -v25
	v_fma_f32 v22, v22, v34, v18
	v_fma_f32 v23, v23, v35, v19
	v_fma_f32 v18, v20, v32, v16
	v_fma_f32 v19, v21, v33, v17
	s_and_b64 vcc, exec, s[8:9]
	s_mov_b64 s[26:27], -1
	v_fma_f32 v26, v20, v36, -v26
	v_fma_f32 v27, v21, v37, -v27
	s_nop 0
	v_cvt_pk_bf16_f32 v16, v26, v27
	v_cvt_pk_bf16_f32 v17, v24, v25
	v_cvt_pk_bf16_f32 v18, v18, v19
	v_cvt_pk_bf16_f32 v19, v22, v23
	s_cbranch_vccz .LBB0_1332
	s_andn2_b64 vcc, exec, s[26:27]
	s_cbranch_vccz .LBB0_1337

; __device__ __forceinline__ unsigned cvt_pk_bf16(float lo, float hi) { unsigned r; asm volatile("v_cvt_pk_bf16_f32 %0, %1, %2" : "=v"(r) : "v"(lo), "v"(hi)); return r; }
;     __device__ __forceinline__ void operator()(const f32x4 (&acc)[2][2][4][2], const Unit& u, int wr, int wc, int fr, int fq) const {
;     ...
;             for (int m = 0; m < 4; ++m) { const int row = row0 + ai * HALF + m * 16;
;                 f32x4 c = {1.f, 1.f, 1.f, 1.f}, s = {0.f, 0.f, 0.f, 0.f};
;                 if (rope) { c = __builtin_bit_cast(f32x4, __builtin_amdgcn_raw_buffer_load_b128(cs, (row * 64 + f0) * 4, 0, 0)); s = __builtin_bit_cast(f32x4, __builtin_amdgcn_raw_buffer_load_b128(sn, (row * 64 + f0) * 4, 0, 0)); }
; #pragma unroll
;                 for (int bj = 0; bj < 2; ++bj) { f32x4 v0 = acc[ai][bj][m][0] * scl, v1 = acc[ai][bj][m][1] * scl;
;                     rope_pair(v0, v1, c, s);
;                     u32x4 w; w.x = cvt_pk_bf16(v0[0], v0[1]); w.y = cvt_pk_bf16(v0[2], v0[3]); w.z = cvt_pk_bf16(v1[0], v1[1]); w.w = cvt_pk_bf16(v1[2], v1[3]);
;                     if (pn < 16) __builtin_amdgcn_raw_buffer_store_b128(w, q, (row * 4096 + bj * HALF + cw) * 2, pn * 512, 0);
;                     else { const int kvh = ((pn - 16) & 3) * 2 + bj; const int off = ((((row >> 13) * 8 + kvh) * 8192 + (row & 8191)) * 128 + cw) * 2;
;                         if (pn < 20) __builtin_amdgcn_raw_buffer_store_b128(w, k, off, 0, 0); else __builtin_amdgcn_raw_buffer_store_b128(w, v, off, 0, 0); } } }
.LBB0_1339:
	v_lshlrev_b32_e32 v25, 7, v24
	v_and_b32_e32 v25, 0xfff80, v25
	v_mul_f32_e32 v10, s38, v10
	v_mul_f32_e32 v11, s38, v11
	v_mul_f32_e32 v8, s38, v8
	v_mul_f32_e32 v9, s38, v9
	v_add_u32_e32 v25, v25, v153
	v_mul_f32_e32 v14, s38, v14
	v_mul_f32_e32 v15, s38, v15
	v_mul_f32_e32 v12, s38, v12
	v_mul_f32_e32 v13, s38, v13
	s_waitcnt vmcnt(0)
	v_mul_f32_e32 v26, v8, v16
	v_mul_f32_e32 v27, v9, v17
	v_mul_f32_e32 v28, v10, v18
	v_mul_f32_e32 v29, v11, v19
	v_mul_f32_e32 v8, v8, v20
	v_mul_f32_e32 v9, v9, v21
	v_mul_f32_e32 v10, v10, v22
	v_mul_f32_e32 v11, v11, v23
	v_fma_f32 v28, v14, v22, -v28
	v_fma_f32 v29, v15, v23, -v29
	v_fma_f32 v26, v12, v20, -v26
	v_fma_f32 v27, v13, v21, -v27
	v_fma_f32 v14, v14, v18, v10
	v_fma_f32 v15, v15, v19, v11
	v_fma_f32 v10, v12, v16, v8
	v_fma_f32 v11, v13, v17, v9
	s_mov_b64 s[10:11], -1
	s_and_b64 vcc, exec, s[8:9]
	v_lshlrev_b32_e32 v12, 1, v25
	v_cvt_pk_bf16_f32 v8, v26, v27
	v_cvt_pk_bf16_f32 v9, v28, v29
	v_cvt_pk_bf16_f32 v10, v10, v11
	v_cvt_pk_bf16_f32 v11, v14, v15
	s_cbranch_vccnz .LBB0_1345
	v_lshl_add_u32 v13, v72, 21, v12
	s_and_b64 vcc, exec, s[6:7]
	s_cbranch_vccnz .LBB0_1342
	s_mov_b32 s26, s22
	s_mov_b32 s27, s23
	s_mov_b64 s[10:11], 0
	buffer_store_dwordx4 v[8:11], v13, s[24:27], 0 offen

; __device__ __forceinline__ unsigned cvt_pk_bf16(float lo, float hi) { unsigned r; asm volatile("v_cvt_pk_bf16_f32 %0, %1, %2" : "=v"(r) : "v"(lo), "v"(hi)); return r; }
;     __device__ __forceinline__ void operator()(const f32x4 (&acc)[2][2][4][2], const Unit& u, int wr, int wc, int fr, int fq) const {
;     ...
;                 for (int bj = 0; bj < 2; ++bj) { f32x4 v0 = acc[ai][bj][m][0] * scl, v1 = acc[ai][bj][m][1] * scl;
;                     rope_pair(v0, v1, c, s);
;                     u32x4 w; w.x = cvt_pk_bf16(v0[0], v0[1]); w.y = cvt_pk_bf16(v0[2], v0[3]); w.z = cvt_pk_bf16(v1[0], v1[1]); w.w = cvt_pk_bf16(v1[2], v1[3]);
;                     if (pn < 16) __builtin_amdgcn_raw_buffer_store_b128(w, q, (row * 4096 + bj * HALF + cw) * 2, pn * 512, 0);
;                     else { const int kvh = ((pn - 16) & 3) * 2 + bj; const int off = ((((row >> 13) * 8 + kvh) * 8192 + (row & 8191)) * 128 + cw) * 2;
;                         if (pn < 20) __builtin_amdgcn_raw_buffer_store_b128(w, k, off, 0, 0); else __builtin_amdgcn_raw_buffer_store_b128(w, v, off, 0, 0); } } }
.LBB0_1347:
	v_mul_f32_e32 v2, s38, v2
	v_mul_f32_e32 v3, s38, v3
	v_mul_f32_e32 v0, s38, v0
	v_mul_f32_e32 v1, s38, v1
	v_mul_f32_e32 v6, s38, v6
	v_mul_f32_e32 v7, s38, v7
	v_mul_f32_e32 v4, s38, v4
	v_mul_f32_e32 v5, s38, v5
	v_mul_f32_e32 v8, v2, v18
	v_mul_f32_e32 v9, v3, v19
	v_mul_f32_e32 v10, v0, v16
	v_mul_f32_e32 v11, v1, v17
	v_mul_f32_e32 v2, v2, v22
	v_mul_f32_e32 v3, v3, v23
	v_mul_f32_e32 v0, v0, v20
	v_mul_f32_e32 v1, v1, v21
	v_fma_f32 v8, v6, v22, -v8
	v_fma_f32 v9, v7, v23, -v9
	v_fma_f32 v6, v6, v18, v2
	v_fma_f32 v7, v7, v19, v3
	v_fma_f32 v2, v4, v16, v0
	v_fma_f32 v3, v5, v17, v1
	s_and_b64 vcc, exec, s[8:9]
	s_mov_b64 s[8:9], -1
	v_fma_f32 v10, v4, v20, -v10
	v_fma_f32 v11, v5, v21, -v11
	s_nop 0
	v_cvt_pk_bf16_f32 v0, v10, v11
	v_cvt_pk_bf16_f32 v1, v8, v9
	v_cvt_pk_bf16_f32 v2, v2, v3
	v_cvt_pk_bf16_f32 v3, v6, v7
	s_cbranch_vccz .LBB0_1350
	s_andn2_b64 vcc, exec, s[8:9]
	s_cbranch_vccz .LBB0_1355

;     __device__ __forceinline__ void operator()(const f32x4 (&acc)[2][2][4][2], const Unit& u, int wr, int wc, int fr, int fq) const {
;         const int pn = u.pn + pn_off; const int row0 = u.pm * BM + wr * 64 + fr, f0 = 16 * wc + 4 * fq, cw = wc * 32 + 8 * fq;
;         const bool rope = (pn < 20) || (pn >= 24 && pn < 40);
; #pragma unroll
;         for (int ai = 0; ai < 2; ++ai)
; #pragma unroll
;             for (int m = 0; m < 4; ++m) { const int row = row0 + ai * HALF + m * 16;
;                 f32x4 c = {1.f, 1.f, 1.f, 1.f}, s = {0.f, 0.f, 0.f, 0.f};
;                 if (rope) { c = *(const f32x4*)(rt.cs + (size_t)row * 64 + f0); s = *(const f32x4*)(rt.sn + (size_t)row * 64 + f0); }
; #pragma unroll
;                 for (int bj = 0; bj < 2; ++bj) { f32x4 v0 = acc[ai][bj][m][0] * scl, v1 = acc[ai][bj][m][1] * scl;
;                     if (pn < 40) {
;                         rope_pair(v0, v1, c, s);
.LBB0_1378:
	s_add_i32 s8, s8, 24
	s_lshl_b32 s0, s8, 8
	s_lshl_b32 s8, s8, 1
	s_and_b32 s39, s8, 6
	s_ashr_i32 s8, s9, 10
	s_and_b32 s8, s8, -8
	v_lshlrev_b32_e32 v144, 7, v152
	s_ashr_i32 s49, s0, 31
	s_mov_b32 s48, s0
	s_or_b32 s54, s8, s39
	v_lshlrev_b64 v[156:157], 13, v[152:153]
	s_andn2_b64 vcc, exec, s[12:13]
	v_and_b32_e32 v166, 0xfe780, v144
	s_cbranch_vccnz .LBB0_1384
	s_waitcnt vmcnt(0)
	v_mul_f32_e32 v158, v122, v134
	v_mul_f32_e32 v159, v123, v135
	v_mul_f32_e32 v160, v120, v132
	v_mul_f32_e32 v161, v121, v133
	v_fma_f32 v158, v126, v130, -v158
	v_fma_f32 v159, v127, v131, -v159
	v_mul_f32_e32 v126, v126, v134
	v_mul_f32_e32 v127, v127, v135
	v_mul_f32_e32 v168, v124, v132
	v_mul_f32_e32 v169, v125, v133
	v_fma_f32 v160, v124, v128, -v160
	v_fma_f32 v161, v125, v129, -v161
	v_fma_f32 v124, v122, v130, v126
	v_fma_f32 v125, v123, v131, v127
	v_fma_f32 v126, v120, v128, v168
	v_fma_f32 v127, v121, v129, v169
	s_mov_b64 s[8:9], -1
	s_and_b64 vcc, exec, s[56:57]
	s_cbranch_vccnz .LBB0_1537
	s_andn2_b64 vcc, exec, s[8:9]
	s_cbranch_vccz .LBB0_1538

;     __device__ __forceinline__ void operator()(const f32x4 (&acc)[2][2][4][2], const Unit& u, int wr, int wc, int fr, int fq) const {
;     ...
;                     } else {
;                         if (bj == 0) { *(f32x4*)(KIR + (size_t)row * 128 + cw) = v0; *(f32x4*)(KIR + (size_t)row * 128 + cw + 4) = v1; }
;                         else if (wc == 0) { *(f32x4*)(WI + (size_t)row * 32 + cw) = v0 * 0.015625f; *(f32x4*)(WI + (size_t)row * 32 + cw + 4) = v1 * 0.015625f; }
.LBB0_1384:
	s_nop 1
	v_cndmask_b32_e64 v120, 0, 1, s[10:11]
	v_cmp_ne_u32_e64 s[12:13], 1, v120
	v_cndmask_b32_e64 v120, 0, 1, s[30:31]
	s_mov_b64 s[8:9], -1
	s_andn2_b64 vcc, exec, s[10:11]
	v_cmp_ne_u32_e64 s[10:11], 1, v120
	s_cbranch_vccnz .LBB0_1388
	s_and_b64 vcc, exec, s[10:11]
	s_cbranch_vccnz .LBB0_1387
	v_lshlrev_b64 v[120:121], 7, v[152:153]
	v_lshl_add_u64 v[120:121], s[26:27], 0, v[120:121]
	v_lshl_add_u64 v[158:159], v[150:151], 2, v[120:121]
	v_mul_f32_e32 v126, s36, v118
	v_mul_f32_e32 v127, s36, v119
	v_mul_f32_e32 v124, s36, v116
	v_mul_f32_e32 v125, s36, v117
	v_mul_f32_e32 v122, s36, v114
	v_mul_f32_e32 v123, s36, v115
	v_mul_f32_e32 v120, s36, v112
	v_mul_f32_e32 v121, s36, v113
	global_store_dwordx4 v[158:159], v[124:127], off
	global_store_dwordx4 v[158:159], v[120:123], off offset:16

; __device__ __forceinline__ unsigned cvt_pk_bf16(float lo, float hi) { unsigned r; asm volatile("v_cvt_pk_bf16_f32 %0, %1, %2" : "=v"(r) : "v"(lo), "v"(hi)); return r; }
;     __device__ __forceinline__ void operator()(const f32x4 (&acc)[2][2][4][2], const Unit& u, int wr, int wc, int fr, int fq) const {
;     ...
;                 for (int bj = 0; bj < 2; ++bj) { f32x4 v0 = acc[ai][bj][m][0] * scl, v1 = acc[ai][bj][m][1] * scl;
;                     if (pn < 40) {
;                         rope_pair(v0, v1, c, s);
;                         u32x4 w;
;                         if (pn >= 24) { w.x = cvt_pk_f16(v0[0], v0[1]); w.y = cvt_pk_f16(v0[2], v0[3]); w.z = cvt_pk_f16(v1[0], v1[1]); w.w = cvt_pk_f16(v1[2], v1[3]); }
;                         else { w.x = cvt_pk_bf16(v0[0], v0[1]); w.y = cvt_pk_bf16(v0[2], v0[3]); w.z = cvt_pk_bf16(v1[0], v1[1]); w.w = cvt_pk_bf16(v1[2], v1[3]); }
.LBB0_1388:
	s_nop 0
	v_cndmask_b32_e64 v120, 0, 1, s[56:57]
	s_andn2_b64 vcc, exec, s[8:9]
	v_cmp_ne_u32_e64 s[8:9], 1, v120
	s_cbranch_vccnz .LBB0_1394
	s_waitcnt vmcnt(0)
	v_mul_f32_e32 v120, v114, v134
	v_mul_f32_e32 v121, v115, v135
	v_mul_f32_e32 v122, v112, v132
	v_mul_f32_e32 v123, v113, v133
	v_fma_f32 v120, v118, v130, -v120
	v_fma_f32 v121, v119, v131, -v121
	v_mul_f32_e32 v118, v118, v134
	v_mul_f32_e32 v119, v119, v135
	v_mul_f32_e32 v124, v116, v132
	v_mul_f32_e32 v125, v117, v133
	v_fma_f32 v122, v116, v128, -v122
	v_fma_f32 v123, v117, v129, -v123
	v_fma_f32 v116, v114, v130, v118
	v_fma_f32 v117, v115, v131, v119
	v_fma_f32 v118, v112, v128, v124
	v_fma_f32 v119, v113, v129, v125
	s_and_b64 vcc, exec, s[8:9]
	s_mov_b64 s[56:57], -1
	s_cbranch_vccz .LBB0_1544
	s_andn2_b64 vcc, exec, s[56:57]
	s_cbranch_vccz .LBB0_1545

;     __device__ __forceinline__ void operator()(const f32x4 (&acc)[2][2][4][2], const Unit& u, int wr, int wc, int fr, int fq) const {
;     ...
;             for (int m = 0; m < 4; ++m) { const int row = row0 + ai * HALF + m * 16;
;                 f32x4 c = {1.f, 1.f, 1.f, 1.f}, s = {0.f, 0.f, 0.f, 0.f};
;                 if (rope) { c = *(const f32x4*)(rt.cs + (size_t)row * 64 + f0); s = *(const f32x4*)(rt.sn + (size_t)row * 64 + f0); }
; #pragma unroll
;                 for (int bj = 0; bj < 2; ++bj) { f32x4 v0 = acc[ai][bj][m][0] * scl, v1 = acc[ai][bj][m][1] * scl;
;                     if (pn < 40) {
;                         rope_pair(v0, v1, c, s);
.LBB0_1398:
	v_lshlrev_b32_e32 v124, 7, v122
	v_lshlrev_b64 v[120:121], 13, v[122:123]
	s_andn2_b64 vcc, exec, s[56:57]
	s_waitcnt vmcnt(0)
	v_and_b32_e32 v128, 0xfef80, v124
	s_cbranch_vccnz .LBB0_1404
	v_mul_f32_e32 v124, v106, v118
	v_mul_f32_e32 v125, v107, v119
	v_mul_f32_e32 v126, v104, v116
	v_mul_f32_e32 v127, v105, v117
	v_fma_f32 v124, v110, v114, -v124
	v_fma_f32 v125, v111, v115, -v125
	v_mul_f32_e32 v110, v110, v118
	v_mul_f32_e32 v111, v111, v119
	v_mul_f32_e32 v130, v108, v116
	v_mul_f32_e32 v131, v109, v117
	v_fma_f32 v126, v108, v112, -v126
	v_fma_f32 v127, v109, v113, -v127
	v_fma_f32 v108, v106, v114, v110
	v_fma_f32 v109, v107, v115, v111
	v_fma_f32 v110, v104, v112, v130
	v_fma_f32 v111, v105, v113, v131
	s_and_b64 vcc, exec, s[8:9]
	s_mov_b64 s[56:57], -1
	s_cbranch_vccz .LBB0_1551
	s_andn2_b64 vcc, exec, s[56:57]
	s_cbranch_vccz .LBB0_1552

;     __device__ __forceinline__ void operator()(const f32x4 (&acc)[2][2][4][2], const Unit& u, int wr, int wc, int fr, int fq) const {
;     ...
;                     } else {
;                         if (bj == 0) { *(f32x4*)(KIR + (size_t)row * 128 + cw) = v0; *(f32x4*)(KIR + (size_t)row * 128 + cw + 4) = v1; }
;                         else if (wc == 0) { *(f32x4*)(WI + (size_t)row * 32 + cw) = v0 * 0.015625f; *(f32x4*)(WI + (size_t)row * 32 + cw + 4) = v1 * 0.015625f; }
.LBB0_1404:
	s_and_b64 vcc, exec, s[12:13]
	s_mov_b64 s[56:57], -1
	s_cbranch_vccnz .LBB0_1408
	s_and_b64 vcc, exec, s[10:11]
	s_cbranch_vccnz .LBB0_1407
	v_lshlrev_b64 v[104:105], 7, v[122:123]
	v_lshl_add_u64 v[104:105], s[26:27], 0, v[104:105]
	v_lshl_add_u64 v[122:123], v[150:151], 2, v[104:105]
	v_mul_f32_e32 v110, s36, v102
	v_mul_f32_e32 v111, s36, v103
	v_mul_f32_e32 v108, s36, v100
	v_mul_f32_e32 v109, s36, v101
	v_mul_f32_e32 v106, s36, v98
	v_mul_f32_e32 v107, s36, v99
	v_mul_f32_e32 v104, s36, v96
	v_mul_f32_e32 v105, s36, v97
	global_store_dwordx4 v[122:123], v[108:111], off
	global_store_dwordx4 v[122:123], v[104:107], off offset:16

; __device__ __forceinline__ unsigned cvt_pk_bf16(float lo, float hi) { unsigned r; asm volatile("v_cvt_pk_bf16_f32 %0, %1, %2" : "=v"(r) : "v"(lo), "v"(hi)); return r; }
;     __device__ __forceinline__ void operator()(const f32x4 (&acc)[2][2][4][2], const Unit& u, int wr, int wc, int fr, int fq) const {
;     ...
;                 for (int bj = 0; bj < 2; ++bj) { f32x4 v0 = acc[ai][bj][m][0] * scl, v1 = acc[ai][bj][m][1] * scl;
;                     if (pn < 40) {
;                         rope_pair(v0, v1, c, s);
;                         u32x4 w;
;                         if (pn >= 24) { w.x = cvt_pk_f16(v0[0], v0[1]); w.y = cvt_pk_f16(v0[2], v0[3]); w.z = cvt_pk_f16(v1[0], v1[1]); w.w = cvt_pk_f16(v1[2], v1[3]); }
;                         else { w.x = cvt_pk_bf16(v0[0], v0[1]); w.y = cvt_pk_bf16(v0[2], v0[3]); w.z = cvt_pk_bf16(v1[0], v1[1]); w.w = cvt_pk_bf16(v1[2], v1[3]); }
.LBB0_1408:
	s_andn2_b64 vcc, exec, s[56:57]
	s_cbranch_vccnz .LBB0_1414
	v_mul_f32_e32 v104, v98, v118
	v_mul_f32_e32 v105, v99, v119
	v_mul_f32_e32 v106, v96, v116
	v_mul_f32_e32 v107, v97, v117
	v_fma_f32 v104, v102, v114, -v104
	v_fma_f32 v105, v103, v115, -v105
	v_mul_f32_e32 v102, v102, v118
	v_mul_f32_e32 v103, v103, v119
	v_mul_f32_e32 v108, v100, v116
	v_mul_f32_e32 v109, v101, v117
	v_fma_f32 v106, v100, v112, -v106
	v_fma_f32 v107, v101, v113, -v107
	v_fma_f32 v100, v98, v114, v102
	v_fma_f32 v101, v99, v115, v103
	v_fma_f32 v102, v96, v112, v108
	v_fma_f32 v103, v97, v113, v109
	s_and_b64 vcc, exec, s[8:9]
	s_mov_b64 s[56:57], -1
	s_cbranch_vccz .LBB0_1558
	s_andn2_b64 vcc, exec, s[56:57]
	s_cbranch_vccz .LBB0_1559

;     __device__ __forceinline__ void operator()(const f32x4 (&acc)[2][2][4][2], const Unit& u, int wr, int wc, int fr, int fq) const {
;     ...
;             for (int m = 0; m < 4; ++m) { const int row = row0 + ai * HALF + m * 16;
;                 f32x4 c = {1.f, 1.f, 1.f, 1.f}, s = {0.f, 0.f, 0.f, 0.f};
;                 if (rope) { c = *(const f32x4*)(rt.cs + (size_t)row * 64 + f0); s = *(const f32x4*)(rt.sn + (size_t)row * 64 + f0); }
; #pragma unroll
;                 for (int bj = 0; bj < 2; ++bj) { f32x4 v0 = acc[ai][bj][m][0] * scl, v1 = acc[ai][bj][m][1] * scl;
;                     if (pn < 40) {
;                         rope_pair(v0, v1, c, s);
.LBB0_1418:
	v_lshlrev_b32_e32 v108, 7, v106
	v_lshlrev_b64 v[104:105], 13, v[106:107]
	s_andn2_b64 vcc, exec, s[56:57]
	v_and_b32_e32 v112, 0xff780, v108
	s_cbranch_vccnz .LBB0_1424
	s_waitcnt vmcnt(0)
	v_mul_f32_e32 v108, v90, v102
	v_mul_f32_e32 v109, v91, v103
	v_mul_f32_e32 v110, v88, v100
	v_mul_f32_e32 v111, v89, v101
	v_fma_f32 v108, v94, v98, -v108
	v_fma_f32 v109, v95, v99, -v109
	v_mul_f32_e32 v94, v94, v102
	v_mul_f32_e32 v95, v95, v103
	v_mul_f32_e32 v114, v92, v100
	v_mul_f32_e32 v115, v93, v101
	v_fma_f32 v110, v92, v96, -v110
	v_fma_f32 v111, v93, v97, -v111
	v_fma_f32 v92, v90, v98, v94
	v_fma_f32 v93, v91, v99, v95
	v_fma_f32 v94, v88, v96, v114
	v_fma_f32 v95, v89, v97, v115
	s_and_b64 vcc, exec, s[8:9]
	s_mov_b64 s[56:57], -1
	s_cbranch_vccz .LBB0_1565
	s_andn2_b64 vcc, exec, s[56:57]
	s_cbranch_vccz .LBB0_1566

;     __device__ __forceinline__ void operator()(const f32x4 (&acc)[2][2][4][2], const Unit& u, int wr, int wc, int fr, int fq) const {
;     ...
;                     } else {
;                         if (bj == 0) { *(f32x4*)(KIR + (size_t)row * 128 + cw) = v0; *(f32x4*)(KIR + (size_t)row * 128 + cw + 4) = v1; }
;                         else if (wc == 0) { *(f32x4*)(WI + (size_t)row * 32 + cw) = v0 * 0.015625f; *(f32x4*)(WI + (size_t)row * 32 + cw + 4) = v1 * 0.015625f; }
.LBB0_1424:
	s_and_b64 vcc, exec, s[12:13]
	s_mov_b64 s[56:57], -1
	s_cbranch_vccnz .LBB0_1428
	s_and_b64 vcc, exec, s[10:11]
	s_cbranch_vccnz .LBB0_1427
	v_lshlrev_b64 v[88:89], 7, v[106:107]
	v_lshl_add_u64 v[88:89], s[26:27], 0, v[88:89]
	v_lshl_add_u64 v[106:107], v[150:151], 2, v[88:89]
	v_mul_f32_e32 v94, s36, v86
	v_mul_f32_e32 v95, s36, v87
	v_mul_f32_e32 v92, s36, v84
	v_mul_f32_e32 v93, s36, v85
	v_mul_f32_e32 v90, s36, v82
	v_mul_f32_e32 v91, s36, v83
	v_mul_f32_e32 v88, s36, v80
	v_mul_f32_e32 v89, s36, v81
	global_store_dwordx4 v[106:107], v[92:95], off
	global_store_dwordx4 v[106:107], v[88:91], off offset:16

; __device__ __forceinline__ unsigned cvt_pk_bf16(float lo, float hi) { unsigned r; asm volatile("v_cvt_pk_bf16_f32 %0, %1, %2" : "=v"(r) : "v"(lo), "v"(hi)); return r; }
;     __device__ __forceinline__ void operator()(const f32x4 (&acc)[2][2][4][2], const Unit& u, int wr, int wc, int fr, int fq) const {
;     ...
;                 for (int bj = 0; bj < 2; ++bj) { f32x4 v0 = acc[ai][bj][m][0] * scl, v1 = acc[ai][bj][m][1] * scl;
;                     if (pn < 40) {
;                         rope_pair(v0, v1, c, s);
;                         u32x4 w;
;                         if (pn >= 24) { w.x = cvt_pk_f16(v0[0], v0[1]); w.y = cvt_pk_f16(v0[2], v0[3]); w.z = cvt_pk_f16(v1[0], v1[1]); w.w = cvt_pk_f16(v1[2], v1[3]); }
;                         else { w.x = cvt_pk_bf16(v0[0], v0[1]); w.y = cvt_pk_bf16(v0[2], v0[3]); w.z = cvt_pk_bf16(v1[0], v1[1]); w.w = cvt_pk_bf16(v1[2], v1[3]); }
.LBB0_1428:
	s_andn2_b64 vcc, exec, s[56:57]
	s_cbranch_vccnz .LBB0_1434
	s_waitcnt vmcnt(0)
	v_mul_f32_e32 v88, v82, v102
	v_mul_f32_e32 v89, v83, v103
	v_mul_f32_e32 v90, v80, v100
	v_mul_f32_e32 v91, v81, v101
	v_fma_f32 v88, v86, v98, -v88
	v_fma_f32 v89, v87, v99, -v89
	v_mul_f32_e32 v86, v86, v102
	v_mul_f32_e32 v87, v87, v103
	v_mul_f32_e32 v92, v84, v100
	v_mul_f32_e32 v93, v85, v101
	v_fma_f32 v90, v84, v96, -v90
	v_fma_f32 v91, v85, v97, -v91
	v_fma_f32 v84, v82, v98, v86
	v_fma_f32 v85, v83, v99, v87
	v_fma_f32 v86, v80, v96, v92
	v_fma_f32 v87, v81, v97, v93
	s_and_b64 vcc, exec, s[8:9]
	s_mov_b64 s[56:57], -1
	s_cbranch_vccz .LBB0_1572
	s_andn2_b64 vcc, exec, s[56:57]
	s_cbranch_vccz .LBB0_1573

;     __device__ __forceinline__ void operator()(const f32x4 (&acc)[2][2][4][2], const Unit& u, int wr, int wc, int fr, int fq) const {
;     ...
;             for (int m = 0; m < 4; ++m) { const int row = row0 + ai * HALF + m * 16;
;                 f32x4 c = {1.f, 1.f, 1.f, 1.f}, s = {0.f, 0.f, 0.f, 0.f};
;                 if (rope) { c = *(const f32x4*)(rt.cs + (size_t)row * 64 + f0); s = *(const f32x4*)(rt.sn + (size_t)row * 64 + f0); }
; #pragma unroll
;                 for (int bj = 0; bj < 2; ++bj) { f32x4 v0 = acc[ai][bj][m][0] * scl, v1 = acc[ai][bj][m][1] * scl;
;                     if (pn < 40) {
;                         rope_pair(v0, v1, c, s);
.LBB0_1438:
	v_lshlrev_b32_e32 v92, 7, v90
	v_lshlrev_b64 v[88:89], 13, v[90:91]
	s_andn2_b64 vcc, exec, s[56:57]
	s_waitcnt vmcnt(1)
	v_and_b32_e32 v96, 0xfff80, v92
	s_cbranch_vccnz .LBB0_1444
	s_waitcnt vmcnt(0)
	v_mul_f32_e32 v92, v74, v86
	v_mul_f32_e32 v93, v75, v87
	v_mul_f32_e32 v94, v72, v84
	v_mul_f32_e32 v95, v73, v85
	v_fma_f32 v92, v78, v82, -v92
	v_fma_f32 v93, v79, v83, -v93
	v_mul_f32_e32 v78, v78, v86
	v_mul_f32_e32 v79, v79, v87
	v_mul_f32_e32 v98, v76, v84
	v_mul_f32_e32 v99, v77, v85
	v_fma_f32 v94, v76, v80, -v94
	v_fma_f32 v95, v77, v81, -v95
	v_fma_f32 v76, v74, v82, v78
	v_fma_f32 v77, v75, v83, v79
	v_fma_f32 v78, v72, v80, v98
	v_fma_f32 v79, v73, v81, v99
	s_and_b64 vcc, exec, s[8:9]
	s_mov_b64 s[56:57], -1
	s_cbranch_vccz .LBB0_1579
	s_andn2_b64 vcc, exec, s[56:57]
	s_cbranch_vccz .LBB0_1580

;     __device__ __forceinline__ void operator()(const f32x4 (&acc)[2][2][4][2], const Unit& u, int wr, int wc, int fr, int fq) const {
;     ...
;                     } else {
;                         if (bj == 0) { *(f32x4*)(KIR + (size_t)row * 128 + cw) = v0; *(f32x4*)(KIR + (size_t)row * 128 + cw + 4) = v1; }
;                         else if (wc == 0) { *(f32x4*)(WI + (size_t)row * 32 + cw) = v0 * 0.015625f; *(f32x4*)(WI + (size_t)row * 32 + cw + 4) = v1 * 0.015625f; }
.LBB0_1444:
	s_and_b64 vcc, exec, s[12:13]
	s_mov_b64 s[56:57], -1
	s_cbranch_vccnz .LBB0_1448
	s_and_b64 vcc, exec, s[10:11]
	s_cbranch_vccnz .LBB0_1447
	v_lshlrev_b64 v[72:73], 7, v[90:91]
	v_lshl_add_u64 v[72:73], s[26:27], 0, v[72:73]
	v_lshl_add_u64 v[90:91], v[150:151], 2, v[72:73]
	v_mul_f32_e32 v78, s36, v70
	v_mul_f32_e32 v79, s36, v71
	v_mul_f32_e32 v76, s36, v68
	v_mul_f32_e32 v77, s36, v69
	v_mul_f32_e32 v74, s36, v66
	v_mul_f32_e32 v75, s36, v67
	v_mul_f32_e32 v72, s36, v64
	v_mul_f32_e32 v73, s36, v65
	global_store_dwordx4 v[90:91], v[76:79], off
	global_store_dwordx4 v[90:91], v[72:75], off offset:16

; __device__ __forceinline__ unsigned cvt_pk_bf16(float lo, float hi) { unsigned r; asm volatile("v_cvt_pk_bf16_f32 %0, %1, %2" : "=v"(r) : "v"(lo), "v"(hi)); return r; }
;     __device__ __forceinline__ void operator()(const f32x4 (&acc)[2][2][4][2], const Unit& u, int wr, int wc, int fr, int fq) const {
;     ...
;                 for (int bj = 0; bj < 2; ++bj) { f32x4 v0 = acc[ai][bj][m][0] * scl, v1 = acc[ai][bj][m][1] * scl;
;                     if (pn < 40) {
;                         rope_pair(v0, v1, c, s);
;                         u32x4 w;
;                         if (pn >= 24) { w.x = cvt_pk_f16(v0[0], v0[1]); w.y = cvt_pk_f16(v0[2], v0[3]); w.z = cvt_pk_f16(v1[0], v1[1]); w.w = cvt_pk_f16(v1[2], v1[3]); }
;                         else { w.x = cvt_pk_bf16(v0[0], v0[1]); w.y = cvt_pk_bf16(v0[2], v0[3]); w.z = cvt_pk_bf16(v1[0], v1[1]); w.w = cvt_pk_bf16(v1[2], v1[3]); }
.LBB0_1448:
	s_andn2_b64 vcc, exec, s[56:57]
	s_cbranch_vccnz .LBB0_1454
	s_waitcnt vmcnt(0)
	v_mul_f32_e32 v72, v66, v86
	v_mul_f32_e32 v73, v67, v87
	v_mul_f32_e32 v74, v64, v84
	v_mul_f32_e32 v75, v65, v85
	v_fma_f32 v72, v70, v82, -v72
	v_fma_f32 v73, v71, v83, -v73
	v_mul_f32_e32 v70, v70, v86
	v_mul_f32_e32 v71, v71, v87
	v_mul_f32_e32 v76, v68, v84
	v_mul_f32_e32 v77, v69, v85
	v_fma_f32 v74, v68, v80, -v74
	v_fma_f32 v75, v69, v81, -v75
	v_fma_f32 v68, v66, v82, v70
	v_fma_f32 v69, v67, v83, v71
	v_fma_f32 v70, v64, v80, v76
	v_fma_f32 v71, v65, v81, v77
	s_and_b64 vcc, exec, s[8:9]
	s_mov_b64 s[56:57], -1
	s_cbranch_vccz .LBB0_1586
	s_andn2_b64 vcc, exec, s[56:57]
	s_cbranch_vccz .LBB0_1587

;     __device__ __forceinline__ void operator()(const f32x4 (&acc)[2][2][4][2], const Unit& u, int wr, int wc, int fr, int fq) const {
;     ...
;             for (int m = 0; m < 4; ++m) { const int row = row0 + ai * HALF + m * 16;
;                 f32x4 c = {1.f, 1.f, 1.f, 1.f}, s = {0.f, 0.f, 0.f, 0.f};
;                 if (rope) { c = *(const f32x4*)(rt.cs + (size_t)row * 64 + f0); s = *(const f32x4*)(rt.sn + (size_t)row * 64 + f0); }
; #pragma unroll
;                 for (int bj = 0; bj < 2; ++bj) { f32x4 v0 = acc[ai][bj][m][0] * scl, v1 = acc[ai][bj][m][1] * scl;
;                     if (pn < 40) {
;                         rope_pair(v0, v1, c, s);
.LBB0_1458:
	v_ashrrev_i32_e32 v72, 10, v76
	v_lshlrev_b32_e32 v73, 7, v76
	v_and_or_b32 v72, v72, -8, s39
	v_lshlrev_b64 v[74:75], 13, v[76:77]
	s_andn2_b64 vcc, exec, s[54:55]
	v_and_b32_e32 v82, 0xfe780, v73
	s_cbranch_vccnz .LBB0_1464
	s_waitcnt vmcnt(0)
	v_mul_f32_e32 v78, v58, v70
	v_mul_f32_e32 v79, v59, v71
	v_mul_f32_e32 v80, v56, v68
	v_mul_f32_e32 v81, v57, v69
	v_fma_f32 v78, v62, v66, -v78
	v_fma_f32 v79, v63, v67, -v79
	v_mul_f32_e32 v62, v62, v70
	v_mul_f32_e32 v63, v63, v71
	v_mul_f32_e32 v84, v60, v68
	v_mul_f32_e32 v85, v61, v69
	v_fma_f32 v80, v60, v64, -v80
	v_fma_f32 v81, v61, v65, -v81
	v_fma_f32 v60, v58, v66, v62
	v_fma_f32 v61, v59, v67, v63
	v_fma_f32 v62, v56, v64, v84
	v_fma_f32 v63, v57, v65, v85
	s_and_b64 vcc, exec, s[8:9]
	s_mov_b64 s[54:55], -1
	s_cbranch_vccz .LBB0_1593
	s_andn2_b64 vcc, exec, s[54:55]
	s_cbranch_vccz .LBB0_1594

;     __device__ __forceinline__ void operator()(const f32x4 (&acc)[2][2][4][2], const Unit& u, int wr, int wc, int fr, int fq) const {
;     ...
;                     } else {
;                         if (bj == 0) { *(f32x4*)(KIR + (size_t)row * 128 + cw) = v0; *(f32x4*)(KIR + (size_t)row * 128 + cw + 4) = v1; }
;                         else if (wc == 0) { *(f32x4*)(WI + (size_t)row * 32 + cw) = v0 * 0.015625f; *(f32x4*)(WI + (size_t)row * 32 + cw + 4) = v1 * 0.015625f; }
.LBB0_1464:
	s_and_b64 vcc, exec, s[12:13]
	s_mov_b64 s[54:55], -1
	s_cbranch_vccnz .LBB0_1468
	s_and_b64 vcc, exec, s[10:11]
	s_cbranch_vccnz .LBB0_1467
	v_lshlrev_b64 v[56:57], 7, v[76:77]
	v_lshl_add_u64 v[56:57], s[26:27], 0, v[56:57]
	v_lshl_add_u64 v[76:77], v[150:151], 2, v[56:57]
	v_mul_f32_e32 v62, s36, v54
	v_mul_f32_e32 v63, s36, v55
	v_mul_f32_e32 v60, s36, v52
	v_mul_f32_e32 v61, s36, v53
	v_mul_f32_e32 v58, s36, v50
	v_mul_f32_e32 v59, s36, v51
	v_mul_f32_e32 v56, s36, v48
	v_mul_f32_e32 v57, s36, v49
	global_store_dwordx4 v[76:77], v[60:63], off
	global_store_dwordx4 v[76:77], v[56:59], off offset:16

; __device__ __forceinline__ unsigned cvt_pk_bf16(float lo, float hi) { unsigned r; asm volatile("v_cvt_pk_bf16_f32 %0, %1, %2" : "=v"(r) : "v"(lo), "v"(hi)); return r; }
;     __device__ __forceinline__ void operator()(const f32x4 (&acc)[2][2][4][2], const Unit& u, int wr, int wc, int fr, int fq) const {
;     ...
;                 for (int bj = 0; bj < 2; ++bj) { f32x4 v0 = acc[ai][bj][m][0] * scl, v1 = acc[ai][bj][m][1] * scl;
;                     if (pn < 40) {
;                         rope_pair(v0, v1, c, s);
;                         u32x4 w;
;                         if (pn >= 24) { w.x = cvt_pk_f16(v0[0], v0[1]); w.y = cvt_pk_f16(v0[2], v0[3]); w.z = cvt_pk_f16(v1[0], v1[1]); w.w = cvt_pk_f16(v1[2], v1[3]); }
;                         else { w.x = cvt_pk_bf16(v0[0], v0[1]); w.y = cvt_pk_bf16(v0[2], v0[3]); w.z = cvt_pk_bf16(v1[0], v1[1]); w.w = cvt_pk_bf16(v1[2], v1[3]); }
.LBB0_1468:
	s_andn2_b64 vcc, exec, s[54:55]
	s_cbranch_vccnz .LBB0_1474
	s_waitcnt vmcnt(0)
	v_mul_f32_e32 v56, v50, v70
	v_mul_f32_e32 v57, v51, v71
	v_mul_f32_e32 v58, v48, v68
	v_mul_f32_e32 v59, v49, v69
	v_fma_f32 v56, v54, v66, -v56
	v_fma_f32 v57, v55, v67, -v57
	v_mul_f32_e32 v54, v54, v70
	v_mul_f32_e32 v55, v55, v71
	v_mul_f32_e32 v60, v52, v68
	v_mul_f32_e32 v61, v53, v69
	v_fma_f32 v58, v52, v64, -v58
	v_fma_f32 v59, v53, v65, -v59
	v_fma_f32 v52, v50, v66, v54
	v_fma_f32 v53, v51, v67, v55
	v_fma_f32 v54, v48, v64, v60
	v_fma_f32 v55, v49, v65, v61
	s_and_b64 vcc, exec, s[8:9]
	s_mov_b64 s[54:55], -1
	s_cbranch_vccz .LBB0_1600
	s_andn2_b64 vcc, exec, s[54:55]
	s_cbranch_vccz .LBB0_1601

;     __device__ __forceinline__ void operator()(const f32x4 (&acc)[2][2][4][2], const Unit& u, int wr, int wc, int fr, int fq) const {
;     ...
;             for (int m = 0; m < 4; ++m) { const int row = row0 + ai * HALF + m * 16;
;                 f32x4 c = {1.f, 1.f, 1.f, 1.f}, s = {0.f, 0.f, 0.f, 0.f};
;                 if (rope) { c = *(const f32x4*)(rt.cs + (size_t)row * 64 + f0); s = *(const f32x4*)(rt.sn + (size_t)row * 64 + f0); }
; #pragma unroll
;                 for (int bj = 0; bj < 2; ++bj) { f32x4 v0 = acc[ai][bj][m][0] * scl, v1 = acc[ai][bj][m][1] * scl;
;                     if (pn < 40) {
;                         rope_pair(v0, v1, c, s);
.LBB0_1478:
	v_lshlrev_b32_e32 v60, 7, v58
	v_lshlrev_b64 v[56:57], 13, v[58:59]
	s_andn2_b64 vcc, exec, s[54:55]
	s_waitcnt vmcnt(1)
	v_and_b32_e32 v64, 0xfef80, v60
	s_cbranch_vccnz .LBB0_1484
	s_waitcnt vmcnt(0)
	v_mul_f32_e32 v60, v42, v54
	v_mul_f32_e32 v61, v43, v55
	v_mul_f32_e32 v62, v40, v52
	v_mul_f32_e32 v63, v41, v53
	v_fma_f32 v60, v46, v50, -v60
	v_fma_f32 v61, v47, v51, -v61
	v_mul_f32_e32 v46, v46, v54
	v_mul_f32_e32 v47, v47, v55
	v_mul_f32_e32 v66, v44, v52
	v_mul_f32_e32 v67, v45, v53
	v_fma_f32 v62, v44, v48, -v62
	v_fma_f32 v63, v45, v49, -v63
	v_fma_f32 v44, v42, v50, v46
	v_fma_f32 v45, v43, v51, v47
	v_fma_f32 v46, v40, v48, v66
	v_fma_f32 v47, v41, v49, v67
	s_and_b64 vcc, exec, s[8:9]
	s_mov_b64 s[54:55], -1
	s_cbranch_vccz .LBB0_1607
	s_andn2_b64 vcc, exec, s[54:55]
	s_cbranch_vccz .LBB0_1608

;     __device__ __forceinline__ void operator()(const f32x4 (&acc)[2][2][4][2], const Unit& u, int wr, int wc, int fr, int fq) const {
;     ...
;                     } else {
;                         if (bj == 0) { *(f32x4*)(KIR + (size_t)row * 128 + cw) = v0; *(f32x4*)(KIR + (size_t)row * 128 + cw + 4) = v1; }
;                         else if (wc == 0) { *(f32x4*)(WI + (size_t)row * 32 + cw) = v0 * 0.015625f; *(f32x4*)(WI + (size_t)row * 32 + cw + 4) = v1 * 0.015625f; }
.LBB0_1484:
	s_and_b64 vcc, exec, s[12:13]
	s_mov_b64 s[54:55], -1
	s_cbranch_vccnz .LBB0_1488
	s_and_b64 vcc, exec, s[10:11]
	s_cbranch_vccnz .LBB0_1487
	v_lshlrev_b64 v[40:41], 7, v[58:59]
	v_lshl_add_u64 v[40:41], s[26:27], 0, v[40:41]
	v_lshl_add_u64 v[58:59], v[150:151], 2, v[40:41]
	v_mul_f32_e32 v46, s36, v38
	v_mul_f32_e32 v47, s36, v39
	v_mul_f32_e32 v44, s36, v36
	v_mul_f32_e32 v45, s36, v37
	v_mul_f32_e32 v42, s36, v34
	v_mul_f32_e32 v43, s36, v35
	v_mul_f32_e32 v40, s36, v32
	v_mul_f32_e32 v41, s36, v33
	global_store_dwordx4 v[58:59], v[44:47], off
	global_store_dwordx4 v[58:59], v[40:43], off offset:16

; __device__ __forceinline__ unsigned cvt_pk_bf16(float lo, float hi) { unsigned r; asm volatile("v_cvt_pk_bf16_f32 %0, %1, %2" : "=v"(r) : "v"(lo), "v"(hi)); return r; }
;     __device__ __forceinline__ void operator()(const f32x4 (&acc)[2][2][4][2], const Unit& u, int wr, int wc, int fr, int fq) const {
;     ...
;                 for (int bj = 0; bj < 2; ++bj) { f32x4 v0 = acc[ai][bj][m][0] * scl, v1 = acc[ai][bj][m][1] * scl;
;                     if (pn < 40) {
;                         rope_pair(v0, v1, c, s);
;                         u32x4 w;
;                         if (pn >= 24) { w.x = cvt_pk_f16(v0[0], v0[1]); w.y = cvt_pk_f16(v0[2], v0[3]); w.z = cvt_pk_f16(v1[0], v1[1]); w.w = cvt_pk_f16(v1[2], v1[3]); }
;                         else { w.x = cvt_pk_bf16(v0[0], v0[1]); w.y = cvt_pk_bf16(v0[2], v0[3]); w.z = cvt_pk_bf16(v1[0], v1[1]); w.w = cvt_pk_bf16(v1[2], v1[3]); }
.LBB0_1488:
	s_andn2_b64 vcc, exec, s[54:55]
	s_cbranch_vccnz .LBB0_1494
	s_waitcnt vmcnt(0)
	v_mul_f32_e32 v40, v34, v54
	v_mul_f32_e32 v41, v35, v55
	v_mul_f32_e32 v42, v32, v52
	v_mul_f32_e32 v43, v33, v53
	v_fma_f32 v40, v38, v50, -v40
	v_fma_f32 v41, v39, v51, -v41
	v_mul_f32_e32 v38, v38, v54
	v_mul_f32_e32 v39, v39, v55
	v_mul_f32_e32 v44, v36, v52
	v_mul_f32_e32 v45, v37, v53
	v_fma_f32 v42, v36, v48, -v42
	v_fma_f32 v43, v37, v49, -v43
	v_fma_f32 v36, v34, v50, v38
	v_fma_f32 v37, v35, v51, v39
	v_fma_f32 v38, v32, v48, v44
	v_fma_f32 v39, v33, v49, v45
	s_and_b64 vcc, exec, s[8:9]
	s_mov_b64 s[54:55], -1
	s_cbranch_vccz .LBB0_1614
	s_andn2_b64 vcc, exec, s[54:55]
	s_cbranch_vccz .LBB0_1615

;     __device__ __forceinline__ void operator()(const f32x4 (&acc)[2][2][4][2], const Unit& u, int wr, int wc, int fr, int fq) const {
;     ...
;             for (int m = 0; m < 4; ++m) { const int row = row0 + ai * HALF + m * 16;
;                 f32x4 c = {1.f, 1.f, 1.f, 1.f}, s = {0.f, 0.f, 0.f, 0.f};
;                 if (rope) { c = *(const f32x4*)(rt.cs + (size_t)row * 64 + f0); s = *(const f32x4*)(rt.sn + (size_t)row * 64 + f0); }
; #pragma unroll
;                 for (int bj = 0; bj < 2; ++bj) { f32x4 v0 = acc[ai][bj][m][0] * scl, v1 = acc[ai][bj][m][1] * scl;
;                     if (pn < 40) {
;                         rope_pair(v0, v1, c, s);
.LBB0_1498:
	v_lshlrev_b32_e32 v44, 7, v42
	v_lshlrev_b64 v[40:41], 13, v[42:43]
	s_andn2_b64 vcc, exec, s[54:55]
	v_and_b32_e32 v48, 0xff780, v44
	s_cbranch_vccnz .LBB0_1504
	s_waitcnt vmcnt(0)
	v_mul_f32_e32 v44, v26, v38
	v_mul_f32_e32 v45, v27, v39
	v_mul_f32_e32 v46, v24, v36
	v_mul_f32_e32 v47, v25, v37
	v_fma_f32 v44, v30, v34, -v44
	v_fma_f32 v45, v31, v35, -v45
	v_mul_f32_e32 v30, v30, v38
	v_mul_f32_e32 v31, v31, v39
	v_mul_f32_e32 v50, v28, v36
	v_mul_f32_e32 v51, v29, v37
	v_fma_f32 v46, v28, v32, -v46
	v_fma_f32 v47, v29, v33, -v47
	v_fma_f32 v28, v26, v34, v30
	v_fma_f32 v29, v27, v35, v31
	v_fma_f32 v30, v24, v32, v50
	v_fma_f32 v31, v25, v33, v51
	s_and_b64 vcc, exec, s[8:9]
	s_mov_b64 s[54:55], -1
	s_cbranch_vccz .LBB0_1621
	s_andn2_b64 vcc, exec, s[54:55]
	s_cbranch_vccz .LBB0_1622

;     __device__ __forceinline__ void operator()(const f32x4 (&acc)[2][2][4][2], const Unit& u, int wr, int wc, int fr, int fq) const {
;     ...
;                     } else {
;                         if (bj == 0) { *(f32x4*)(KIR + (size_t)row * 128 + cw) = v0; *(f32x4*)(KIR + (size_t)row * 128 + cw + 4) = v1; }
;                         else if (wc == 0) { *(f32x4*)(WI + (size_t)row * 32 + cw) = v0 * 0.015625f; *(f32x4*)(WI + (size_t)row * 32 + cw + 4) = v1 * 0.015625f; }
.LBB0_1504:
	s_and_b64 vcc, exec, s[12:13]
	s_mov_b64 s[54:55], -1
	s_cbranch_vccnz .LBB0_1508
	s_and_b64 vcc, exec, s[10:11]
	s_cbranch_vccnz .LBB0_1507
	v_lshlrev_b64 v[24:25], 7, v[42:43]
	v_lshl_add_u64 v[24:25], s[26:27], 0, v[24:25]
	v_lshl_add_u64 v[42:43], v[150:151], 2, v[24:25]
	v_mul_f32_e32 v30, s36, v22
	v_mul_f32_e32 v31, s36, v23
	v_mul_f32_e32 v28, s36, v20
	v_mul_f32_e32 v29, s36, v21
	v_mul_f32_e32 v26, s36, v18
	v_mul_f32_e32 v27, s36, v19
	v_mul_f32_e32 v24, s36, v16
	v_mul_f32_e32 v25, s36, v17
	global_store_dwordx4 v[42:43], v[28:31], off
	global_store_dwordx4 v[42:43], v[24:27], off offset:16

; __device__ __forceinline__ unsigned cvt_pk_bf16(float lo, float hi) { unsigned r; asm volatile("v_cvt_pk_bf16_f32 %0, %1, %2" : "=v"(r) : "v"(lo), "v"(hi)); return r; }
;     __device__ __forceinline__ void operator()(const f32x4 (&acc)[2][2][4][2], const Unit& u, int wr, int wc, int fr, int fq) const {
;     ...
;                 for (int bj = 0; bj < 2; ++bj) { f32x4 v0 = acc[ai][bj][m][0] * scl, v1 = acc[ai][bj][m][1] * scl;
;                     if (pn < 40) {
;                         rope_pair(v0, v1, c, s);
;                         u32x4 w;
;                         if (pn >= 24) { w.x = cvt_pk_f16(v0[0], v0[1]); w.y = cvt_pk_f16(v0[2], v0[3]); w.z = cvt_pk_f16(v1[0], v1[1]); w.w = cvt_pk_f16(v1[2], v1[3]); }
;                         else { w.x = cvt_pk_bf16(v0[0], v0[1]); w.y = cvt_pk_bf16(v0[2], v0[3]); w.z = cvt_pk_bf16(v1[0], v1[1]); w.w = cvt_pk_bf16(v1[2], v1[3]); }
.LBB0_1508:
	s_andn2_b64 vcc, exec, s[54:55]
	s_cbranch_vccnz .LBB0_1514
	s_waitcnt vmcnt(0)
	v_mul_f32_e32 v24, v18, v38
	v_mul_f32_e32 v25, v19, v39
	v_mul_f32_e32 v26, v16, v36
	v_mul_f32_e32 v27, v17, v37
	v_fma_f32 v24, v22, v34, -v24
	v_fma_f32 v25, v23, v35, -v25
	v_mul_f32_e32 v22, v22, v38
	v_mul_f32_e32 v23, v23, v39
	v_mul_f32_e32 v28, v20, v36
	v_mul_f32_e32 v29, v21, v37
	v_fma_f32 v26, v20, v32, -v26
	v_fma_f32 v27, v21, v33, -v27
	v_fma_f32 v20, v18, v34, v22
	v_fma_f32 v21, v19, v35, v23
	v_fma_f32 v22, v16, v32, v28
	v_fma_f32 v23, v17, v33, v29
	s_and_b64 vcc, exec, s[8:9]
	s_mov_b64 s[54:55], -1
	s_cbranch_vccz .LBB0_1628
	s_andn2_b64 vcc, exec, s[54:55]
	s_cbranch_vccz .LBB0_1629

;     __device__ __forceinline__ void operator()(const f32x4 (&acc)[2][2][4][2], const Unit& u, int wr, int wc, int fr, int fq) const {
;     ...
;             for (int m = 0; m < 4; ++m) { const int row = row0 + ai * HALF + m * 16;
;                 f32x4 c = {1.f, 1.f, 1.f, 1.f}, s = {0.f, 0.f, 0.f, 0.f};
;                 if (rope) { c = *(const f32x4*)(rt.cs + (size_t)row * 64 + f0); s = *(const f32x4*)(rt.sn + (size_t)row * 64 + f0); }
; #pragma unroll
;                 for (int bj = 0; bj < 2; ++bj) { f32x4 v0 = acc[ai][bj][m][0] * scl, v1 = acc[ai][bj][m][1] * scl;
;                     if (pn < 40) {
;                         rope_pair(v0, v1, c, s);
.LBB0_1518:
	v_lshlrev_b32_e32 v28, 7, v26
	v_lshlrev_b64 v[24:25], 13, v[26:27]
	s_andn2_b64 vcc, exec, s[6:7]
	s_waitcnt vmcnt(1)
	v_and_b32_e32 v32, 0xfff80, v28
	s_cbranch_vccnz .LBB0_1524
	s_waitcnt vmcnt(0)
	v_mul_f32_e32 v28, v10, v22
	v_mul_f32_e32 v29, v11, v23
	v_mul_f32_e32 v30, v8, v20
	v_mul_f32_e32 v31, v9, v21
	v_fma_f32 v28, v14, v18, -v28
	v_fma_f32 v29, v15, v19, -v29
	v_mul_f32_e32 v14, v14, v22
	v_mul_f32_e32 v15, v15, v23
	v_mul_f32_e32 v34, v12, v20
	v_mul_f32_e32 v35, v13, v21
	v_fma_f32 v30, v12, v16, -v30
	v_fma_f32 v31, v13, v17, -v31
	v_fma_f32 v12, v10, v18, v14
	v_fma_f32 v13, v11, v19, v15
	v_fma_f32 v14, v8, v16, v34
	v_fma_f32 v15, v9, v17, v35
	s_and_b64 vcc, exec, s[8:9]
	s_mov_b64 s[6:7], -1
	s_cbranch_vccz .LBB0_1635
	s_andn2_b64 vcc, exec, s[6:7]
	s_cbranch_vccz .LBB0_1636

;     __device__ __forceinline__ void operator()(const f32x4 (&acc)[2][2][4][2], const Unit& u, int wr, int wc, int fr, int fq) const {
;     ...
;                     } else {
;                         if (bj == 0) { *(f32x4*)(KIR + (size_t)row * 128 + cw) = v0; *(f32x4*)(KIR + (size_t)row * 128 + cw + 4) = v1; }
;                         else if (wc == 0) { *(f32x4*)(WI + (size_t)row * 32 + cw) = v0 * 0.015625f; *(f32x4*)(WI + (size_t)row * 32 + cw + 4) = v1 * 0.015625f; }
.LBB0_1524:
	s_and_b64 vcc, exec, s[12:13]
	s_mov_b64 s[6:7], -1
	s_cbranch_vccnz .LBB0_1528
	s_and_b64 vcc, exec, s[10:11]
	s_cbranch_vccnz .LBB0_1527
	v_lshlrev_b64 v[8:9], 7, v[26:27]
	v_lshl_add_u64 v[8:9], s[26:27], 0, v[8:9]
	v_lshl_add_u64 v[26:27], v[150:151], 2, v[8:9]
	v_mul_f32_e32 v14, s36, v6
	v_mul_f32_e32 v15, s36, v7
	v_mul_f32_e32 v12, s36, v4
	v_mul_f32_e32 v13, s36, v5
	v_mul_f32_e32 v10, s36, v2
	v_mul_f32_e32 v11, s36, v3
	v_mul_f32_e32 v8, s36, v0
	v_mul_f32_e32 v9, s36, v1
	global_store_dwordx4 v[26:27], v[12:15], off
	global_store_dwordx4 v[26:27], v[8:11], off offset:16

; __device__ __forceinline__ unsigned cvt_pk_bf16(float lo, float hi) { unsigned r; asm volatile("v_cvt_pk_bf16_f32 %0, %1, %2" : "=v"(r) : "v"(lo), "v"(hi)); return r; }
;     __device__ __forceinline__ void operator()(const f32x4 (&acc)[2][2][4][2], const Unit& u, int wr, int wc, int fr, int fq) const {
;     ...
;                 for (int bj = 0; bj < 2; ++bj) { f32x4 v0 = acc[ai][bj][m][0] * scl, v1 = acc[ai][bj][m][1] * scl;
;                     if (pn < 40) {
;                         rope_pair(v0, v1, c, s);
;                         u32x4 w;
;                         if (pn >= 24) { w.x = cvt_pk_f16(v0[0], v0[1]); w.y = cvt_pk_f16(v0[2], v0[3]); w.z = cvt_pk_f16(v1[0], v1[1]); w.w = cvt_pk_f16(v1[2], v1[3]); }
;                         else { w.x = cvt_pk_bf16(v0[0], v0[1]); w.y = cvt_pk_bf16(v0[2], v0[3]); w.z = cvt_pk_bf16(v1[0], v1[1]); w.w = cvt_pk_bf16(v1[2], v1[3]); }
.LBB0_1528:
	s_andn2_b64 vcc, exec, s[6:7]
	s_cbranch_vccnz .LBB0_1534
	s_waitcnt vmcnt(0)
	v_mul_f32_e32 v8, v2, v22
	v_mul_f32_e32 v9, v3, v23
	v_mul_f32_e32 v10, v0, v20
	v_mul_f32_e32 v11, v1, v21
	v_fma_f32 v8, v6, v18, -v8
	v_fma_f32 v9, v7, v19, -v9
	v_mul_f32_e32 v6, v6, v22
	v_mul_f32_e32 v7, v7, v23
	v_mul_f32_e32 v12, v4, v20
	v_mul_f32_e32 v13, v5, v21
	v_fma_f32 v10, v4, v16, -v10
	v_fma_f32 v11, v5, v17, -v11
	v_fma_f32 v4, v2, v18, v6
	v_fma_f32 v5, v3, v19, v7
	v_fma_f32 v6, v0, v16, v12
	v_fma_f32 v7, v1, v17, v13
	s_and_b64 vcc, exec, s[8:9]
	s_mov_b64 s[6:7], -1
	s_cbranch_vccz .LBB0_1642
	s_andn2_b64 vcc, exec, s[6:7]
	s_cbranch_vccz .LBB0_1643

; __device__ __forceinline__ f32x4 f16x4_to_f32(u32x2e_t w) { return __builtin_convertvector(__builtin_bit_cast(f16x4_t, w), f32x4); }
;     __device__ __forceinline__ void operator()(const f32x4 (&acc)[2][2][4][2], const Unit& u, int wr, int wc, int fr, int fq) const {
;         const int row0 = u.pm * BM + wr * 64 + fr, col0 = u.pn * BM + wc * 32 + 4 * fq;
; #pragma unroll
;         for (int ai = 0; ai < 2; ++ai) {
;             f32x4 xv[4][2][2];
; #pragma unroll
;             for (int m = 0; m < 4; ++m) { const int off = ((row0 + ai * HALF + m * 16) * 4096 + col0) * 2;
; #pragma unroll
;                 for (int bj = 0; bj < 2; ++bj)
; #pragma unroll
;                     for (int n = 0; n < 2; ++n) {
;                         if constexpr (XH) xv[m][bj][n] = f16x4_to_f32(__builtin_bit_cast(u32x2e_t, __builtin_amdgcn_raw_buffer_load_b64(X, off + (bj * HALF + n * 16) * 2, 0, 0)));
;                         else xv[m][bj][n] = __builtin_bit_cast(f32x4, __builtin_amdgcn_raw_buffer_load_b128(X, 2 * off + (bj * HALF + n * 16) * 4, 0, 0)); } }
; #pragma unroll
;             for (int m = 0; m < 4; ++m) { const int off = ((row0 + ai * HALF + m * 16) * 4096 + col0) * 2;
; #pragma unroll
;                 for (int bj = 0; bj < 2; ++bj)
; #pragma unroll
;                     for (int n = 0; n < 2; ++n) { const f32x4 r = xv[m][bj][n] * alpha + acc[ai][bj][m][n] * scl;
;                         u32x2e_t w; w.x = cvt_pk_f16(r[0], r[1]); w.y = cvt_pk_f16(r[2], r[3]);
;                         __builtin_amdgcn_raw_buffer_store_b64(w, Y, off + (bj * HALF + n * 16) * 2, 0, 0); } }
.LBB0_3429:
	v_mov_b32_e32 v141, 0
	s_lshl_b32 s10, s10, 8
	v_mbcnt_lo_u32_b32 v141, -1, v141
	v_mbcnt_hi_u32_b32 v141, -1, v141
	s_add_i32 s10, s10, s49
	v_and_or_b32 v142, v141, 15, s10
	s_lshl_b32 s10, s11, 9
	v_ashrrev_i32_e32 v141, 1, v141
	s_or_b32 s10, s10, s52
	v_lshlrev_b32_e32 v142, 13, v142
	v_and_b32_e32 v141, -8, v141
	v_add3_u32 v141, s10, v141, v142
	buffer_load_dwordx2 v[142:143], v141, s[16:19], 0 offen
	buffer_load_dwordx2 v[144:145], v141, s[16:19], 0 offen offset:32
	buffer_load_dwordx2 v[146:147], v141, s[16:19], 0 offen offset:256
	buffer_load_dwordx2 v[148:149], v141, s[16:19], 0 offen offset:288
	v_add_u32_e32 v208, 0x20000, v141
	v_add_u32_e32 v209, 0x40000, v141
	v_add_u32_e32 v210, 0x60000, v141
	buffer_load_dwordx2 v[150:151], v208, s[16:19], 0 offen
	buffer_load_dwordx2 v[152:153], v208, s[16:19], 0 offen offset:32
	buffer_load_dwordx2 v[154:155], v208, s[16:19], 0 offen offset:256
	buffer_load_dwordx2 v[156:157], v208, s[16:19], 0 offen offset:288
	buffer_load_dwordx2 v[158:159], v209, s[16:19], 0 offen
	buffer_load_dwordx2 v[160:161], v209, s[16:19], 0 offen offset:32
	buffer_load_dwordx2 v[162:163], v209, s[16:19], 0 offen offset:256
	buffer_load_dwordx2 v[164:165], v209, s[16:19], 0 offen offset:288
	buffer_load_dwordx2 v[166:167], v210, s[16:19], 0 offen
	buffer_load_dwordx2 v[168:169], v210, s[16:19], 0 offen offset:32
	buffer_load_dwordx2 v[170:171], v210, s[16:19], 0 offen offset:256
	buffer_load_dwordx2 v[172:173], v210, s[16:19], 0 offen offset:288
	s_mov_b32 s10, s18
	s_mov_b32 s11, s19
	s_andn2_b64 vcc, exec, s[4:5]
	s_mov_b64 s[4:5], -1
	s_waitcnt vmcnt(0)
	v_cvt_f32_f16_e32 v174, v143
	v_cvt_f32_f16_sdwa v175, v143 dst_sel:DWORD dst_unused:UNUSED_PAD src0_sel:WORD_1
	v_cvt_f32_f16_e32 v176, v142
	v_cvt_f32_f16_sdwa v177, v142 dst_sel:DWORD dst_unused:UNUSED_PAD src0_sel:WORD_1
	v_cvt_f32_f16_e32 v142, v145
	v_cvt_f32_f16_sdwa v143, v145 dst_sel:DWORD dst_unused:UNUSED_PAD src0_sel:WORD_1
	v_cvt_f32_f16_e32 v178, v144
	v_cvt_f32_f16_sdwa v179, v144 dst_sel:DWORD dst_unused:UNUSED_PAD src0_sel:WORD_1
	v_cvt_f32_f16_e32 v144, v147
	v_cvt_f32_f16_sdwa v145, v147 dst_sel:DWORD dst_unused:UNUSED_PAD src0_sel:WORD_1
	v_cvt_f32_f16_e32 v180, v146
	v_cvt_f32_f16_sdwa v181, v146 dst_sel:DWORD dst_unused:UNUSED_PAD src0_sel:WORD_1
	v_cvt_f32_f16_e32 v146, v149
	v_cvt_f32_f16_sdwa v147, v149 dst_sel:DWORD dst_unused:UNUSED_PAD src0_sel:WORD_1
	v_cvt_f32_f16_e32 v182, v148
	v_cvt_f32_f16_sdwa v183, v148 dst_sel:DWORD dst_unused:UNUSED_PAD src0_sel:WORD_1
	v_cvt_f32_f16_e32 v148, v151
	v_cvt_f32_f16_sdwa v149, v151 dst_sel:DWORD dst_unused:UNUSED_PAD src0_sel:WORD_1
	v_cvt_f32_f16_e32 v184, v150
	v_cvt_f32_f16_sdwa v185, v150 dst_sel:DWORD dst_unused:UNUSED_PAD src0_sel:WORD_1
	v_cvt_f32_f16_e32 v150, v153
	v_cvt_f32_f16_sdwa v151, v153 dst_sel:DWORD dst_unused:UNUSED_PAD src0_sel:WORD_1
	v_cvt_f32_f16_e32 v186, v152
	v_cvt_f32_f16_sdwa v187, v152 dst_sel:DWORD dst_unused:UNUSED_PAD src0_sel:WORD_1
	v_cvt_f32_f16_e32 v152, v155
	v_cvt_f32_f16_sdwa v153, v155 dst_sel:DWORD dst_unused:UNUSED_PAD src0_sel:WORD_1
	v_cvt_f32_f16_e32 v188, v154
	v_cvt_f32_f16_sdwa v189, v154 dst_sel:DWORD dst_unused:UNUSED_PAD src0_sel:WORD_1
	v_cvt_f32_f16_e32 v154, v157
	v_cvt_f32_f16_sdwa v155, v157 dst_sel:DWORD dst_unused:UNUSED_PAD src0_sel:WORD_1
	v_cvt_f32_f16_e32 v190, v156
	v_cvt_f32_f16_sdwa v191, v156 dst_sel:DWORD dst_unused:UNUSED_PAD src0_sel:WORD_1
	v_cvt_f32_f16_e32 v156, v159
	v_cvt_f32_f16_sdwa v157, v159 dst_sel:DWORD dst_unused:UNUSED_PAD src0_sel:WORD_1
	v_cvt_f32_f16_e32 v192, v158
	v_cvt_f32_f16_sdwa v193, v158 dst_sel:DWORD dst_unused:UNUSED_PAD src0_sel:WORD_1
	v_cvt_f32_f16_e32 v158, v161
	v_cvt_f32_f16_sdwa v159, v161 dst_sel:DWORD dst_unused:UNUSED_PAD src0_sel:WORD_1
	v_cvt_f32_f16_e32 v194, v160
	v_cvt_f32_f16_sdwa v195, v160 dst_sel:DWORD dst_unused:UNUSED_PAD src0_sel:WORD_1
	v_cvt_f32_f16_e32 v160, v163
	v_cvt_f32_f16_sdwa v161, v163 dst_sel:DWORD dst_unused:UNUSED_PAD src0_sel:WORD_1
	v_cvt_f32_f16_e32 v196, v162
	v_cvt_f32_f16_sdwa v197, v162 dst_sel:DWORD dst_unused:UNUSED_PAD src0_sel:WORD_1
	v_cvt_f32_f16_e32 v162, v165
	v_cvt_f32_f16_sdwa v163, v165 dst_sel:DWORD dst_unused:UNUSED_PAD src0_sel:WORD_1
	v_cvt_f32_f16_e32 v198, v164
	v_cvt_f32_f16_sdwa v199, v164 dst_sel:DWORD dst_unused:UNUSED_PAD src0_sel:WORD_1
	v_cvt_f32_f16_e32 v164, v167
	v_cvt_f32_f16_sdwa v165, v167 dst_sel:DWORD dst_unused:UNUSED_PAD src0_sel:WORD_1
	v_cvt_f32_f16_e32 v200, v166
	v_cvt_f32_f16_sdwa v201, v166 dst_sel:DWORD dst_unused:UNUSED_PAD src0_sel:WORD_1
	v_cvt_f32_f16_e32 v166, v169
	v_cvt_f32_f16_sdwa v167, v169 dst_sel:DWORD dst_unused:UNUSED_PAD src0_sel:WORD_1
	v_cvt_f32_f16_e32 v202, v168
	v_cvt_f32_f16_sdwa v203, v168 dst_sel:DWORD dst_unused:UNUSED_PAD src0_sel:WORD_1
	v_cvt_f32_f16_e32 v168, v171
	v_cvt_f32_f16_sdwa v169, v171 dst_sel:DWORD dst_unused:UNUSED_PAD src0_sel:WORD_1
	v_cvt_f32_f16_e32 v204, v170
	v_cvt_f32_f16_sdwa v205, v170 dst_sel:DWORD dst_unused:UNUSED_PAD src0_sel:WORD_1
	v_cvt_f32_f16_e32 v170, v173
	v_cvt_f32_f16_sdwa v171, v173 dst_sel:DWORD dst_unused:UNUSED_PAD src0_sel:WORD_1
	v_cvt_f32_f16_e32 v206, v172
	v_cvt_f32_f16_sdwa v207, v172 dst_sel:DWORD dst_unused:UNUSED_PAD src0_sel:WORD_1
	v_mul_f32_e32 v172, s12, v176
	v_mul_f32_e32 v173, s12, v177
	v_mul_f32_e32 v174, s12, v174
	v_mul_f32_e32 v175, s12, v175
	v_fma_f32 v124, v124, s14, v172
	v_fma_f32 v125, v125, s14, v173
	v_fma_f32 v126, v126, s14, v174
	v_fma_f32 v127, v127, s14, v175
	v_cvt_pk_f16_f32 v124, v124, v125
	v_cvt_pk_f16_f32 v125, v126, v127
	buffer_store_dwordx2 v[124:125], v141, s[8:11], 0 offen
	v_mul_f32_e32 v124, s12, v178
; __device__ __forceinline__ f32x4 f16x4_to_f32(u32x2e_t w) { return __builtin_convertvector(__builtin_bit_cast(f16x4_t, w), f32x4); }
;     __device__ __forceinline__ void operator()(const f32x4 (&acc)[2][2][4][2], const Unit& u, int wr, int wc, int fr, int fq) const {
;     ...
;             for (int m = 0; m < 4; ++m) { const int off = ((row0 + ai * HALF + m * 16) * 4096 + col0) * 2;
; #pragma unroll
;                 for (int bj = 0; bj < 2; ++bj)
; #pragma unroll
;                     for (int n = 0; n < 2; ++n) {
;                         if constexpr (XH) xv[m][bj][n] = f16x4_to_f32(__builtin_bit_cast(u32x2e_t, __builtin_amdgcn_raw_buffer_load_b64(X, off + (bj * HALF + n * 16) * 2, 0, 0)));
;                         else xv[m][bj][n] = __builtin_bit_cast(f32x4, __builtin_amdgcn_raw_buffer_load_b128(X, 2 * off + (bj * HALF + n * 16) * 4, 0, 0)); } }
; #pragma unroll
;             for (int m = 0; m < 4; ++m) { const int off = ((row0 + ai * HALF + m * 16) * 4096 + col0) * 2;
; #pragma unroll
;                 for (int bj = 0; bj < 2; ++bj)
; #pragma unroll
;                     for (int n = 0; n < 2; ++n) { const f32x4 r = xv[m][bj][n] * alpha + acc[ai][bj][m][n] * scl;
;                         u32x2e_t w; w.x = cvt_pk_f16(r[0], r[1]); w.y = cvt_pk_f16(r[2], r[3]);
;                         __builtin_amdgcn_raw_buffer_store_b64(w, Y, off + (bj * HALF + n * 16) * 2, 0, 0); } }
	v_mul_f32_e32 v125, s12, v179
	v_mul_f32_e32 v126, s12, v142
	v_mul_f32_e32 v127, s12, v143
	v_fma_f32 v120, v120, s14, v124
	v_fma_f32 v121, v121, s14, v125
	v_fma_f32 v122, v122, s14, v126
	v_fma_f32 v123, v123, s14, v127
	v_cvt_pk_f16_f32 v120, v120, v121
	v_cvt_pk_f16_f32 v121, v122, v123
	buffer_store_dwordx2 v[120:121], v141, s[8:11], 0 offen offset:32
	v_mul_f32_e32 v120, s12, v180
	v_mul_f32_e32 v121, s12, v181
	v_mul_f32_e32 v122, s12, v144
	v_mul_f32_e32 v123, s12, v145
	v_fma_f32 v116, v116, s14, v120
	v_fma_f32 v117, v117, s14, v121
	v_fma_f32 v118, v118, s14, v122
	v_fma_f32 v119, v119, s14, v123
	v_cvt_pk_f16_f32 v116, v116, v117
	v_cvt_pk_f16_f32 v117, v118, v119
	buffer_store_dwordx2 v[116:117], v141, s[8:11], 0 offen offset:256
	v_mul_f32_e32 v116, s12, v182
	v_mul_f32_e32 v117, s12, v183
	v_mul_f32_e32 v118, s12, v146
	v_mul_f32_e32 v119, s12, v147
	v_fma_f32 v108, v108, s14, v116
	v_fma_f32 v109, v109, s14, v117
	v_fma_f32 v110, v110, s14, v118
	v_fma_f32 v111, v111, s14, v119
	v_cvt_pk_f16_f32 v108, v108, v109
	v_cvt_pk_f16_f32 v109, v110, v111
	buffer_store_dwordx2 v[108:109], v141, s[8:11], 0 offen offset:288
	v_mul_f32_e32 v108, s12, v184
	v_mul_f32_e32 v109, s12, v185
	v_mul_f32_e32 v110, s12, v148
	v_mul_f32_e32 v111, s12, v149
	v_fma_f32 v108, v112, s14, v108
	v_fma_f32 v109, v113, s14, v109
	v_fma_f32 v110, v114, s14, v110
	v_fma_f32 v111, v115, s14, v111
	v_cvt_pk_f16_f32 v108, v108, v109
	v_cvt_pk_f16_f32 v109, v110, v111
	buffer_store_dwordx2 v[108:109], v208, s[8:11], 0 offen
	v_mul_f32_e32 v108, s12, v186
	v_mul_f32_e32 v109, s12, v187
	v_mul_f32_e32 v110, s12, v150
	v_mul_f32_e32 v111, s12, v151
	v_fma_f32 v104, v104, s14, v108
	v_fma_f32 v105, v105, s14, v109
	v_fma_f32 v106, v106, s14, v110
	v_fma_f32 v107, v107, s14, v111
	v_cvt_pk_f16_f32 v104, v104, v105
	v_cvt_pk_f16_f32 v105, v106, v107
	buffer_store_dwordx2 v[104:105], v208, s[8:11], 0 offen offset:32
	v_mul_f32_e32 v104, s12, v188
	v_mul_f32_e32 v105, s12, v189
	v_mul_f32_e32 v106, s12, v152
	v_mul_f32_e32 v107, s12, v153
	v_fma_f32 v100, v100, s14, v104
	v_fma_f32 v101, v101, s14, v105
	v_fma_f32 v102, v102, s14, v106
	v_fma_f32 v103, v103, s14, v107
	v_cvt_pk_f16_f32 v100, v100, v101
	v_cvt_pk_f16_f32 v101, v102, v103
	buffer_store_dwordx2 v[100:101], v208, s[8:11], 0 offen offset:256
	v_mul_f32_e32 v100, s12, v190
	v_mul_f32_e32 v101, s12, v191
	v_mul_f32_e32 v102, s12, v154
	v_mul_f32_e32 v103, s12, v155
	v_fma_f32 v92, v92, s14, v100
	v_fma_f32 v93, v93, s14, v101
	v_fma_f32 v94, v94, s14, v102
	v_fma_f32 v95, v95, s14, v103
	v_cvt_pk_f16_f32 v92, v92, v93
	v_cvt_pk_f16_f32 v93, v94, v95
	buffer_store_dwordx2 v[92:93], v208, s[8:11], 0 offen offset:288
	v_mul_f32_e32 v92, s12, v192
	v_mul_f32_e32 v93, s12, v193
	v_mul_f32_e32 v94, s12, v156
	v_mul_f32_e32 v95, s12, v157
	v_fma_f32 v92, v96, s14, v92
	v_fma_f32 v93, v97, s14, v93
	v_fma_f32 v94, v98, s14, v94
	v_fma_f32 v95, v99, s14, v95
	v_cvt_pk_f16_f32 v92, v92, v93
	v_cvt_pk_f16_f32 v93, v94, v95
	buffer_store_dwordx2 v[92:93], v209, s[8:11], 0 offen
	v_mul_f32_e32 v92, s12, v194
	v_mul_f32_e32 v93, s12, v195
	v_mul_f32_e32 v94, s12, v158
	v_mul_f32_e32 v95, s12, v159
	v_fma_f32 v88, v88, s14, v92
	v_fma_f32 v89, v89, s14, v93
	v_fma_f32 v90, v90, s14, v94
	v_fma_f32 v91, v91, s14, v95
	v_cvt_pk_f16_f32 v88, v88, v89
	v_cvt_pk_f16_f32 v89, v90, v91
	buffer_store_dwordx2 v[88:89], v209, s[8:11], 0 offen offset:32
	v_mul_f32_e32 v88, s12, v196
	v_mul_f32_e32 v89, s12, v197
	v_mul_f32_e32 v90, s12, v160
	v_mul_f32_e32 v91, s12, v161
	v_fma_f32 v84, v84, s14, v88
	v_fma_f32 v85, v85, s14, v89
	v_fma_f32 v86, v86, s14, v90
	v_fma_f32 v87, v87, s14, v91
	v_cvt_pk_f16_f32 v84, v84, v85
	v_cvt_pk_f16_f32 v85, v86, v87
	buffer_store_dwordx2 v[84:85], v209, s[8:11], 0 offen offset:256
	v_mul_f32_e32 v84, s12, v198
	v_mul_f32_e32 v85, s12, v199
	v_mul_f32_e32 v86, s12, v162
	v_mul_f32_e32 v87, s12, v163
	v_fma_f32 v76, v76, s14, v84
	v_fma_f32 v77, v77, s14, v85
	v_fma_f32 v78, v78, s14, v86
	v_fma_f32 v79, v79, s14, v87
	v_cvt_pk_f16_f32 v76, v76, v77
	v_cvt_pk_f16_f32 v77, v78, v79
	buffer_store_dwordx2 v[76:77], v209, s[8:11], 0 offen offset:288
	v_mul_f32_e32 v76, s12, v200
	v_mul_f32_e32 v77, s12, v201
	v_mul_f32_e32 v78, s12, v164
	v_mul_f32_e32 v79, s12, v165
	v_fma_f32 v76, v80, s14, v76
	v_fma_f32 v77, v81, s14, v77
	v_fma_f32 v78, v82, s14, v78
	v_fma_f32 v79, v83, s14, v79
	v_cvt_pk_f16_f32 v76, v76, v77
	v_cvt_pk_f16_f32 v77, v78, v79
	buffer_store_dwordx2 v[76:77], v210, s[8:11], 0 offen
	v_mul_f32_e32 v76, s12, v202
	v_mul_f32_e32 v77, s12, v203
	v_mul_f32_e32 v78, s12, v166
	v_mul_f32_e32 v79, s12, v167
	v_fma_f32 v72, v72, s14, v76
	v_fma_f32 v73, v73, s14, v77
	v_fma_f32 v74, v74, s14, v78
	v_fma_f32 v75, v75, s14, v79
	v_cvt_pk_f16_f32 v72, v72, v73
	v_cvt_pk_f16_f32 v73, v74, v75
	buffer_store_dwordx2 v[72:73], v210, s[8:11], 0 offen offset:32
	v_mul_f32_e32 v72, s12, v204
	v_mul_f32_e32 v73, s12, v205
	v_mul_f32_e32 v74, s12, v168
	v_mul_f32_e32 v75, s12, v169
	v_fma_f32 v68, v68, s14, v72
	v_fma_f32 v69, v69, s14, v73
	v_fma_f32 v70, v70, s14, v74
	v_fma_f32 v71, v71, s14, v75
	v_cvt_pk_f16_f32 v68, v68, v69
	v_cvt_pk_f16_f32 v69, v70, v71
	buffer_store_dwordx2 v[68:69], v210, s[8:11], 0 offen offset:256
	v_mul_f32_e32 v68, s12, v206
	v_mul_f32_e32 v69, s12, v207
	v_mul_f32_e32 v70, s12, v170
	v_mul_f32_e32 v71, s12, v171
	v_fma_f32 v64, v64, s14, v68
	v_fma_f32 v65, v65, s14, v69
	v_fma_f32 v66, v66, s14, v70
	v_fma_f32 v67, v67, s14, v71
	v_cvt_pk_f16_f32 v64, v64, v65
	v_cvt_pk_f16_f32 v65, v66, v67
	buffer_store_dwordx2 v[64:65], v210, s[8:11], 0 offen offset:288
	v_add_u32_e32 v144, 0x100000, v141
	buffer_load_dwordx2 v[64:65], v144, s[16:19], 0 offen
	buffer_load_dwordx2 v[66:67], v144, s[16:19], 0 offen offset:32
	buffer_load_dwordx2 v[68:69], v144, s[16:19], 0 offen offset:256
	buffer_load_dwordx2 v[70:71], v144, s[16:19], 0 offen offset:288
	v_add_u32_e32 v145, 0x120000, v141
	v_add_u32_e32 v146, 0x140000, v141
	v_add_u32_e32 v141, 0x160000, v141
	buffer_load_dwordx2 v[72:73], v145, s[16:19], 0 offen
	buffer_load_dwordx2 v[74:75], v145, s[16:19], 0 offen offset:32
	buffer_load_dwordx2 v[76:77], v145, s[16:19], 0 offen offset:256
	buffer_load_dwordx2 v[78:79], v145, s[16:19], 0 offen offset:288
	buffer_load_dwordx2 v[80:81], v146, s[16:19], 0 offen
	buffer_load_dwordx2 v[82:83], v146, s[16:19], 0 offen offset:32
	buffer_load_dwordx2 v[84:85], v146, s[16:19], 0 offen offset:256
	buffer_load_dwordx2 v[86:87], v146, s[16:19], 0 offen offset:288
	buffer_load_dwordx2 v[88:89], v141, s[16:19], 0 offen
	buffer_load_dwordx2 v[90:91], v141, s[16:19], 0 offen offset:32
	buffer_load_dwordx2 v[92:93], v141, s[16:19], 0 offen offset:256
	buffer_load_dwordx2 v[94:95], v141, s[16:19], 0 offen offset:288
	s_waitcnt vmcnt(15)
; __device__ __forceinline__ f32x4 f16x4_to_f32(u32x2e_t w) { return __builtin_convertvector(__builtin_bit_cast(f16x4_t, w), f32x4); }
;     __device__ __forceinline__ void operator()(const f32x4 (&acc)[2][2][4][2], const Unit& u, int wr, int wc, int fr, int fq) const {
;     ...
;             for (int m = 0; m < 4; ++m) { const int off = ((row0 + ai * HALF + m * 16) * 4096 + col0) * 2;
; #pragma unroll
;                 for (int bj = 0; bj < 2; ++bj)
; #pragma unroll
;                     for (int n = 0; n < 2; ++n) {
;                         if constexpr (XH) xv[m][bj][n] = f16x4_to_f32(__builtin_bit_cast(u32x2e_t, __builtin_amdgcn_raw_buffer_load_b64(X, off + (bj * HALF + n * 16) * 2, 0, 0)));
;                         else xv[m][bj][n] = __builtin_bit_cast(f32x4, __builtin_amdgcn_raw_buffer_load_b128(X, 2 * off + (bj * HALF + n * 16) * 4, 0, 0)); } }
	v_cvt_f32_f16_e32 v96, v65
	v_cvt_f32_f16_sdwa v97, v65 dst_sel:DWORD dst_unused:UNUSED_PAD src0_sel:WORD_1
	v_cvt_f32_f16_e32 v98, v64
	v_cvt_f32_f16_sdwa v99, v64 dst_sel:DWORD dst_unused:UNUSED_PAD src0_sel:WORD_1
	s_waitcnt vmcnt(14)
	v_cvt_f32_f16_e32 v64, v67
	v_cvt_f32_f16_sdwa v65, v67 dst_sel:DWORD dst_unused:UNUSED_PAD src0_sel:WORD_1
	v_cvt_f32_f16_e32 v100, v66
	v_cvt_f32_f16_sdwa v101, v66 dst_sel:DWORD dst_unused:UNUSED_PAD src0_sel:WORD_1
	s_waitcnt vmcnt(13)
	v_cvt_f32_f16_e32 v66, v69
	v_cvt_f32_f16_sdwa v67, v69 dst_sel:DWORD dst_unused:UNUSED_PAD src0_sel:WORD_1
	v_cvt_f32_f16_e32 v102, v68
	v_cvt_f32_f16_sdwa v103, v68 dst_sel:DWORD dst_unused:UNUSED_PAD src0_sel:WORD_1
	s_waitcnt vmcnt(12)
	v_cvt_f32_f16_e32 v68, v71
	v_cvt_f32_f16_sdwa v69, v71 dst_sel:DWORD dst_unused:UNUSED_PAD src0_sel:WORD_1
	v_cvt_f32_f16_e32 v104, v70
	v_cvt_f32_f16_sdwa v105, v70 dst_sel:DWORD dst_unused:UNUSED_PAD src0_sel:WORD_1
	s_waitcnt vmcnt(11)
	v_cvt_f32_f16_e32 v70, v73
	v_cvt_f32_f16_sdwa v71, v73 dst_sel:DWORD dst_unused:UNUSED_PAD src0_sel:WORD_1
	v_cvt_f32_f16_e32 v106, v72
	v_cvt_f32_f16_sdwa v107, v72 dst_sel:DWORD dst_unused:UNUSED_PAD src0_sel:WORD_1
	s_waitcnt vmcnt(10)
	v_cvt_f32_f16_e32 v72, v75
	v_cvt_f32_f16_sdwa v73, v75 dst_sel:DWORD dst_unused:UNUSED_PAD src0_sel:WORD_1
	v_cvt_f32_f16_e32 v108, v74
	v_cvt_f32_f16_sdwa v109, v74 dst_sel:DWORD dst_unused:UNUSED_PAD src0_sel:WORD_1
	s_waitcnt vmcnt(9)
	v_cvt_f32_f16_e32 v74, v77
	v_cvt_f32_f16_sdwa v75, v77 dst_sel:DWORD dst_unused:UNUSED_PAD src0_sel:WORD_1
	v_cvt_f32_f16_e32 v110, v76
	v_cvt_f32_f16_sdwa v111, v76 dst_sel:DWORD dst_unused:UNUSED_PAD src0_sel:WORD_1
	s_waitcnt vmcnt(8)
	v_cvt_f32_f16_e32 v76, v79
	v_cvt_f32_f16_sdwa v77, v79 dst_sel:DWORD dst_unused:UNUSED_PAD src0_sel:WORD_1
	v_cvt_f32_f16_e32 v112, v78
	v_cvt_f32_f16_sdwa v113, v78 dst_sel:DWORD dst_unused:UNUSED_PAD src0_sel:WORD_1
	s_waitcnt vmcnt(7)
	v_cvt_f32_f16_e32 v78, v81
	v_cvt_f32_f16_sdwa v79, v81 dst_sel:DWORD dst_unused:UNUSED_PAD src0_sel:WORD_1
	v_cvt_f32_f16_e32 v114, v80
	v_cvt_f32_f16_sdwa v115, v80 dst_sel:DWORD dst_unused:UNUSED_PAD src0_sel:WORD_1
	s_waitcnt vmcnt(6)
	v_cvt_f32_f16_e32 v80, v83
	v_cvt_f32_f16_sdwa v81, v83 dst_sel:DWORD dst_unused:UNUSED_PAD src0_sel:WORD_1
	v_cvt_f32_f16_e32 v116, v82
	v_cvt_f32_f16_sdwa v117, v82 dst_sel:DWORD dst_unused:UNUSED_PAD src0_sel:WORD_1
	s_waitcnt vmcnt(5)
	v_cvt_f32_f16_e32 v82, v85
	v_cvt_f32_f16_sdwa v83, v85 dst_sel:DWORD dst_unused:UNUSED_PAD src0_sel:WORD_1
	v_cvt_f32_f16_e32 v118, v84
	v_cvt_f32_f16_sdwa v119, v84 dst_sel:DWORD dst_unused:UNUSED_PAD src0_sel:WORD_1
	s_waitcnt vmcnt(4)
	v_cvt_f32_f16_e32 v84, v87
	v_cvt_f32_f16_sdwa v85, v87 dst_sel:DWORD dst_unused:UNUSED_PAD src0_sel:WORD_1
	v_cvt_f32_f16_e32 v120, v86
	v_cvt_f32_f16_sdwa v121, v86 dst_sel:DWORD dst_unused:UNUSED_PAD src0_sel:WORD_1
	s_waitcnt vmcnt(3)
	v_cvt_f32_f16_e32 v86, v89
	v_cvt_f32_f16_sdwa v87, v89 dst_sel:DWORD dst_unused:UNUSED_PAD src0_sel:WORD_1
	v_cvt_f32_f16_e32 v122, v88
	v_cvt_f32_f16_sdwa v123, v88 dst_sel:DWORD dst_unused:UNUSED_PAD src0_sel:WORD_1
	s_waitcnt vmcnt(2)
	v_cvt_f32_f16_e32 v88, v91
	v_cvt_f32_f16_sdwa v89, v91 dst_sel:DWORD dst_unused:UNUSED_PAD src0_sel:WORD_1
	v_cvt_f32_f16_e32 v124, v90
	v_cvt_f32_f16_sdwa v125, v90 dst_sel:DWORD dst_unused:UNUSED_PAD src0_sel:WORD_1
	s_waitcnt vmcnt(1)
	v_cvt_f32_f16_e32 v90, v93
	v_cvt_f32_f16_sdwa v91, v93 dst_sel:DWORD dst_unused:UNUSED_PAD src0_sel:WORD_1
	v_cvt_f32_f16_e32 v126, v92
	v_cvt_f32_f16_sdwa v127, v92 dst_sel:DWORD dst_unused:UNUSED_PAD src0_sel:WORD_1
	s_waitcnt vmcnt(0)
; #define PG8_BAR __builtin_amdgcn_s_barrier()
;     __device__ __forceinline__ void operator()(const f32x4 (&acc)[2][2][4][2], const Unit& u, int wr, int wc, int fr, int fq) const {
;     ...
;             for (int m = 0; m < 4; ++m) { const int off = ((row0 + ai * HALF + m * 16) * 4096 + col0) * 2;
; #pragma unroll
;                 for (int bj = 0; bj < 2; ++bj)
; #pragma unroll
;                     for (int n = 0; n < 2; ++n) { const f32x4 r = xv[m][bj][n] * alpha + acc[ai][bj][m][n] * scl;
;                         u32x2e_t w; w.x = cvt_pk_f16(r[0], r[1]); w.y = cvt_pk_f16(r[2], r[3]);
;                         __builtin_amdgcn_raw_buffer_store_b64(w, Y, off + (bj * HALF + n * 16) * 2, 0, 0); } }
;     ...
;         if (!has_next) break;
; #pragma unroll
;         for (int a = 0; a < 2; ++a)
; #pragma unroll
;             for (int b = 0; b < 2; ++b)
; #pragma unroll
;                 for (int m = 0; m < 4; ++m)
; #pragma unroll
;                     for (int n = 0; n < 2; ++n) acc[a][b][m][n] = (f32x4){0.f, 0.f, 0.f, 0.f};
;         cur = nxt; cA = nA; cB = nB; ++ui;
;         if constexpr (ALIGN_EPI) { if (wr == 1) PG8_BAR; }
	v_cvt_f32_f16_e32 v92, v95
	v_cvt_f32_f16_sdwa v93, v95 dst_sel:DWORD dst_unused:UNUSED_PAD src0_sel:WORD_1
	v_cvt_f32_f16_e32 v142, v94
	v_cvt_f32_f16_sdwa v143, v94 dst_sel:DWORD dst_unused:UNUSED_PAD src0_sel:WORD_1
	v_mul_f32_e32 v94, s12, v98
	v_mul_f32_e32 v95, s12, v99
	v_mul_f32_e32 v96, s12, v96
	v_mul_f32_e32 v97, s12, v97
	v_fma_f32 v60, v60, s14, v94
	v_fma_f32 v61, v61, s14, v95
	v_fma_f32 v62, v62, s14, v96
	v_fma_f32 v63, v63, s14, v97
	v_cvt_pk_f16_f32 v60, v60, v61
	v_cvt_pk_f16_f32 v61, v62, v63
	buffer_store_dwordx2 v[60:61], v144, s[8:11], 0 offen
	v_mul_f32_e32 v60, s12, v100
	v_mul_f32_e32 v61, s12, v101
	v_mul_f32_e32 v62, s12, v64
	v_mul_f32_e32 v63, s12, v65
	v_fma_f32 v56, v56, s14, v60
	v_fma_f32 v57, v57, s14, v61
	v_fma_f32 v58, v58, s14, v62
	v_fma_f32 v59, v59, s14, v63
	v_cvt_pk_f16_f32 v56, v56, v57
	v_cvt_pk_f16_f32 v57, v58, v59
	buffer_store_dwordx2 v[56:57], v144, s[8:11], 0 offen offset:32
	v_mul_f32_e32 v56, s12, v102
	v_mul_f32_e32 v57, s12, v103
	v_mul_f32_e32 v58, s12, v66
	v_mul_f32_e32 v59, s12, v67
	v_fma_f32 v52, v52, s14, v56
	v_fma_f32 v53, v53, s14, v57
	v_fma_f32 v54, v54, s14, v58
	v_fma_f32 v55, v55, s14, v59
	v_cvt_pk_f16_f32 v52, v52, v53
	v_cvt_pk_f16_f32 v53, v54, v55
	buffer_store_dwordx2 v[52:53], v144, s[8:11], 0 offen offset:256
	v_mul_f32_e32 v52, s12, v104
	v_mul_f32_e32 v53, s12, v105
	v_mul_f32_e32 v54, s12, v68
	v_mul_f32_e32 v55, s12, v69
	v_fma_f32 v44, v44, s14, v52
	v_fma_f32 v45, v45, s14, v53
	v_fma_f32 v46, v46, s14, v54
	v_fma_f32 v47, v47, s14, v55
	v_cvt_pk_f16_f32 v44, v44, v45
	v_cvt_pk_f16_f32 v45, v46, v47
	buffer_store_dwordx2 v[44:45], v144, s[8:11], 0 offen offset:288
	v_mul_f32_e32 v44, s12, v106
	v_mul_f32_e32 v45, s12, v107
	v_mul_f32_e32 v46, s12, v70
	v_mul_f32_e32 v47, s12, v71
	v_fma_f32 v44, v48, s14, v44
	v_fma_f32 v45, v49, s14, v45
	v_fma_f32 v46, v50, s14, v46
	v_fma_f32 v47, v51, s14, v47
	v_cvt_pk_f16_f32 v44, v44, v45
	v_cvt_pk_f16_f32 v45, v46, v47
	buffer_store_dwordx2 v[44:45], v145, s[8:11], 0 offen
	v_mul_f32_e32 v44, s12, v108
	v_mul_f32_e32 v45, s12, v109
	v_mul_f32_e32 v46, s12, v72
	v_mul_f32_e32 v47, s12, v73
	v_fma_f32 v40, v40, s14, v44
	v_fma_f32 v41, v41, s14, v45
	v_fma_f32 v42, v42, s14, v46
	v_fma_f32 v43, v43, s14, v47
	v_cvt_pk_f16_f32 v40, v40, v41
	v_cvt_pk_f16_f32 v41, v42, v43
	buffer_store_dwordx2 v[40:41], v145, s[8:11], 0 offen offset:32
	v_mul_f32_e32 v40, s12, v110
	v_mul_f32_e32 v41, s12, v111
	v_mul_f32_e32 v42, s12, v74
	v_mul_f32_e32 v43, s12, v75
	v_fma_f32 v36, v36, s14, v40
	v_fma_f32 v37, v37, s14, v41
	v_fma_f32 v38, v38, s14, v42
	v_fma_f32 v39, v39, s14, v43
	v_cvt_pk_f16_f32 v36, v36, v37
	v_cvt_pk_f16_f32 v37, v38, v39
	buffer_store_dwordx2 v[36:37], v145, s[8:11], 0 offen offset:256
	v_mul_f32_e32 v36, s12, v112
	v_mul_f32_e32 v37, s12, v113
	v_mul_f32_e32 v38, s12, v76
	v_mul_f32_e32 v39, s12, v77
	v_fma_f32 v28, v28, s14, v36
	v_fma_f32 v29, v29, s14, v37
	v_fma_f32 v30, v30, s14, v38
	v_fma_f32 v31, v31, s14, v39
	v_cvt_pk_f16_f32 v28, v28, v29
	v_cvt_pk_f16_f32 v29, v30, v31
	buffer_store_dwordx2 v[28:29], v145, s[8:11], 0 offen offset:288
	v_mul_f32_e32 v28, s12, v114
	v_mul_f32_e32 v29, s12, v115
	v_mul_f32_e32 v30, s12, v78
	v_mul_f32_e32 v31, s12, v79
	v_fma_f32 v28, v32, s14, v28
	v_fma_f32 v29, v33, s14, v29
	v_fma_f32 v30, v34, s14, v30
	v_fma_f32 v31, v35, s14, v31
	v_cvt_pk_f16_f32 v28, v28, v29
	v_cvt_pk_f16_f32 v29, v30, v31
	buffer_store_dwordx2 v[28:29], v146, s[8:11], 0 offen
	v_mul_f32_e32 v28, s12, v116
	v_mul_f32_e32 v29, s12, v117
	v_mul_f32_e32 v30, s12, v80
	v_mul_f32_e32 v31, s12, v81
	v_fma_f32 v24, v24, s14, v28
	v_fma_f32 v25, v25, s14, v29
	v_fma_f32 v26, v26, s14, v30
	v_fma_f32 v27, v27, s14, v31
	v_cvt_pk_f16_f32 v24, v24, v25
	v_cvt_pk_f16_f32 v25, v26, v27
	buffer_store_dwordx2 v[24:25], v146, s[8:11], 0 offen offset:32
	v_mul_f32_e32 v24, s12, v118
	v_mul_f32_e32 v25, s12, v119
	v_mul_f32_e32 v26, s12, v82
	v_mul_f32_e32 v27, s12, v83
	v_fma_f32 v20, v20, s14, v24
	v_fma_f32 v21, v21, s14, v25
	v_fma_f32 v22, v22, s14, v26
	v_fma_f32 v23, v23, s14, v27
	v_cvt_pk_f16_f32 v20, v20, v21
	v_cvt_pk_f16_f32 v21, v22, v23
	buffer_store_dwordx2 v[20:21], v146, s[8:11], 0 offen offset:256
	v_mul_f32_e32 v20, s12, v120
	v_mul_f32_e32 v21, s12, v121
	v_mul_f32_e32 v22, s12, v84
	v_mul_f32_e32 v23, s12, v85
	v_fma_f32 v12, v12, s14, v20
	v_fma_f32 v13, v13, s14, v21
	v_fma_f32 v14, v14, s14, v22
	v_fma_f32 v15, v15, s14, v23
	v_cvt_pk_f16_f32 v12, v12, v13
	v_cvt_pk_f16_f32 v13, v14, v15
	buffer_store_dwordx2 v[12:13], v146, s[8:11], 0 offen offset:288
	v_mul_f32_e32 v12, s12, v122
	v_mul_f32_e32 v13, s12, v123
	v_mul_f32_e32 v14, s12, v86
	v_mul_f32_e32 v15, s12, v87
	v_fma_f32 v12, v16, s14, v12
	v_fma_f32 v13, v17, s14, v13
	v_fma_f32 v14, v18, s14, v14
	v_fma_f32 v15, v19, s14, v15
	v_cvt_pk_f16_f32 v12, v12, v13
	v_cvt_pk_f16_f32 v13, v14, v15
	buffer_store_dwordx2 v[12:13], v141, s[8:11], 0 offen
	v_mul_f32_e32 v12, s12, v124
	v_mul_f32_e32 v13, s12, v125
	v_mul_f32_e32 v14, s12, v88
	v_mul_f32_e32 v15, s12, v89
	v_fma_f32 v8, v8, s14, v12
	v_fma_f32 v9, v9, s14, v13
	v_fma_f32 v10, v10, s14, v14
	v_fma_f32 v11, v11, s14, v15
	v_cvt_pk_f16_f32 v8, v8, v9
	v_cvt_pk_f16_f32 v9, v10, v11
	buffer_store_dwordx2 v[8:9], v141, s[8:11], 0 offen offset:32
	v_mul_f32_e32 v8, s12, v126
	v_mul_f32_e32 v9, s12, v127
	v_mul_f32_e32 v10, s12, v90
	v_mul_f32_e32 v11, s12, v91
	v_fma_f32 v4, v4, s14, v8
	v_fma_f32 v5, v5, s14, v9
	v_fma_f32 v6, v6, s14, v10
	v_fma_f32 v7, v7, s14, v11
	v_cvt_pk_f16_f32 v4, v4, v5
	v_cvt_pk_f16_f32 v5, v6, v7
	buffer_store_dwordx2 v[4:5], v141, s[8:11], 0 offen offset:256
	v_mul_f32_e32 v4, s12, v142
	v_mul_f32_e32 v5, s12, v143
	v_mul_f32_e32 v6, s12, v92
	v_mul_f32_e32 v7, s12, v93
	v_fma_f32 v0, v0, s14, v4
	v_fma_f32 v1, v1, s14, v5
	v_fma_f32 v2, v2, s14, v6
	v_fma_f32 v3, v3, s14, v7
	v_cvt_pk_f16_f32 v0, v0, v1
	v_cvt_pk_f16_f32 v1, v2, v3
	buffer_store_dwordx2 v[0:1], v141, s[8:11], 0 offen offset:288
	s_cbranch_vccnz .LBB0_3418
	s_andn2_b64 vcc, exec, s[2:3]
	s_cbranch_vccnz .LBB0_3417
	s_barrier
	s_branch .LBB0_3417

; __device__ __forceinline__ f32x4 f16x4_to_f32(u32x2e_t w) { return __builtin_convertvector(__builtin_bit_cast(f16x4_t, w), f32x4); }
;     __device__ __forceinline__ void operator()(const f32x4 (&acc)[2][2][4][2], const Unit& u, int wr, int wc, int fr, int fq) const {
;         const int row0 = u.pm * BM + wr * 64 + fr, col0 = u.pn * BM + wc * 32 + 4 * fq;
; #pragma unroll
;         for (int ai = 0; ai < 2; ++ai) {
;             f32x4 xv[4][2][2];
; #pragma unroll
;             for (int m = 0; m < 4; ++m) { const int off = ((row0 + ai * HALF + m * 16) * 4096 + col0) * 2;
; #pragma unroll
;                 for (int bj = 0; bj < 2; ++bj)
; #pragma unroll
;                     for (int n = 0; n < 2; ++n) {
;                         if constexpr (XH) xv[m][bj][n] = f16x4_to_f32(__builtin_bit_cast(u32x2e_t, __builtin_amdgcn_raw_buffer_load_b64(X, off + (bj * HALF + n * 16) * 2, 0, 0)));
;                         else xv[m][bj][n] = __builtin_bit_cast(f32x4, __builtin_amdgcn_raw_buffer_load_b128(X, 2 * off + (bj * HALF + n * 16) * 4, 0, 0)); } }
; #pragma unroll
;             for (int m = 0; m < 4; ++m) { const int off = ((row0 + ai * HALF + m * 16) * 4096 + col0) * 2;
; #pragma unroll
;                 for (int bj = 0; bj < 2; ++bj)
; #pragma unroll
;                     for (int n = 0; n < 2; ++n) { const f32x4 r = xv[m][bj][n] * alpha + acc[ai][bj][m][n] * scl;
;                         u32x2e_t w; w.x = cvt_pk_f16(r[0], r[1]); w.y = cvt_pk_f16(r[2], r[3]);
;                         __builtin_amdgcn_raw_buffer_store_b64(w, Y, off + (bj * HALF + n * 16) * 2, 0, 0); } }
.LBB0_3643:
	v_mov_b32_e32 v141, 0
	s_lshl_b32 s10, s49, 8
	v_mbcnt_lo_u32_b32 v141, -1, v141
	v_mbcnt_hi_u32_b32 v141, -1, v141
	s_add_i32 s10, s10, s41
	v_and_or_b32 v142, v141, 15, s10
	s_lshl_b32 s10, s50, 9
	v_ashrrev_i32_e32 v141, 1, v141
	s_or_b32 s10, s10, s44
	v_lshlrev_b32_e32 v142, 13, v142
	v_and_b32_e32 v141, -8, v141
	v_add3_u32 v141, s10, v141, v142
	buffer_load_dwordx2 v[142:143], v141, s[16:19], 0 offen
	buffer_load_dwordx2 v[144:145], v141, s[16:19], 0 offen offset:32
	buffer_load_dwordx2 v[146:147], v141, s[16:19], 0 offen offset:256
	buffer_load_dwordx2 v[148:149], v141, s[16:19], 0 offen offset:288
	v_add_u32_e32 v208, 0x20000, v141
	v_add_u32_e32 v209, 0x40000, v141
	v_add_u32_e32 v210, 0x60000, v141
	buffer_load_dwordx2 v[150:151], v208, s[16:19], 0 offen
	buffer_load_dwordx2 v[152:153], v208, s[16:19], 0 offen offset:32
	buffer_load_dwordx2 v[154:155], v208, s[16:19], 0 offen offset:256
	buffer_load_dwordx2 v[156:157], v208, s[16:19], 0 offen offset:288
	buffer_load_dwordx2 v[158:159], v209, s[16:19], 0 offen
	buffer_load_dwordx2 v[160:161], v209, s[16:19], 0 offen offset:32
	buffer_load_dwordx2 v[162:163], v209, s[16:19], 0 offen offset:256
	buffer_load_dwordx2 v[164:165], v209, s[16:19], 0 offen offset:288
	buffer_load_dwordx2 v[166:167], v210, s[16:19], 0 offen
	buffer_load_dwordx2 v[168:169], v210, s[16:19], 0 offen offset:32
	buffer_load_dwordx2 v[170:171], v210, s[16:19], 0 offen offset:256
	buffer_load_dwordx2 v[172:173], v210, s[16:19], 0 offen offset:288
	s_mov_b32 s10, s18
	s_mov_b32 s11, s19
	s_and_b64 vcc, exec, s[4:5]
	s_mov_b64 s[4:5], -1
	s_waitcnt vmcnt(0)
	v_cvt_f32_f16_e32 v174, v143
	v_cvt_f32_f16_sdwa v175, v143 dst_sel:DWORD dst_unused:UNUSED_PAD src0_sel:WORD_1
	v_cvt_f32_f16_e32 v176, v142
	v_cvt_f32_f16_sdwa v177, v142 dst_sel:DWORD dst_unused:UNUSED_PAD src0_sel:WORD_1
	v_cvt_f32_f16_e32 v142, v145
	v_cvt_f32_f16_sdwa v143, v145 dst_sel:DWORD dst_unused:UNUSED_PAD src0_sel:WORD_1
	v_cvt_f32_f16_e32 v178, v144
	v_cvt_f32_f16_sdwa v179, v144 dst_sel:DWORD dst_unused:UNUSED_PAD src0_sel:WORD_1
	v_cvt_f32_f16_e32 v144, v147
	v_cvt_f32_f16_sdwa v145, v147 dst_sel:DWORD dst_unused:UNUSED_PAD src0_sel:WORD_1
	v_cvt_f32_f16_e32 v180, v146
	v_cvt_f32_f16_sdwa v181, v146 dst_sel:DWORD dst_unused:UNUSED_PAD src0_sel:WORD_1
	v_cvt_f32_f16_e32 v146, v149
	v_cvt_f32_f16_sdwa v147, v149 dst_sel:DWORD dst_unused:UNUSED_PAD src0_sel:WORD_1
	v_cvt_f32_f16_e32 v182, v148
	v_cvt_f32_f16_sdwa v183, v148 dst_sel:DWORD dst_unused:UNUSED_PAD src0_sel:WORD_1
	v_cvt_f32_f16_e32 v148, v151
	v_cvt_f32_f16_sdwa v149, v151 dst_sel:DWORD dst_unused:UNUSED_PAD src0_sel:WORD_1
	v_cvt_f32_f16_e32 v184, v150
	v_cvt_f32_f16_sdwa v185, v150 dst_sel:DWORD dst_unused:UNUSED_PAD src0_sel:WORD_1
	v_cvt_f32_f16_e32 v150, v153
	v_cvt_f32_f16_sdwa v151, v153 dst_sel:DWORD dst_unused:UNUSED_PAD src0_sel:WORD_1
	v_cvt_f32_f16_e32 v186, v152
	v_cvt_f32_f16_sdwa v187, v152 dst_sel:DWORD dst_unused:UNUSED_PAD src0_sel:WORD_1
	v_cvt_f32_f16_e32 v152, v155
	v_cvt_f32_f16_sdwa v153, v155 dst_sel:DWORD dst_unused:UNUSED_PAD src0_sel:WORD_1
	v_cvt_f32_f16_e32 v188, v154
	v_cvt_f32_f16_sdwa v189, v154 dst_sel:DWORD dst_unused:UNUSED_PAD src0_sel:WORD_1
	v_cvt_f32_f16_e32 v154, v157
	v_cvt_f32_f16_sdwa v155, v157 dst_sel:DWORD dst_unused:UNUSED_PAD src0_sel:WORD_1
	v_cvt_f32_f16_e32 v190, v156
	v_cvt_f32_f16_sdwa v191, v156 dst_sel:DWORD dst_unused:UNUSED_PAD src0_sel:WORD_1
	v_cvt_f32_f16_e32 v156, v159
	v_cvt_f32_f16_sdwa v157, v159 dst_sel:DWORD dst_unused:UNUSED_PAD src0_sel:WORD_1
	v_cvt_f32_f16_e32 v192, v158
	v_cvt_f32_f16_sdwa v193, v158 dst_sel:DWORD dst_unused:UNUSED_PAD src0_sel:WORD_1
	v_cvt_f32_f16_e32 v158, v161
	v_cvt_f32_f16_sdwa v159, v161 dst_sel:DWORD dst_unused:UNUSED_PAD src0_sel:WORD_1
	v_cvt_f32_f16_e32 v194, v160
	v_cvt_f32_f16_sdwa v195, v160 dst_sel:DWORD dst_unused:UNUSED_PAD src0_sel:WORD_1
	v_cvt_f32_f16_e32 v160, v163
	v_cvt_f32_f16_sdwa v161, v163 dst_sel:DWORD dst_unused:UNUSED_PAD src0_sel:WORD_1
	v_cvt_f32_f16_e32 v196, v162
	v_cvt_f32_f16_sdwa v197, v162 dst_sel:DWORD dst_unused:UNUSED_PAD src0_sel:WORD_1
	v_cvt_f32_f16_e32 v162, v165
	v_cvt_f32_f16_sdwa v163, v165 dst_sel:DWORD dst_unused:UNUSED_PAD src0_sel:WORD_1
	v_cvt_f32_f16_e32 v198, v164
	v_cvt_f32_f16_sdwa v199, v164 dst_sel:DWORD dst_unused:UNUSED_PAD src0_sel:WORD_1
	v_cvt_f32_f16_e32 v164, v167
	v_cvt_f32_f16_sdwa v165, v167 dst_sel:DWORD dst_unused:UNUSED_PAD src0_sel:WORD_1
	v_cvt_f32_f16_e32 v200, v166
	v_cvt_f32_f16_sdwa v201, v166 dst_sel:DWORD dst_unused:UNUSED_PAD src0_sel:WORD_1
	v_cvt_f32_f16_e32 v166, v169
	v_cvt_f32_f16_sdwa v167, v169 dst_sel:DWORD dst_unused:UNUSED_PAD src0_sel:WORD_1
	v_cvt_f32_f16_e32 v202, v168
	v_cvt_f32_f16_sdwa v203, v168 dst_sel:DWORD dst_unused:UNUSED_PAD src0_sel:WORD_1
	v_cvt_f32_f16_e32 v168, v171
	v_cvt_f32_f16_sdwa v169, v171 dst_sel:DWORD dst_unused:UNUSED_PAD src0_sel:WORD_1
	v_cvt_f32_f16_e32 v204, v170
	v_cvt_f32_f16_sdwa v205, v170 dst_sel:DWORD dst_unused:UNUSED_PAD src0_sel:WORD_1
	v_cvt_f32_f16_e32 v170, v173
	v_cvt_f32_f16_sdwa v171, v173 dst_sel:DWORD dst_unused:UNUSED_PAD src0_sel:WORD_1
	v_cvt_f32_f16_e32 v206, v172
	v_cvt_f32_f16_sdwa v207, v172 dst_sel:DWORD dst_unused:UNUSED_PAD src0_sel:WORD_1
	v_mul_f32_e32 v172, s14, v176
	v_mul_f32_e32 v173, s14, v177
	v_mul_f32_e32 v174, s14, v174
	v_mul_f32_e32 v175, s14, v175
	v_fma_f32 v124, v124, s20, v172
	v_fma_f32 v125, v125, s20, v173
	v_fma_f32 v126, v126, s20, v174
	v_fma_f32 v127, v127, s20, v175
	v_cvt_pk_f16_f32 v124, v124, v125
	v_cvt_pk_f16_f32 v125, v126, v127
	buffer_store_dwordx2 v[124:125], v141, s[8:11], 0 offen
	v_mul_f32_e32 v124, s14, v178
; __device__ __forceinline__ f32x4 f16x4_to_f32(u32x2e_t w) { return __builtin_convertvector(__builtin_bit_cast(f16x4_t, w), f32x4); }
;     __device__ __forceinline__ void operator()(const f32x4 (&acc)[2][2][4][2], const Unit& u, int wr, int wc, int fr, int fq) const {
;     ...
;             for (int m = 0; m < 4; ++m) { const int off = ((row0 + ai * HALF + m * 16) * 4096 + col0) * 2;
; #pragma unroll
;                 for (int bj = 0; bj < 2; ++bj)
; #pragma unroll
;                     for (int n = 0; n < 2; ++n) {
;                         if constexpr (XH) xv[m][bj][n] = f16x4_to_f32(__builtin_bit_cast(u32x2e_t, __builtin_amdgcn_raw_buffer_load_b64(X, off + (bj * HALF + n * 16) * 2, 0, 0)));
;                         else xv[m][bj][n] = __builtin_bit_cast(f32x4, __builtin_amdgcn_raw_buffer_load_b128(X, 2 * off + (bj * HALF + n * 16) * 4, 0, 0)); } }
;     ...
;             for (int m = 0; m < 4; ++m) { const int off = ((row0 + ai * HALF + m * 16) * 4096 + col0) * 2;
; #pragma unroll
;                 for (int bj = 0; bj < 2; ++bj)
; #pragma unroll
;                     for (int n = 0; n < 2; ++n) { const f32x4 r = xv[m][bj][n] * alpha + acc[ai][bj][m][n] * scl;
;                         u32x2e_t w; w.x = cvt_pk_f16(r[0], r[1]); w.y = cvt_pk_f16(r[2], r[3]);
;                         __builtin_amdgcn_raw_buffer_store_b64(w, Y, off + (bj * HALF + n * 16) * 2, 0, 0); } }
	v_mul_f32_e32 v125, s14, v179
	v_mul_f32_e32 v126, s14, v142
	v_mul_f32_e32 v127, s14, v143
	v_fma_f32 v120, v120, s20, v124
	v_fma_f32 v121, v121, s20, v125
	v_fma_f32 v122, v122, s20, v126
	v_fma_f32 v123, v123, s20, v127
	v_cvt_pk_f16_f32 v120, v120, v121
	v_cvt_pk_f16_f32 v121, v122, v123
	buffer_store_dwordx2 v[120:121], v141, s[8:11], 0 offen offset:32
	v_mul_f32_e32 v120, s14, v180
	v_mul_f32_e32 v121, s14, v181
	v_mul_f32_e32 v122, s14, v144
	v_mul_f32_e32 v123, s14, v145
	v_fma_f32 v116, v116, s20, v120
	v_fma_f32 v117, v117, s20, v121
	v_fma_f32 v118, v118, s20, v122
	v_fma_f32 v119, v119, s20, v123
	v_cvt_pk_f16_f32 v116, v116, v117
	v_cvt_pk_f16_f32 v117, v118, v119
	buffer_store_dwordx2 v[116:117], v141, s[8:11], 0 offen offset:256
	v_mul_f32_e32 v116, s14, v182
	v_mul_f32_e32 v117, s14, v183
	v_mul_f32_e32 v118, s14, v146
	v_mul_f32_e32 v119, s14, v147
	v_fma_f32 v108, v108, s20, v116
	v_fma_f32 v109, v109, s20, v117
	v_fma_f32 v110, v110, s20, v118
	v_fma_f32 v111, v111, s20, v119
	v_cvt_pk_f16_f32 v108, v108, v109
	v_cvt_pk_f16_f32 v109, v110, v111
	buffer_store_dwordx2 v[108:109], v141, s[8:11], 0 offen offset:288
	v_mul_f32_e32 v108, s14, v184
	v_mul_f32_e32 v109, s14, v185
	v_mul_f32_e32 v110, s14, v148
	v_mul_f32_e32 v111, s14, v149
	v_fma_f32 v108, v112, s20, v108
	v_fma_f32 v109, v113, s20, v109
	v_fma_f32 v110, v114, s20, v110
	v_fma_f32 v111, v115, s20, v111
	v_cvt_pk_f16_f32 v108, v108, v109
	v_cvt_pk_f16_f32 v109, v110, v111
	buffer_store_dwordx2 v[108:109], v208, s[8:11], 0 offen
	v_mul_f32_e32 v108, s14, v186
	v_mul_f32_e32 v109, s14, v187
	v_mul_f32_e32 v110, s14, v150
	v_mul_f32_e32 v111, s14, v151
	v_fma_f32 v104, v104, s20, v108
	v_fma_f32 v105, v105, s20, v109
	v_fma_f32 v106, v106, s20, v110
	v_fma_f32 v107, v107, s20, v111
	v_cvt_pk_f16_f32 v104, v104, v105
	v_cvt_pk_f16_f32 v105, v106, v107
	buffer_store_dwordx2 v[104:105], v208, s[8:11], 0 offen offset:32
	v_mul_f32_e32 v104, s14, v188
	v_mul_f32_e32 v105, s14, v189
	v_mul_f32_e32 v106, s14, v152
	v_mul_f32_e32 v107, s14, v153
	v_fma_f32 v100, v100, s20, v104
	v_fma_f32 v101, v101, s20, v105
	v_fma_f32 v102, v102, s20, v106
	v_fma_f32 v103, v103, s20, v107
	v_cvt_pk_f16_f32 v100, v100, v101
	v_cvt_pk_f16_f32 v101, v102, v103
	buffer_store_dwordx2 v[100:101], v208, s[8:11], 0 offen offset:256
	v_mul_f32_e32 v100, s14, v190
	v_mul_f32_e32 v101, s14, v191
	v_mul_f32_e32 v102, s14, v154
	v_mul_f32_e32 v103, s14, v155
	v_fma_f32 v92, v92, s20, v100
	v_fma_f32 v93, v93, s20, v101
	v_fma_f32 v94, v94, s20, v102
	v_fma_f32 v95, v95, s20, v103
	v_cvt_pk_f16_f32 v92, v92, v93
	v_cvt_pk_f16_f32 v93, v94, v95
	buffer_store_dwordx2 v[92:93], v208, s[8:11], 0 offen offset:288
	v_mul_f32_e32 v92, s14, v192
	v_mul_f32_e32 v93, s14, v193
	v_mul_f32_e32 v94, s14, v156
	v_mul_f32_e32 v95, s14, v157
	v_fma_f32 v92, v96, s20, v92
	v_fma_f32 v93, v97, s20, v93
	v_fma_f32 v94, v98, s20, v94
	v_fma_f32 v95, v99, s20, v95
	v_cvt_pk_f16_f32 v92, v92, v93
	v_cvt_pk_f16_f32 v93, v94, v95
	buffer_store_dwordx2 v[92:93], v209, s[8:11], 0 offen
	v_mul_f32_e32 v92, s14, v194
	v_mul_f32_e32 v93, s14, v195
	v_mul_f32_e32 v94, s14, v158
	v_mul_f32_e32 v95, s14, v159
	v_fma_f32 v88, v88, s20, v92
	v_fma_f32 v89, v89, s20, v93
	v_fma_f32 v90, v90, s20, v94
	v_fma_f32 v91, v91, s20, v95
	v_cvt_pk_f16_f32 v88, v88, v89
	v_cvt_pk_f16_f32 v89, v90, v91
	buffer_store_dwordx2 v[88:89], v209, s[8:11], 0 offen offset:32
	v_mul_f32_e32 v88, s14, v196
	v_mul_f32_e32 v89, s14, v197
	v_mul_f32_e32 v90, s14, v160
	v_mul_f32_e32 v91, s14, v161
	v_fma_f32 v84, v84, s20, v88
	v_fma_f32 v85, v85, s20, v89
	v_fma_f32 v86, v86, s20, v90
	v_fma_f32 v87, v87, s20, v91
	v_cvt_pk_f16_f32 v84, v84, v85
	v_cvt_pk_f16_f32 v85, v86, v87
	buffer_store_dwordx2 v[84:85], v209, s[8:11], 0 offen offset:256
	v_mul_f32_e32 v84, s14, v198
	v_mul_f32_e32 v85, s14, v199
	v_mul_f32_e32 v86, s14, v162
	v_mul_f32_e32 v87, s14, v163
	v_fma_f32 v76, v76, s20, v84
	v_fma_f32 v77, v77, s20, v85
	v_fma_f32 v78, v78, s20, v86
	v_fma_f32 v79, v79, s20, v87
	v_cvt_pk_f16_f32 v76, v76, v77
	v_cvt_pk_f16_f32 v77, v78, v79
	buffer_store_dwordx2 v[76:77], v209, s[8:11], 0 offen offset:288
	v_mul_f32_e32 v76, s14, v200
	v_mul_f32_e32 v77, s14, v201
	v_mul_f32_e32 v78, s14, v164
	v_mul_f32_e32 v79, s14, v165
	v_fma_f32 v76, v80, s20, v76
	v_fma_f32 v77, v81, s20, v77
	v_fma_f32 v78, v82, s20, v78
	v_fma_f32 v79, v83, s20, v79
	v_cvt_pk_f16_f32 v76, v76, v77
	v_cvt_pk_f16_f32 v77, v78, v79
	buffer_store_dwordx2 v[76:77], v210, s[8:11], 0 offen
	v_mul_f32_e32 v76, s14, v202
	v_mul_f32_e32 v77, s14, v203
	v_mul_f32_e32 v78, s14, v166
	v_mul_f32_e32 v79, s14, v167
	v_fma_f32 v72, v72, s20, v76
	v_fma_f32 v73, v73, s20, v77
	v_fma_f32 v74, v74, s20, v78
	v_fma_f32 v75, v75, s20, v79
	v_cvt_pk_f16_f32 v72, v72, v73
	v_cvt_pk_f16_f32 v73, v74, v75
	buffer_store_dwordx2 v[72:73], v210, s[8:11], 0 offen offset:32
	v_mul_f32_e32 v72, s14, v204
	v_mul_f32_e32 v73, s14, v205
	v_mul_f32_e32 v74, s14, v168
	v_mul_f32_e32 v75, s14, v169
	v_fma_f32 v68, v68, s20, v72
	v_fma_f32 v69, v69, s20, v73
	v_fma_f32 v70, v70, s20, v74
	v_fma_f32 v71, v71, s20, v75
	v_cvt_pk_f16_f32 v68, v68, v69
	v_cvt_pk_f16_f32 v69, v70, v71
	buffer_store_dwordx2 v[68:69], v210, s[8:11], 0 offen offset:256
	v_mul_f32_e32 v68, s14, v206
	v_mul_f32_e32 v69, s14, v207
	v_mul_f32_e32 v70, s14, v170
	v_mul_f32_e32 v71, s14, v171
	v_fma_f32 v64, v64, s20, v68
	v_fma_f32 v65, v65, s20, v69
	v_fma_f32 v66, v66, s20, v70
	v_fma_f32 v67, v67, s20, v71
	v_cvt_pk_f16_f32 v64, v64, v65
	v_cvt_pk_f16_f32 v65, v66, v67
	buffer_store_dwordx2 v[64:65], v210, s[8:11], 0 offen offset:288
	v_add_u32_e32 v144, 0x100000, v141
	buffer_load_dwordx2 v[64:65], v144, s[16:19], 0 offen
	buffer_load_dwordx2 v[66:67], v144, s[16:19], 0 offen offset:32
	buffer_load_dwordx2 v[68:69], v144, s[16:19], 0 offen offset:256
	buffer_load_dwordx2 v[70:71], v144, s[16:19], 0 offen offset:288
	v_add_u32_e32 v145, 0x120000, v141
	v_add_u32_e32 v146, 0x140000, v141
	v_add_u32_e32 v141, 0x160000, v141
	buffer_load_dwordx2 v[72:73], v145, s[16:19], 0 offen
	buffer_load_dwordx2 v[74:75], v145, s[16:19], 0 offen offset:32
	buffer_load_dwordx2 v[76:77], v145, s[16:19], 0 offen offset:256
	buffer_load_dwordx2 v[78:79], v145, s[16:19], 0 offen offset:288
	buffer_load_dwordx2 v[80:81], v146, s[16:19], 0 offen
	buffer_load_dwordx2 v[82:83], v146, s[16:19], 0 offen offset:32
	buffer_load_dwordx2 v[84:85], v146, s[16:19], 0 offen offset:256
	buffer_load_dwordx2 v[86:87], v146, s[16:19], 0 offen offset:288
	buffer_load_dwordx2 v[88:89], v141, s[16:19], 0 offen
	buffer_load_dwordx2 v[90:91], v141, s[16:19], 0 offen offset:32
	buffer_load_dwordx2 v[92:93], v141, s[16:19], 0 offen offset:256
	buffer_load_dwordx2 v[94:95], v141, s[16:19], 0 offen offset:288
	s_waitcnt vmcnt(15)
; __device__ __forceinline__ f32x4 f16x4_to_f32(u32x2e_t w) { return __builtin_convertvector(__builtin_bit_cast(f16x4_t, w), f32x4); }
;     __device__ __forceinline__ void operator()(const f32x4 (&acc)[2][2][4][2], const Unit& u, int wr, int wc, int fr, int fq) const {
;     ...
;             for (int m = 0; m < 4; ++m) { const int off = ((row0 + ai * HALF + m * 16) * 4096 + col0) * 2;
; #pragma unroll
;                 for (int bj = 0; bj < 2; ++bj)
; #pragma unroll
;                     for (int n = 0; n < 2; ++n) {
;                         if constexpr (XH) xv[m][bj][n] = f16x4_to_f32(__builtin_bit_cast(u32x2e_t, __builtin_amdgcn_raw_buffer_load_b64(X, off + (bj * HALF + n * 16) * 2, 0, 0)));
;                         else xv[m][bj][n] = __builtin_bit_cast(f32x4, __builtin_amdgcn_raw_buffer_load_b128(X, 2 * off + (bj * HALF + n * 16) * 4, 0, 0)); } }
	v_cvt_f32_f16_e32 v96, v65
	v_cvt_f32_f16_sdwa v97, v65 dst_sel:DWORD dst_unused:UNUSED_PAD src0_sel:WORD_1
	v_cvt_f32_f16_e32 v98, v64
	v_cvt_f32_f16_sdwa v99, v64 dst_sel:DWORD dst_unused:UNUSED_PAD src0_sel:WORD_1
	s_waitcnt vmcnt(14)
	v_cvt_f32_f16_e32 v64, v67
	v_cvt_f32_f16_sdwa v65, v67 dst_sel:DWORD dst_unused:UNUSED_PAD src0_sel:WORD_1
	v_cvt_f32_f16_e32 v100, v66
	v_cvt_f32_f16_sdwa v101, v66 dst_sel:DWORD dst_unused:UNUSED_PAD src0_sel:WORD_1
	s_waitcnt vmcnt(13)
	v_cvt_f32_f16_e32 v66, v69
	v_cvt_f32_f16_sdwa v67, v69 dst_sel:DWORD dst_unused:UNUSED_PAD src0_sel:WORD_1
	v_cvt_f32_f16_e32 v102, v68
	v_cvt_f32_f16_sdwa v103, v68 dst_sel:DWORD dst_unused:UNUSED_PAD src0_sel:WORD_1
	s_waitcnt vmcnt(12)
	v_cvt_f32_f16_e32 v68, v71
	v_cvt_f32_f16_sdwa v69, v71 dst_sel:DWORD dst_unused:UNUSED_PAD src0_sel:WORD_1
	v_cvt_f32_f16_e32 v104, v70
	v_cvt_f32_f16_sdwa v105, v70 dst_sel:DWORD dst_unused:UNUSED_PAD src0_sel:WORD_1
	s_waitcnt vmcnt(11)
	v_cvt_f32_f16_e32 v70, v73
	v_cvt_f32_f16_sdwa v71, v73 dst_sel:DWORD dst_unused:UNUSED_PAD src0_sel:WORD_1
	v_cvt_f32_f16_e32 v106, v72
	v_cvt_f32_f16_sdwa v107, v72 dst_sel:DWORD dst_unused:UNUSED_PAD src0_sel:WORD_1
	s_waitcnt vmcnt(10)
	v_cvt_f32_f16_e32 v72, v75
	v_cvt_f32_f16_sdwa v73, v75 dst_sel:DWORD dst_unused:UNUSED_PAD src0_sel:WORD_1
	v_cvt_f32_f16_e32 v108, v74
	v_cvt_f32_f16_sdwa v109, v74 dst_sel:DWORD dst_unused:UNUSED_PAD src0_sel:WORD_1
	s_waitcnt vmcnt(9)
	v_cvt_f32_f16_e32 v74, v77
	v_cvt_f32_f16_sdwa v75, v77 dst_sel:DWORD dst_unused:UNUSED_PAD src0_sel:WORD_1
	v_cvt_f32_f16_e32 v110, v76
	v_cvt_f32_f16_sdwa v111, v76 dst_sel:DWORD dst_unused:UNUSED_PAD src0_sel:WORD_1
	s_waitcnt vmcnt(8)
	v_cvt_f32_f16_e32 v76, v79
	v_cvt_f32_f16_sdwa v77, v79 dst_sel:DWORD dst_unused:UNUSED_PAD src0_sel:WORD_1
	v_cvt_f32_f16_e32 v112, v78
	v_cvt_f32_f16_sdwa v113, v78 dst_sel:DWORD dst_unused:UNUSED_PAD src0_sel:WORD_1
	s_waitcnt vmcnt(7)
	v_cvt_f32_f16_e32 v78, v81
	v_cvt_f32_f16_sdwa v79, v81 dst_sel:DWORD dst_unused:UNUSED_PAD src0_sel:WORD_1
	v_cvt_f32_f16_e32 v114, v80
	v_cvt_f32_f16_sdwa v115, v80 dst_sel:DWORD dst_unused:UNUSED_PAD src0_sel:WORD_1
	s_waitcnt vmcnt(6)
	v_cvt_f32_f16_e32 v80, v83
	v_cvt_f32_f16_sdwa v81, v83 dst_sel:DWORD dst_unused:UNUSED_PAD src0_sel:WORD_1
	v_cvt_f32_f16_e32 v116, v82
	v_cvt_f32_f16_sdwa v117, v82 dst_sel:DWORD dst_unused:UNUSED_PAD src0_sel:WORD_1
	s_waitcnt vmcnt(5)
	v_cvt_f32_f16_e32 v82, v85
	v_cvt_f32_f16_sdwa v83, v85 dst_sel:DWORD dst_unused:UNUSED_PAD src0_sel:WORD_1
	v_cvt_f32_f16_e32 v118, v84
	v_cvt_f32_f16_sdwa v119, v84 dst_sel:DWORD dst_unused:UNUSED_PAD src0_sel:WORD_1
	s_waitcnt vmcnt(4)
	v_cvt_f32_f16_e32 v84, v87
	v_cvt_f32_f16_sdwa v85, v87 dst_sel:DWORD dst_unused:UNUSED_PAD src0_sel:WORD_1
	v_cvt_f32_f16_e32 v120, v86
	v_cvt_f32_f16_sdwa v121, v86 dst_sel:DWORD dst_unused:UNUSED_PAD src0_sel:WORD_1
	s_waitcnt vmcnt(3)
	v_cvt_f32_f16_e32 v86, v89
	v_cvt_f32_f16_sdwa v87, v89 dst_sel:DWORD dst_unused:UNUSED_PAD src0_sel:WORD_1
	v_cvt_f32_f16_e32 v122, v88
	v_cvt_f32_f16_sdwa v123, v88 dst_sel:DWORD dst_unused:UNUSED_PAD src0_sel:WORD_1
	s_waitcnt vmcnt(2)
	v_cvt_f32_f16_e32 v88, v91
	v_cvt_f32_f16_sdwa v89, v91 dst_sel:DWORD dst_unused:UNUSED_PAD src0_sel:WORD_1
	v_cvt_f32_f16_e32 v124, v90
	v_cvt_f32_f16_sdwa v125, v90 dst_sel:DWORD dst_unused:UNUSED_PAD src0_sel:WORD_1
	s_waitcnt vmcnt(1)
	v_cvt_f32_f16_e32 v90, v93
	v_cvt_f32_f16_sdwa v91, v93 dst_sel:DWORD dst_unused:UNUSED_PAD src0_sel:WORD_1
	v_cvt_f32_f16_e32 v126, v92
	v_cvt_f32_f16_sdwa v127, v92 dst_sel:DWORD dst_unused:UNUSED_PAD src0_sel:WORD_1
	s_waitcnt vmcnt(0)
;     __device__ __forceinline__ void operator()(const f32x4 (&acc)[2][2][4][2], const Unit& u, int wr, int wc, int fr, int fq) const {
;     ...
;             for (int m = 0; m < 4; ++m) { const int off = ((row0 + ai * HALF + m * 16) * 4096 + col0) * 2;
; #pragma unroll
;                 for (int bj = 0; bj < 2; ++bj)
; #pragma unroll
;                     for (int n = 0; n < 2; ++n) { const f32x4 r = xv[m][bj][n] * alpha + acc[ai][bj][m][n] * scl;
;                         u32x2e_t w; w.x = cvt_pk_f16(r[0], r[1]); w.y = cvt_pk_f16(r[2], r[3]);
;                         __builtin_amdgcn_raw_buffer_store_b64(w, Y, off + (bj * HALF + n * 16) * 2, 0, 0); } }
	v_cvt_f32_f16_e32 v92, v95
	v_cvt_f32_f16_sdwa v93, v95 dst_sel:DWORD dst_unused:UNUSED_PAD src0_sel:WORD_1
	v_cvt_f32_f16_e32 v142, v94
	v_cvt_f32_f16_sdwa v143, v94 dst_sel:DWORD dst_unused:UNUSED_PAD src0_sel:WORD_1
	v_mul_f32_e32 v94, s14, v98
	v_mul_f32_e32 v95, s14, v99
	v_mul_f32_e32 v96, s14, v96
	v_mul_f32_e32 v97, s14, v97
	v_fma_f32 v60, v60, s20, v94
	v_fma_f32 v61, v61, s20, v95
	v_fma_f32 v62, v62, s20, v96
	v_fma_f32 v63, v63, s20, v97
	v_cvt_pk_f16_f32 v60, v60, v61
	v_cvt_pk_f16_f32 v61, v62, v63
	buffer_store_dwordx2 v[60:61], v144, s[8:11], 0 offen
	v_mul_f32_e32 v60, s14, v100
	v_mul_f32_e32 v61, s14, v101
	v_mul_f32_e32 v62, s14, v64
	v_mul_f32_e32 v63, s14, v65
	v_fma_f32 v56, v56, s20, v60
	v_fma_f32 v57, v57, s20, v61
	v_fma_f32 v58, v58, s20, v62
	v_fma_f32 v59, v59, s20, v63
	v_cvt_pk_f16_f32 v56, v56, v57
	v_cvt_pk_f16_f32 v57, v58, v59
	buffer_store_dwordx2 v[56:57], v144, s[8:11], 0 offen offset:32
	v_mul_f32_e32 v56, s14, v102
	v_mul_f32_e32 v57, s14, v103
	v_mul_f32_e32 v58, s14, v66
	v_mul_f32_e32 v59, s14, v67
	v_fma_f32 v52, v52, s20, v56
	v_fma_f32 v53, v53, s20, v57
	v_fma_f32 v54, v54, s20, v58
	v_fma_f32 v55, v55, s20, v59
	v_cvt_pk_f16_f32 v52, v52, v53
	v_cvt_pk_f16_f32 v53, v54, v55
	buffer_store_dwordx2 v[52:53], v144, s[8:11], 0 offen offset:256
	v_mul_f32_e32 v52, s14, v104
	v_mul_f32_e32 v53, s14, v105
	v_mul_f32_e32 v54, s14, v68
	v_mul_f32_e32 v55, s14, v69
	v_fma_f32 v44, v44, s20, v52
	v_fma_f32 v45, v45, s20, v53
	v_fma_f32 v46, v46, s20, v54
	v_fma_f32 v47, v47, s20, v55
	v_cvt_pk_f16_f32 v44, v44, v45
	v_cvt_pk_f16_f32 v45, v46, v47
	buffer_store_dwordx2 v[44:45], v144, s[8:11], 0 offen offset:288
	v_mul_f32_e32 v44, s14, v106
	v_mul_f32_e32 v45, s14, v107
	v_mul_f32_e32 v46, s14, v70
	v_mul_f32_e32 v47, s14, v71
	v_fma_f32 v44, v48, s20, v44
	v_fma_f32 v45, v49, s20, v45
	v_fma_f32 v46, v50, s20, v46
	v_fma_f32 v47, v51, s20, v47
	v_cvt_pk_f16_f32 v44, v44, v45
	v_cvt_pk_f16_f32 v45, v46, v47
	buffer_store_dwordx2 v[44:45], v145, s[8:11], 0 offen
	v_mul_f32_e32 v44, s14, v108
	v_mul_f32_e32 v45, s14, v109
	v_mul_f32_e32 v46, s14, v72
	v_mul_f32_e32 v47, s14, v73
	v_fma_f32 v40, v40, s20, v44
	v_fma_f32 v41, v41, s20, v45
	v_fma_f32 v42, v42, s20, v46
	v_fma_f32 v43, v43, s20, v47
	v_cvt_pk_f16_f32 v40, v40, v41
	v_cvt_pk_f16_f32 v41, v42, v43
	buffer_store_dwordx2 v[40:41], v145, s[8:11], 0 offen offset:32
	v_mul_f32_e32 v40, s14, v110
	v_mul_f32_e32 v41, s14, v111
	v_mul_f32_e32 v42, s14, v74
	v_mul_f32_e32 v43, s14, v75
	v_fma_f32 v36, v36, s20, v40
	v_fma_f32 v37, v37, s20, v41
	v_fma_f32 v38, v38, s20, v42
	v_fma_f32 v39, v39, s20, v43
	v_cvt_pk_f16_f32 v36, v36, v37
	v_cvt_pk_f16_f32 v37, v38, v39
	buffer_store_dwordx2 v[36:37], v145, s[8:11], 0 offen offset:256
	v_mul_f32_e32 v36, s14, v112
	v_mul_f32_e32 v37, s14, v113
	v_mul_f32_e32 v38, s14, v76
	v_mul_f32_e32 v39, s14, v77
	v_fma_f32 v28, v28, s20, v36
	v_fma_f32 v29, v29, s20, v37
	v_fma_f32 v30, v30, s20, v38
	v_fma_f32 v31, v31, s20, v39
	v_cvt_pk_f16_f32 v28, v28, v29
	v_cvt_pk_f16_f32 v29, v30, v31
	buffer_store_dwordx2 v[28:29], v145, s[8:11], 0 offen offset:288
	v_mul_f32_e32 v28, s14, v114
	v_mul_f32_e32 v29, s14, v115
	v_mul_f32_e32 v30, s14, v78
	v_mul_f32_e32 v31, s14, v79
	v_fma_f32 v28, v32, s20, v28
	v_fma_f32 v29, v33, s20, v29
	v_fma_f32 v30, v34, s20, v30
	v_fma_f32 v31, v35, s20, v31
	v_cvt_pk_f16_f32 v28, v28, v29
	v_cvt_pk_f16_f32 v29, v30, v31
	buffer_store_dwordx2 v[28:29], v146, s[8:11], 0 offen
	v_mul_f32_e32 v28, s14, v116
	v_mul_f32_e32 v29, s14, v117
	v_mul_f32_e32 v30, s14, v80
	v_mul_f32_e32 v31, s14, v81
	v_fma_f32 v24, v24, s20, v28
	v_fma_f32 v25, v25, s20, v29
	v_fma_f32 v26, v26, s20, v30
	v_fma_f32 v27, v27, s20, v31
	v_cvt_pk_f16_f32 v24, v24, v25
	v_cvt_pk_f16_f32 v25, v26, v27
	buffer_store_dwordx2 v[24:25], v146, s[8:11], 0 offen offset:32
	v_mul_f32_e32 v24, s14, v118
	v_mul_f32_e32 v25, s14, v119
	v_mul_f32_e32 v26, s14, v82
	v_mul_f32_e32 v27, s14, v83
	v_fma_f32 v20, v20, s20, v24
	v_fma_f32 v21, v21, s20, v25
	v_fma_f32 v22, v22, s20, v26
	v_fma_f32 v23, v23, s20, v27
	v_cvt_pk_f16_f32 v20, v20, v21
	v_cvt_pk_f16_f32 v21, v22, v23
	buffer_store_dwordx2 v[20:21], v146, s[8:11], 0 offen offset:256
	v_mul_f32_e32 v20, s14, v120
	v_mul_f32_e32 v21, s14, v121
	v_mul_f32_e32 v22, s14, v84
	v_mul_f32_e32 v23, s14, v85
	v_fma_f32 v12, v12, s20, v20
	v_fma_f32 v13, v13, s20, v21
	v_fma_f32 v14, v14, s20, v22
	v_fma_f32 v15, v15, s20, v23
	v_cvt_pk_f16_f32 v12, v12, v13
	v_cvt_pk_f16_f32 v13, v14, v15
	buffer_store_dwordx2 v[12:13], v146, s[8:11], 0 offen offset:288
	v_mul_f32_e32 v12, s14, v122
	v_mul_f32_e32 v13, s14, v123
	v_mul_f32_e32 v14, s14, v86
	v_mul_f32_e32 v15, s14, v87
	v_fma_f32 v12, v16, s20, v12
	v_fma_f32 v13, v17, s20, v13
	v_fma_f32 v14, v18, s20, v14
	v_fma_f32 v15, v19, s20, v15
	v_cvt_pk_f16_f32 v12, v12, v13
	v_cvt_pk_f16_f32 v13, v14, v15
	buffer_store_dwordx2 v[12:13], v141, s[8:11], 0 offen
	v_mul_f32_e32 v12, s14, v124
	v_mul_f32_e32 v13, s14, v125
	v_mul_f32_e32 v14, s14, v88
	v_mul_f32_e32 v15, s14, v89
	v_fma_f32 v8, v8, s20, v12
	v_fma_f32 v9, v9, s20, v13
	v_fma_f32 v10, v10, s20, v14
	v_fma_f32 v11, v11, s20, v15
	v_cvt_pk_f16_f32 v8, v8, v9
	v_cvt_pk_f16_f32 v9, v10, v11
	buffer_store_dwordx2 v[8:9], v141, s[8:11], 0 offen offset:32
	v_mul_f32_e32 v8, s14, v126
	v_mul_f32_e32 v9, s14, v127
	v_mul_f32_e32 v10, s14, v90
	v_mul_f32_e32 v11, s14, v91
	v_fma_f32 v4, v4, s20, v8
	v_fma_f32 v5, v5, s20, v9
	v_fma_f32 v6, v6, s20, v10
	v_fma_f32 v7, v7, s20, v11
	v_cvt_pk_f16_f32 v4, v4, v5
	v_cvt_pk_f16_f32 v5, v6, v7
	buffer_store_dwordx2 v[4:5], v141, s[8:11], 0 offen offset:256
	v_mul_f32_e32 v4, s14, v142
	v_mul_f32_e32 v5, s14, v143
	v_mul_f32_e32 v6, s14, v92
	v_mul_f32_e32 v7, s14, v93
	v_fma_f32 v0, v0, s20, v4
	v_fma_f32 v1, v1, s20, v5
	v_fma_f32 v2, v2, s20, v6
	v_fma_f32 v3, v3, s20, v7
	v_cvt_pk_f16_f32 v0, v0, v1
	v_cvt_pk_f16_f32 v1, v2, v3
	buffer_store_dwordx2 v[0:1], v141, s[8:11], 0 offen offset:288
	s_cbranch_vccnz .LBB0_3628
	s_andn2_b64 vcc, exec, s[2:3]
	s_cbranch_vccnz .LBB0_3627
	s_barrier
	s_branch .LBB0_3627
